# HGRN2 prep epilogue: the denormal range-scaling ops of the log expansion (v_cmp/v_cndmask/v_ldexp/v_cndmask/v_sub, five per log) removed: the argument 1-k of an f32 k is 0 or a normal number, for whic
# baseline (speedup 1.0000x reference)
; __device__ __forceinline__ unsigned cvt_pk_bf16(float lo, float hi) { unsigned r; asm volatile("v_cvt_pk_bf16_f32 %0, %1, %2" : "=v"(r) : "v"(lo), "v"(hi)); return r; }
; __device__ __forceinline__ float row_scan16(float v) { v += dpp_shr0<0x111>(v); v += dpp_shr0<0x112>(v); v += dpp_shr0<0x114>(v); v += dpp_shr0<0x118>(v); return v; }
; __device__ __forceinline__ float row_last16(float v, int lane) { return __builtin_bit_cast(float, __builtin_amdgcn_ds_bpermute((lane | 15) << 2, __builtin_bit_cast(int, v))); }
;     __device__ __forceinline__ void operator()(const f32x4 (&acc)[2][2][4][2], const Unit& u, int wr, int wc, int fr, int fq) const {
;     ...
;         const int colh = u.pn * HALF + wc * 32 + 8 * fq;
;         f32x4 om[2];
; #pragma unroll
;         for (int n = 0; n < 2; ++n) { const f32x4 l = *(const f32x4*)(lb + colh + 4 * n); om[n] = 1.0f - l; }
; #pragma unroll
;         for (int ai = 0; ai < 2; ++ai)
; #pragma unroll
;             for (int mp = 0; mp < 2; ++mp) {
;                 const int rowa = u.pm * BM + ai * HALF + wr * 64 + mp * 32 + fr;
;                 const int g = rowa >> 5;
;                 float qi[2][8], ki[2][8]; bf16_t* kot = KOT + ((size_t)g * 1024 + colh) * 32 + fr;
;                 float dec[8];
; #pragma unroll
;                 for (int n = 0; n < 2; ++n)
; #pragma unroll
;                     for (int q = 0; q < 4; ++q) { const int j = 4 * n + q;
;                         const float k0 = om[n][q] / (1.0f + __expf(acc[ai][1][2 * mp][n][q])), k1 = om[n][q] / (1.0f + __expf(acc[ai][1][2 * mp + 1][n][q]));
;                         const float p0 = row_scan16(__logf(1.0f - k0)); const float t0 = row_last16(p0, lane);
;                         const float p1 = row_scan16(__logf(1.0f - k1)) + t0; const float bl = row_last16(p1, lane);
;                         const float e0 = __expf(p0), e1 = __expf(p1);
;                         qi[0][j] = acc[ai][0][2 * mp][n][q] * e0; qi[1][j] = acc[ai][0][2 * mp + 1][n][q] * e1;
;                         ki[0][j] = k0 * __expf(-p0); ki[1][j] = k1 * __expf(-p1);
;                         kot[(size_t)j * 32] = (bf16_t)cvt_pk_bf16(k0 * __expf(bl - p0), 0.f); kot[(size_t)j * 32 + 16] = (bf16_t)cvt_pk_bf16(k1 * __expf(bl - p1), 0.f);
;                         dec[j] = __expf(bl); }
.LBB0_1145:
	v_lshl_or_b32 v158, s30, 7, v165
	v_ashrrev_i32_e32 v159, 31, v158
	v_lshl_add_u64 v[130:131], v[158:159], 2, s[16:17]
	global_load_dwordx4 v[134:137], v[130:131], off
	s_nop 0
	global_load_dwordx4 v[130:133], v[130:131], off offset:16
	v_mul_f32_e32 v146, 0x3fb8aa3b, v114
	v_mul_f32_e32 v170, 0x3fb8aa3b, v99
	v_mul_f32_e32 v160, 0x3fb8aa3b, v98
	v_exp_f32_e32 v146, v146
	v_exp_f32_e32 v170, v170
	s_lshl_b32 s2, s28, 8
	v_mul_f32_e32 v161, 0x3fb8aa3b, v115
	v_exp_f32_e32 v171, v160
	s_add_i32 s2, s2, s54
	v_exp_f32_e32 v172, v161
	s_ashr_i32 s0, s2, 5
	s_ashr_i32 s1, s0, 31
	v_add_f32_e32 v173, 1.0, v146
	v_add_f32_e32 v175, 1.0, v170
	s_lshl_b64 s[38:39], s[0:1], 10
	v_add_f32_e32 v171, 1.0, v171
	v_add_f32_e32 v174, 1.0, v172
	v_lshl_add_u64 v[160:161], s[38:39], 0, v[158:159]
	v_lshlrev_b64 v[160:161], 6, v[160:161]
	v_lshl_add_u64 v[160:161], v[148:149], 0, v[160:161]
	v_mul_f32_e32 v190, 0x3fb8aa3b, v101
	v_exp_f32_e32 v190, v190
	v_mul_f32_e32 v195, 0x3fb8aa3b, v90
	v_exp_f32_e32 v195, v195
	v_mul_f32_e32 v200, 0x3fb8aa3b, v91
	v_exp_f32_e32 v200, v200
	v_mul_f32_e32 v205, 0x3fb8aa3b, v92
	v_exp_f32_e32 v205, v205
	s_waitcnt vmcnt(0)
	v_sub_f32_e32 v170, 1.0, v134
	v_sub_f32_e32 v146, 1.0, v135
	v_sub_f32_e32 v135, 1.0, v130
	v_div_scale_f32 v130, s[0:1], v173, v173, v170
	v_div_scale_f32 v172, s[0:1], v171, v171, v170
	v_rcp_f32_e32 v179, v130
	v_div_scale_f32 v177, s[8:9], v174, v174, v146
	v_rcp_f32_e32 v180, v172
	v_rcp_f32_e32 v181, v177
	v_fma_f32 v183, -v130, v179, 1.0
	v_sub_f32_e32 v134, 1.0, v131
	v_div_scale_f32 v131, vcc, v170, v173, v170
	v_fma_f32 v184, -v172, v180, 1.0
	v_fmac_f32_e32 v179, v183, v179
	v_div_scale_f32 v176, s[0:1], v170, v171, v170
	v_fma_f32 v185, -v177, v181, 1.0
	v_fmac_f32_e32 v180, v184, v180
	v_mul_f32_e32 v183, v131, v179
	v_div_scale_f32 v178, s[8:9], v146, v174, v146
	v_fmac_f32_e32 v181, v185, v181
	v_mul_f32_e32 v184, v176, v180
	v_fma_f32 v187, -v130, v183, v131
	v_mul_f32_e32 v185, v178, v181
	v_fma_f32 v188, -v172, v184, v176
	v_fmac_f32_e32 v183, v187, v179
	v_fma_f32 v189, -v177, v185, v178
	v_fmac_f32_e32 v184, v188, v180
	v_fma_f32 v130, -v130, v183, v131
	v_fmac_f32_e32 v185, v189, v181
	v_fma_f32 v131, -v172, v184, v176
	v_div_fmas_f32 v130, v130, v179, v183
	s_mov_b64 vcc, s[0:1]
	v_fma_f32 v176, -v177, v185, v178
	v_div_fixup_f32 v177, v130, v173, v170
	v_div_fmas_f32 v130, v131, v180, v184
	v_div_fixup_f32 v178, v130, v171, v170
	v_sub_f32_e32 v130, 1.0, v177
	v_sub_f32_e32 v171, 1.0, v178
	v_div_scale_f32 v182, s[48:49], v175, v175, v146
	v_log_f32_e32 v130, v130
	v_sub_f32_e32 v136, 1.0, v136
	v_log_f32_e32 v171, v171
	v_mul_f32_e32 v173, 0x3f317217, v130
	v_fma_f32 v173, v130, s72, -v173
	v_fmac_f32_e32 v173, 0x3377d1cf, v130
	v_mul_f32_e32 v179, 0x3f317217, v171
	v_fma_f32 v179, v171, s72, -v179
	v_fmac_f32_e32 v173, 0x3f317217, v130
	v_cmp_lt_f32_e64 vcc, |v130|, s73
	v_fmac_f32_e32 v179, 0x3377d1cf, v171
	v_fmac_f32_e32 v179, 0x3f317217, v171
	v_cndmask_b32_e32 v130, v130, v173, vcc
	v_cmp_lt_f32_e64 vcc, |v171|, s73
	v_sub_f32_e32 v137, 1.0, v137
	v_add_f32_dpp v130, v130, v130 row_shr:1 row_mask:0xf bank_mask:0xf bound_ctrl:1
	v_cndmask_b32_e32 v131, v171, v179, vcc
	s_nop 0
	v_add_f32_dpp v130, v130, v130 row_shr:2 row_mask:0xf bank_mask:0xf bound_ctrl:1
	s_mov_b64 vcc, s[8:9]
	v_add_f32_dpp v131, v131, v131 row_shr:1 row_mask:0xf bank_mask:0xf bound_ctrl:1
	v_add_f32_dpp v130, v130, v130 row_shr:4 row_mask:0xf bank_mask:0xf bound_ctrl:1
	v_div_fmas_f32 v176, v176, v181, v185
	v_add_f32_dpp v131, v131, v131 row_shr:2 row_mask:0xf bank_mask:0xf bound_ctrl:1
	v_add_f32_dpp v171, v130, v130 row_shr:8 row_mask:0xf bank_mask:0xf bound_ctrl:1
	v_mul_f32_e32 v172, 0x3fb8aa3b, v171
	v_add_f32_dpp v130, v131, v131 row_shr:4 row_mask:0xf bank_mask:0xf bound_ctrl:1
	ds_bpermute_b32 v131, v162, v171
	v_mul_f32_e32 v173, 0xbfb8aa3b, v171
	v_add_f32_dpp v130, v130, v130 row_shr:8 row_mask:0xf bank_mask:0xf bound_ctrl:1
	v_exp_f32_e32 v172, v172
	v_exp_f32_e32 v179, v173
	s_waitcnt lgkmcnt(0)
	v_add_f32_e32 v131, v130, v131
	ds_bpermute_b32 v130, v162, v131
	v_mul_f32_e32 v173, v126, v172
	v_mul_f32_e32 v172, v177, v179
	v_mul_f32_e32 v179, 0x3fb8aa3b, v131
	v_mul_f32_e32 v180, 0xbfb8aa3b, v131
	s_waitcnt lgkmcnt(0)
	v_sub_f32_e32 v171, v130, v171
	v_mul_f32_e32 v171, 0x3fb8aa3b, v171
	v_sub_f32_e32 v131, v130, v131
	v_exp_f32_e32 v183, v171
	v_mul_f32_e32 v131, 0x3fb8aa3b, v131
	v_exp_f32_e32 v180, v180
	v_exp_f32_e32 v184, v131
	v_mul_f32_e32 v177, v177, v183
	v_cvt_pk_bf16_f32 v177, v177, v147
	v_mul_f32_e32 v131, v178, v180
	v_mul_f32_e32 v178, v178, v184
	global_store_short v[160:161], v177, off
	v_cvt_pk_bf16_f32 v177, v178, v147
	v_exp_f32_e32 v179, v179
	global_store_short v[160:161], v177, off offset:32
	v_rcp_f32_e32 v177, v182
	v_mul_f32_e32 v184, 0x3fb8aa3b, v100
	v_mul_f32_e32 v171, v118, v179
	v_div_fixup_f32 v179, v176, v174, v146
	v_fma_f32 v174, -v182, v177, 1.0
	v_fmac_f32_e32 v177, v174, v177
	v_div_scale_f32 v174, vcc, v146, v175, v146
	v_mul_f32_e32 v176, v174, v177
	v_fma_f32 v178, -v182, v176, v174
	v_fmac_f32_e32 v176, v178, v177
	v_sub_f32_e32 v178, 1.0, v179
	v_fma_f32 v174, -v182, v176, v174
	v_div_fmas_f32 v174, v174, v177, v176
	v_log_f32_e32 v178, v178
	v_div_fixup_f32 v180, v174, v175, v146
	v_exp_f32_e32 v184, v184
	v_mul_f32_e32 v174, 0x3f317217, v178
	v_fma_f32 v174, v178, s72, -v174
	v_fmac_f32_e32 v174, 0x3377d1cf, v178
	v_fmac_f32_e32 v174, 0x3f317217, v178
	v_cmp_lt_f32_e64 vcc, |v178|, s73
	v_sub_f32_e32 v132, 1.0, v132
	v_sub_f32_e32 v133, 1.0, v133
	v_cndmask_b32_e32 v174, v178, v174, vcc
	v_sub_f32_e32 v175, 1.0, v180
	s_nop 0
	v_add_f32_dpp v174, v174, v174 row_shr:1 row_mask:0xf bank_mask:0xf bound_ctrl:1
	s_nop 0
	v_log_f32_e32 v175, v175
	v_add_f32_dpp v174, v174, v174 row_shr:2 row_mask:0xf bank_mask:0xf bound_ctrl:1
	v_mul_f32_e32 v177, 0x3f317217, v175
	v_fma_f32 v177, v175, s72, -v177
	v_fmac_f32_e32 v177, 0x3377d1cf, v175
	v_add_f32_dpp v174, v174, v174 row_shr:4 row_mask:0xf bank_mask:0xf bound_ctrl:1
	v_fmac_f32_e32 v177, 0x3f317217, v175
	v_cmp_lt_f32_e64 s[0:1], |v175|, s73
	v_add_f32_dpp v176, v174, v174 row_shr:8 row_mask:0xf bank_mask:0xf bound_ctrl:1
	ds_bpermute_b32 v174, v162, v176
	v_cndmask_b32_e64 v175, v175, v177, s[0:1]
	s_nop 1
	v_add_f32_dpp v175, v175, v175 row_shr:1 row_mask:0xf bank_mask:0xf bound_ctrl:1
	s_nop 1
	v_add_f32_dpp v175, v175, v175 row_shr:2 row_mask:0xf bank_mask:0xf bound_ctrl:1
	s_nop 1
	v_add_f32_dpp v175, v175, v175 row_shr:4 row_mask:0xf bank_mask:0xf bound_ctrl:1
	s_nop 1
	v_add_f32_dpp v175, v175, v175 row_shr:8 row_mask:0xf bank_mask:0xf bound_ctrl:1
	s_waitcnt lgkmcnt(0)
; __device__ __forceinline__ unsigned cvt_pk_bf16(float lo, float hi) { unsigned r; asm volatile("v_cvt_pk_bf16_f32 %0, %1, %2" : "=v"(r) : "v"(lo), "v"(hi)); return r; }
; __device__ __forceinline__ float row_scan16(float v) { v += dpp_shr0<0x111>(v); v += dpp_shr0<0x112>(v); v += dpp_shr0<0x114>(v); v += dpp_shr0<0x118>(v); return v; }
; __device__ __forceinline__ float row_last16(float v, int lane) { return __builtin_bit_cast(float, __builtin_amdgcn_ds_bpermute((lane | 15) << 2, __builtin_bit_cast(int, v))); }
;     __device__ __forceinline__ void operator()(const f32x4 (&acc)[2][2][4][2], const Unit& u, int wr, int wc, int fr, int fq) const {
;     ...
;                     for (int q = 0; q < 4; ++q) { const int j = 4 * n + q;
;                         const float k0 = om[n][q] / (1.0f + __expf(acc[ai][1][2 * mp][n][q])), k1 = om[n][q] / (1.0f + __expf(acc[ai][1][2 * mp + 1][n][q]));
;                         const float p0 = row_scan16(__logf(1.0f - k0)); const float t0 = row_last16(p0, lane);
;                         const float p1 = row_scan16(__logf(1.0f - k1)) + t0; const float bl = row_last16(p1, lane);
;                         const float e0 = __expf(p0), e1 = __expf(p1);
;                         qi[0][j] = acc[ai][0][2 * mp][n][q] * e0; qi[1][j] = acc[ai][0][2 * mp + 1][n][q] * e1;
;                         ki[0][j] = k0 * __expf(-p0); ki[1][j] = k1 * __expf(-p1);
;                         kot[(size_t)j * 32] = (bf16_t)cvt_pk_bf16(k0 * __expf(bl - p0), 0.f); kot[(size_t)j * 32 + 16] = (bf16_t)cvt_pk_bf16(k1 * __expf(bl - p1), 0.f);
;                         dec[j] = __expf(bl); }
	v_add_f32_e32 v181, v175, v174
	v_mul_f32_e32 v174, 0x3fb8aa3b, v176
	v_exp_f32_e32 v175, v174
	ds_bpermute_b32 v174, v162, v181
	v_mul_f32_e32 v177, 0x3fb8aa3b, v181
	v_exp_f32_e32 v178, v177
	v_mul_f32_e32 v177, v127, v175
	v_mul_f32_e32 v175, 0xbfb8aa3b, v176
	s_waitcnt lgkmcnt(0)
	v_sub_f32_e32 v176, v174, v176
	v_mul_f32_e32 v176, 0x3fb8aa3b, v176
	v_exp_f32_e32 v175, v175
	v_exp_f32_e32 v183, v176
	v_mul_f32_e32 v176, v119, v178
	v_mul_f32_e32 v182, 0xbfb8aa3b, v181
	v_mul_f32_e32 v178, v179, v175
	v_mul_f32_e32 v179, v179, v183
	v_cvt_pk_bf16_f32 v179, v179, v147
	global_store_short v[160:161], v179, off offset:64
	v_mul_f32_e32 v179, 0x3fb8aa3b, v116
	v_exp_f32_e32 v179, v179
	v_exp_f32_e32 v182, v182
	v_sub_f32_e32 v181, v174, v181
	v_mul_f32_e32 v181, 0x3fb8aa3b, v181
	v_exp_f32_e32 v181, v181
	v_add_f32_e32 v179, 1.0, v179
	v_mul_f32_e32 v175, v180, v182
	v_div_scale_f32 v182, s[0:1], v179, v179, v136
	v_rcp_f32_e32 v183, v182
	v_mul_f32_e32 v180, v180, v181
	v_cvt_pk_bf16_f32 v180, v180, v147
	global_store_short v[160:161], v180, off offset:96
	v_fma_f32 v180, -v182, v183, 1.0
	v_fmac_f32_e32 v183, v180, v183
	v_div_scale_f32 v180, vcc, v136, v179, v136
	v_mul_f32_e32 v181, v180, v183
	v_fma_f32 v185, -v182, v181, v180
	v_fmac_f32_e32 v181, v185, v183
	v_fma_f32 v180, -v182, v181, v180
	v_add_f32_e32 v182, 1.0, v184
	v_div_scale_f32 v184, s[0:1], v182, v182, v136
	v_rcp_f32_e32 v185, v184
	v_div_fmas_f32 v180, v180, v183, v181
	v_div_fixup_f32 v187, v180, v179, v136
	v_fma_f32 v179, -v184, v185, 1.0
	v_fmac_f32_e32 v185, v179, v185
	v_div_scale_f32 v179, vcc, v136, v182, v136
	v_mul_f32_e32 v180, v179, v185
	v_fma_f32 v181, -v184, v180, v179
	v_fmac_f32_e32 v180, v181, v185
	v_sub_f32_e32 v181, 1.0, v187
	v_fma_f32 v179, -v184, v180, v179
	v_div_fmas_f32 v179, v179, v185, v180
	v_log_f32_e32 v181, v181
	v_div_fixup_f32 v184, v179, v182, v136
	v_mul_f32_e32 v179, 0x3f317217, v181
	v_fma_f32 v179, v181, s72, -v179
	v_fmac_f32_e32 v179, 0x3377d1cf, v181
	v_fmac_f32_e32 v179, 0x3f317217, v181
	v_cmp_lt_f32_e64 vcc, |v181|, s73
	s_nop 1
	v_cndmask_b32_e32 v179, v181, v179, vcc
	v_sub_f32_e32 v180, 1.0, v184
	s_nop 0
	v_add_f32_dpp v179, v179, v179 row_shr:1 row_mask:0xf bank_mask:0xf bound_ctrl:1
	s_nop 0
	v_log_f32_e32 v180, v180
	v_add_f32_dpp v179, v179, v179 row_shr:2 row_mask:0xf bank_mask:0xf bound_ctrl:1
	v_mul_f32_e32 v182, 0x3f317217, v180
	v_fma_f32 v182, v180, s72, -v182
	v_fmac_f32_e32 v182, 0x3377d1cf, v180
	v_add_f32_dpp v179, v179, v179 row_shr:4 row_mask:0xf bank_mask:0xf bound_ctrl:1
	v_fmac_f32_e32 v182, 0x3f317217, v180
	v_cmp_lt_f32_e64 s[0:1], |v180|, s73
	v_add_f32_dpp v181, v179, v179 row_shr:8 row_mask:0xf bank_mask:0xf bound_ctrl:1
	ds_bpermute_b32 v179, v162, v181
	v_cndmask_b32_e64 v180, v180, v182, s[0:1]
	s_nop 1
	v_add_f32_dpp v180, v180, v180 row_shr:1 row_mask:0xf bank_mask:0xf bound_ctrl:1
	s_nop 1
	v_add_f32_dpp v180, v180, v180 row_shr:2 row_mask:0xf bank_mask:0xf bound_ctrl:1
	s_nop 1
	v_add_f32_dpp v180, v180, v180 row_shr:4 row_mask:0xf bank_mask:0xf bound_ctrl:1
	s_nop 1
	v_add_f32_dpp v180, v180, v180 row_shr:8 row_mask:0xf bank_mask:0xf bound_ctrl:1
	s_waitcnt lgkmcnt(0)
	v_add_f32_e32 v185, v180, v179
	v_mul_f32_e32 v179, 0x3fb8aa3b, v181
	v_exp_f32_e32 v180, v179
	ds_bpermute_b32 v179, v162, v185
	v_mul_f32_e32 v182, 0x3fb8aa3b, v185
	v_exp_f32_e32 v183, v182
	v_mul_f32_e32 v182, v128, v180
	v_mul_f32_e32 v180, 0xbfb8aa3b, v181
	s_waitcnt lgkmcnt(0)
	v_sub_f32_e32 v181, v179, v181
	v_mul_f32_e32 v181, 0x3fb8aa3b, v181
	v_exp_f32_e32 v180, v180
	v_exp_f32_e32 v189, v181
	v_mul_f32_e32 v181, v120, v183
	v_mul_f32_e32 v188, 0xbfb8aa3b, v185
	v_mul_f32_e32 v183, v187, v180
	v_mul_f32_e32 v187, v187, v189
	v_cvt_pk_bf16_f32 v187, v187, v147
	global_store_short v[160:161], v187, off offset:128
	v_mul_f32_e32 v187, 0x3fb8aa3b, v117
	v_exp_f32_e32 v187, v187
	v_exp_f32_e32 v188, v188
	v_sub_f32_e32 v185, v179, v185
	v_mul_f32_e32 v185, 0x3fb8aa3b, v185
	v_exp_f32_e32 v185, v185
	v_add_f32_e32 v187, 1.0, v187
	v_mul_f32_e32 v180, v184, v188
	v_div_scale_f32 v188, s[0:1], v187, v187, v137
	v_rcp_f32_e32 v189, v188
	v_mul_f32_e32 v184, v184, v185
	v_cvt_pk_bf16_f32 v184, v184, v147
	global_store_short v[160:161], v184, off offset:160
	v_fma_f32 v184, -v188, v189, 1.0
	v_fmac_f32_e32 v189, v184, v189
	v_div_scale_f32 v184, vcc, v137, v187, v137
	v_mul_f32_e32 v185, v184, v189
	v_fma_f32 v191, -v188, v185, v184
	v_fmac_f32_e32 v185, v191, v189
	v_fma_f32 v184, -v188, v185, v184
	v_add_f32_e32 v188, 1.0, v190
	v_div_scale_f32 v190, s[0:1], v188, v188, v137
	v_rcp_f32_e32 v191, v190
	v_div_fmas_f32 v184, v184, v189, v185
	v_div_fixup_f32 v192, v184, v187, v137
	v_fma_f32 v184, -v190, v191, 1.0
	v_fmac_f32_e32 v191, v184, v191
	v_div_scale_f32 v184, vcc, v137, v188, v137
	v_mul_f32_e32 v185, v184, v191
	v_fma_f32 v187, -v190, v185, v184
	v_fmac_f32_e32 v185, v187, v191
	v_sub_f32_e32 v187, 1.0, v192
	v_fma_f32 v184, -v190, v185, v184
	v_div_fmas_f32 v184, v184, v191, v185
	v_log_f32_e32 v187, v187
	v_div_fixup_f32 v190, v184, v188, v137
	v_mul_f32_e32 v184, 0x3f317217, v187
	v_fma_f32 v184, v187, s72, -v184
	v_fmac_f32_e32 v184, 0x3377d1cf, v187
	v_fmac_f32_e32 v184, 0x3f317217, v187
	v_cmp_lt_f32_e64 vcc, |v187|, s73
	s_nop 1
	v_cndmask_b32_e32 v184, v187, v184, vcc
	v_sub_f32_e32 v185, 1.0, v190
	s_nop 0
	v_add_f32_dpp v184, v184, v184 row_shr:1 row_mask:0xf bank_mask:0xf bound_ctrl:1
	s_nop 0
	v_log_f32_e32 v185, v185
	v_add_f32_dpp v184, v184, v184 row_shr:2 row_mask:0xf bank_mask:0xf bound_ctrl:1
	v_mul_f32_e32 v188, 0x3f317217, v185
	v_fma_f32 v188, v185, s72, -v188
	v_fmac_f32_e32 v188, 0x3377d1cf, v185
	v_add_f32_dpp v184, v184, v184 row_shr:4 row_mask:0xf bank_mask:0xf bound_ctrl:1
	v_fmac_f32_e32 v188, 0x3f317217, v185
	v_cmp_lt_f32_e64 s[0:1], |v185|, s73
	v_add_f32_dpp v187, v184, v184 row_shr:8 row_mask:0xf bank_mask:0xf bound_ctrl:1
	ds_bpermute_b32 v184, v162, v187
	v_cndmask_b32_e64 v185, v185, v188, s[0:1]
	s_nop 1
	v_add_f32_dpp v185, v185, v185 row_shr:1 row_mask:0xf bank_mask:0xf bound_ctrl:1
	s_nop 1
	v_add_f32_dpp v185, v185, v185 row_shr:2 row_mask:0xf bank_mask:0xf bound_ctrl:1
	s_nop 1
	v_add_f32_dpp v185, v185, v185 row_shr:4 row_mask:0xf bank_mask:0xf bound_ctrl:1
	s_nop 1
	v_add_f32_dpp v185, v185, v185 row_shr:8 row_mask:0xf bank_mask:0xf bound_ctrl:1
	s_waitcnt lgkmcnt(0)
; __device__ __forceinline__ unsigned cvt_pk_bf16(float lo, float hi) { unsigned r; asm volatile("v_cvt_pk_bf16_f32 %0, %1, %2" : "=v"(r) : "v"(lo), "v"(hi)); return r; }
; __device__ __forceinline__ float row_scan16(float v) { v += dpp_shr0<0x111>(v); v += dpp_shr0<0x112>(v); v += dpp_shr0<0x114>(v); v += dpp_shr0<0x118>(v); return v; }
; __device__ __forceinline__ float row_last16(float v, int lane) { return __builtin_bit_cast(float, __builtin_amdgcn_ds_bpermute((lane | 15) << 2, __builtin_bit_cast(int, v))); }
;     __device__ __forceinline__ void operator()(const f32x4 (&acc)[2][2][4][2], const Unit& u, int wr, int wc, int fr, int fq) const {
;     ...
;                     for (int q = 0; q < 4; ++q) { const int j = 4 * n + q;
;                         const float k0 = om[n][q] / (1.0f + __expf(acc[ai][1][2 * mp][n][q])), k1 = om[n][q] / (1.0f + __expf(acc[ai][1][2 * mp + 1][n][q]));
;                         const float p0 = row_scan16(__logf(1.0f - k0)); const float t0 = row_last16(p0, lane);
;                         const float p1 = row_scan16(__logf(1.0f - k1)) + t0; const float bl = row_last16(p1, lane);
;                         const float e0 = __expf(p0), e1 = __expf(p1);
;                         qi[0][j] = acc[ai][0][2 * mp][n][q] * e0; qi[1][j] = acc[ai][0][2 * mp + 1][n][q] * e1;
;                         ki[0][j] = k0 * __expf(-p0); ki[1][j] = k1 * __expf(-p1);
;                         kot[(size_t)j * 32] = (bf16_t)cvt_pk_bf16(k0 * __expf(bl - p0), 0.f); kot[(size_t)j * 32 + 16] = (bf16_t)cvt_pk_bf16(k1 * __expf(bl - p1), 0.f);
;                         dec[j] = __expf(bl); }
	v_add_f32_e32 v191, v185, v184
	v_mul_f32_e32 v184, 0x3fb8aa3b, v187
	v_exp_f32_e32 v185, v184
	ds_bpermute_b32 v184, v162, v191
	v_mul_f32_e32 v188, 0x3fb8aa3b, v191
	v_exp_f32_e32 v189, v188
	v_mul_f32_e32 v188, v129, v185
	v_mul_f32_e32 v185, 0xbfb8aa3b, v187
	s_waitcnt lgkmcnt(0)
	v_sub_f32_e32 v187, v184, v187
	v_mul_f32_e32 v187, 0x3fb8aa3b, v187
	v_exp_f32_e32 v185, v185
	v_exp_f32_e32 v194, v187
	v_mul_f32_e32 v187, v121, v189
	v_mul_f32_e32 v193, 0xbfb8aa3b, v191
	v_mul_f32_e32 v189, v192, v185
	v_mul_f32_e32 v192, v192, v194
	v_cvt_pk_bf16_f32 v192, v192, v147
	global_store_short v[160:161], v192, off offset:192
	v_mul_f32_e32 v192, 0x3fb8aa3b, v106
	v_exp_f32_e32 v192, v192
	v_exp_f32_e32 v193, v193
	v_sub_f32_e32 v191, v184, v191
	v_mul_f32_e32 v191, 0x3fb8aa3b, v191
	v_exp_f32_e32 v191, v191
	v_add_f32_e32 v192, 1.0, v192
	v_mul_f32_e32 v185, v190, v193
	v_div_scale_f32 v193, s[0:1], v192, v192, v135
	v_rcp_f32_e32 v194, v193
	v_mul_f32_e32 v190, v190, v191
	v_cvt_pk_bf16_f32 v190, v190, v147
	global_store_short v[160:161], v190, off offset:224
	v_fma_f32 v190, -v193, v194, 1.0
	v_fmac_f32_e32 v194, v190, v194
	v_div_scale_f32 v190, vcc, v135, v192, v135
	v_mul_f32_e32 v191, v190, v194
	v_fma_f32 v196, -v193, v191, v190
	v_fmac_f32_e32 v191, v196, v194
	v_fma_f32 v190, -v193, v191, v190
	v_add_f32_e32 v193, 1.0, v195
	v_div_scale_f32 v195, s[0:1], v193, v193, v135
	v_rcp_f32_e32 v196, v195
	v_div_fmas_f32 v190, v190, v194, v191
	v_div_fixup_f32 v197, v190, v192, v135
	v_fma_f32 v190, -v195, v196, 1.0
	v_fmac_f32_e32 v196, v190, v196
	v_div_scale_f32 v190, vcc, v135, v193, v135
	v_mul_f32_e32 v191, v190, v196
	v_fma_f32 v192, -v195, v191, v190
	v_fmac_f32_e32 v191, v192, v196
	v_sub_f32_e32 v192, 1.0, v197
	v_fma_f32 v190, -v195, v191, v190
	v_div_fmas_f32 v190, v190, v196, v191
	v_log_f32_e32 v192, v192
	v_div_fixup_f32 v195, v190, v193, v135
	v_mul_f32_e32 v190, 0x3f317217, v192
	v_fma_f32 v190, v192, s72, -v190
	v_fmac_f32_e32 v190, 0x3377d1cf, v192
	v_fmac_f32_e32 v190, 0x3f317217, v192
	v_cmp_lt_f32_e64 vcc, |v192|, s73
	s_nop 1
	v_cndmask_b32_e32 v190, v192, v190, vcc
	v_sub_f32_e32 v191, 1.0, v195
	s_nop 0
	v_add_f32_dpp v190, v190, v190 row_shr:1 row_mask:0xf bank_mask:0xf bound_ctrl:1
	s_nop 0
	v_log_f32_e32 v191, v191
	v_add_f32_dpp v190, v190, v190 row_shr:2 row_mask:0xf bank_mask:0xf bound_ctrl:1
	v_mul_f32_e32 v193, 0x3f317217, v191
	v_fma_f32 v193, v191, s72, -v193
	v_fmac_f32_e32 v193, 0x3377d1cf, v191
	v_add_f32_dpp v190, v190, v190 row_shr:4 row_mask:0xf bank_mask:0xf bound_ctrl:1
	v_fmac_f32_e32 v193, 0x3f317217, v191
	v_cmp_lt_f32_e64 s[0:1], |v191|, s73
	v_add_f32_dpp v192, v190, v190 row_shr:8 row_mask:0xf bank_mask:0xf bound_ctrl:1
	ds_bpermute_b32 v190, v162, v192
	v_cndmask_b32_e64 v191, v191, v193, s[0:1]
	s_nop 1
	v_add_f32_dpp v191, v191, v191 row_shr:1 row_mask:0xf bank_mask:0xf bound_ctrl:1
	s_nop 1
	v_add_f32_dpp v191, v191, v191 row_shr:2 row_mask:0xf bank_mask:0xf bound_ctrl:1
	s_nop 1
	v_add_f32_dpp v191, v191, v191 row_shr:4 row_mask:0xf bank_mask:0xf bound_ctrl:1
	s_nop 1
	v_add_f32_dpp v191, v191, v191 row_shr:8 row_mask:0xf bank_mask:0xf bound_ctrl:1
	s_waitcnt lgkmcnt(0)
	v_add_f32_e32 v196, v191, v190
	v_mul_f32_e32 v190, 0x3fb8aa3b, v192
	v_exp_f32_e32 v191, v190
	ds_bpermute_b32 v190, v162, v196
	v_mul_f32_e32 v193, 0x3fb8aa3b, v196
	v_exp_f32_e32 v194, v193
	v_mul_f32_e32 v193, v122, v191
	v_mul_f32_e32 v191, 0xbfb8aa3b, v192
	s_waitcnt lgkmcnt(0)
	v_sub_f32_e32 v192, v190, v192
	v_mul_f32_e32 v192, 0x3fb8aa3b, v192
	v_exp_f32_e32 v191, v191
	v_exp_f32_e32 v199, v192
	v_mul_f32_e32 v192, v110, v194
	v_mul_f32_e32 v198, 0xbfb8aa3b, v196
	v_mul_f32_e32 v194, v197, v191
	v_mul_f32_e32 v197, v197, v199
	v_cvt_pk_bf16_f32 v197, v197, v147
	global_store_short v[160:161], v197, off offset:256
	v_mul_f32_e32 v197, 0x3fb8aa3b, v107
	v_exp_f32_e32 v197, v197
	v_exp_f32_e32 v198, v198
	v_sub_f32_e32 v196, v190, v196
	v_mul_f32_e32 v196, 0x3fb8aa3b, v196
	v_exp_f32_e32 v196, v196
	v_add_f32_e32 v197, 1.0, v197
	v_mul_f32_e32 v191, v195, v198
	v_div_scale_f32 v198, s[0:1], v197, v197, v134
	v_rcp_f32_e32 v199, v198
	v_mul_f32_e32 v195, v195, v196
	v_cvt_pk_bf16_f32 v195, v195, v147
	global_store_short v[160:161], v195, off offset:288
	v_fma_f32 v195, -v198, v199, 1.0
	v_fmac_f32_e32 v199, v195, v199
	v_div_scale_f32 v195, vcc, v134, v197, v134
	v_mul_f32_e32 v196, v195, v199
	v_fma_f32 v201, -v198, v196, v195
	v_fmac_f32_e32 v196, v201, v199
	v_fma_f32 v195, -v198, v196, v195
	v_add_f32_e32 v198, 1.0, v200
	v_div_scale_f32 v200, s[0:1], v198, v198, v134
	v_rcp_f32_e32 v201, v200
	v_div_fmas_f32 v195, v195, v199, v196
	v_div_fixup_f32 v202, v195, v197, v134
	v_fma_f32 v195, -v200, v201, 1.0
	v_fmac_f32_e32 v201, v195, v201
	v_div_scale_f32 v195, vcc, v134, v198, v134
	v_mul_f32_e32 v196, v195, v201
	v_fma_f32 v197, -v200, v196, v195
	v_fmac_f32_e32 v196, v197, v201
	v_sub_f32_e32 v197, 1.0, v202
	v_fma_f32 v195, -v200, v196, v195
	v_div_fmas_f32 v195, v195, v201, v196
	v_log_f32_e32 v197, v197
	v_div_fixup_f32 v200, v195, v198, v134
	v_mul_f32_e32 v195, 0x3f317217, v197
	v_fma_f32 v195, v197, s72, -v195
	v_fmac_f32_e32 v195, 0x3377d1cf, v197
	v_fmac_f32_e32 v195, 0x3f317217, v197
	v_cmp_lt_f32_e64 vcc, |v197|, s73
	s_nop 1
	v_cndmask_b32_e32 v195, v197, v195, vcc
	v_sub_f32_e32 v196, 1.0, v200
	s_nop 0
	v_add_f32_dpp v195, v195, v195 row_shr:1 row_mask:0xf bank_mask:0xf bound_ctrl:1
	s_nop 0
	v_log_f32_e32 v196, v196
	v_add_f32_dpp v195, v195, v195 row_shr:2 row_mask:0xf bank_mask:0xf bound_ctrl:1
	v_mul_f32_e32 v198, 0x3f317217, v196
	v_fma_f32 v198, v196, s72, -v198
	v_fmac_f32_e32 v198, 0x3377d1cf, v196
	v_add_f32_dpp v195, v195, v195 row_shr:4 row_mask:0xf bank_mask:0xf bound_ctrl:1
	v_fmac_f32_e32 v198, 0x3f317217, v196
	v_cmp_lt_f32_e64 s[0:1], |v196|, s73
	v_add_f32_dpp v197, v195, v195 row_shr:8 row_mask:0xf bank_mask:0xf bound_ctrl:1
	ds_bpermute_b32 v195, v162, v197
	v_cndmask_b32_e64 v196, v196, v198, s[0:1]
	s_nop 1
	v_add_f32_dpp v196, v196, v196 row_shr:1 row_mask:0xf bank_mask:0xf bound_ctrl:1
	s_nop 1
	v_add_f32_dpp v196, v196, v196 row_shr:2 row_mask:0xf bank_mask:0xf bound_ctrl:1
	s_nop 1
	v_add_f32_dpp v196, v196, v196 row_shr:4 row_mask:0xf bank_mask:0xf bound_ctrl:1
	s_nop 1
	v_add_f32_dpp v196, v196, v196 row_shr:8 row_mask:0xf bank_mask:0xf bound_ctrl:1
	s_waitcnt lgkmcnt(0)
; __device__ __forceinline__ unsigned cvt_pk_bf16(float lo, float hi) { unsigned r; asm volatile("v_cvt_pk_bf16_f32 %0, %1, %2" : "=v"(r) : "v"(lo), "v"(hi)); return r; }
; __device__ __forceinline__ float row_scan16(float v) { v += dpp_shr0<0x111>(v); v += dpp_shr0<0x112>(v); v += dpp_shr0<0x114>(v); v += dpp_shr0<0x118>(v); return v; }
; __device__ __forceinline__ float row_last16(float v, int lane) { return __builtin_bit_cast(float, __builtin_amdgcn_ds_bpermute((lane | 15) << 2, __builtin_bit_cast(int, v))); }
;     __device__ __forceinline__ void operator()(const f32x4 (&acc)[2][2][4][2], const Unit& u, int wr, int wc, int fr, int fq) const {
;     ...
;                     for (int q = 0; q < 4; ++q) { const int j = 4 * n + q;
;                         const float k0 = om[n][q] / (1.0f + __expf(acc[ai][1][2 * mp][n][q])), k1 = om[n][q] / (1.0f + __expf(acc[ai][1][2 * mp + 1][n][q]));
;                         const float p0 = row_scan16(__logf(1.0f - k0)); const float t0 = row_last16(p0, lane);
;                         const float p1 = row_scan16(__logf(1.0f - k1)) + t0; const float bl = row_last16(p1, lane);
;                         const float e0 = __expf(p0), e1 = __expf(p1);
;                         qi[0][j] = acc[ai][0][2 * mp][n][q] * e0; qi[1][j] = acc[ai][0][2 * mp + 1][n][q] * e1;
;                         ki[0][j] = k0 * __expf(-p0); ki[1][j] = k1 * __expf(-p1);
;                         kot[(size_t)j * 32] = (bf16_t)cvt_pk_bf16(k0 * __expf(bl - p0), 0.f); kot[(size_t)j * 32 + 16] = (bf16_t)cvt_pk_bf16(k1 * __expf(bl - p1), 0.f);
;                         dec[j] = __expf(bl); }
	v_add_f32_e32 v201, v196, v195
	v_mul_f32_e32 v195, 0x3fb8aa3b, v197
	v_exp_f32_e32 v196, v195
	ds_bpermute_b32 v195, v162, v201
	v_mul_f32_e32 v198, 0x3fb8aa3b, v201
	v_exp_f32_e32 v199, v198
	v_mul_f32_e32 v198, v123, v196
	v_mul_f32_e32 v196, 0xbfb8aa3b, v197
	s_waitcnt lgkmcnt(0)
	v_sub_f32_e32 v197, v195, v197
	v_mul_f32_e32 v197, 0x3fb8aa3b, v197
	v_exp_f32_e32 v196, v196
	v_exp_f32_e32 v204, v197
	v_mul_f32_e32 v197, v111, v199
	v_mul_f32_e32 v203, 0xbfb8aa3b, v201
	v_mul_f32_e32 v199, v202, v196
	v_mul_f32_e32 v202, v202, v204
	v_cvt_pk_bf16_f32 v202, v202, v147
	global_store_short v[160:161], v202, off offset:320
	v_mul_f32_e32 v202, 0x3fb8aa3b, v108
	v_exp_f32_e32 v202, v202
	v_exp_f32_e32 v203, v203
	v_sub_f32_e32 v201, v195, v201
	v_mul_f32_e32 v201, 0x3fb8aa3b, v201
	v_exp_f32_e32 v201, v201
	v_add_f32_e32 v202, 1.0, v202
	v_mul_f32_e32 v196, v200, v203
	v_div_scale_f32 v203, s[0:1], v202, v202, v132
	v_rcp_f32_e32 v204, v203
	v_mul_f32_e32 v200, v200, v201
	v_cvt_pk_bf16_f32 v200, v200, v147
	global_store_short v[160:161], v200, off offset:352
	v_fma_f32 v200, -v203, v204, 1.0
	v_fmac_f32_e32 v204, v200, v204
	v_div_scale_f32 v200, vcc, v132, v202, v132
	v_mul_f32_e32 v201, v200, v204
	v_fma_f32 v206, -v203, v201, v200
	v_fmac_f32_e32 v201, v206, v204
	v_fma_f32 v200, -v203, v201, v200
	v_add_f32_e32 v203, 1.0, v205
	v_div_scale_f32 v205, s[0:1], v203, v203, v132
	v_rcp_f32_e32 v206, v205
	v_div_fmas_f32 v200, v200, v204, v201
	v_div_fixup_f32 v201, v200, v202, v132
	v_fma_f32 v200, -v205, v206, 1.0
	v_fmac_f32_e32 v206, v200, v206
	v_div_scale_f32 v200, vcc, v132, v203, v132
	v_mul_f32_e32 v202, v200, v206
	v_fma_f32 v204, -v205, v202, v200
	v_fmac_f32_e32 v202, v204, v206
	v_sub_f32_e32 v204, 1.0, v201
	v_fma_f32 v200, -v205, v202, v200
	v_div_fmas_f32 v200, v200, v206, v202
	v_log_f32_e32 v204, v204
	v_div_fixup_f32 v202, v200, v203, v132
	v_mul_f32_e32 v200, 0x3f317217, v204
	v_fma_f32 v200, v204, s72, -v200
	v_fmac_f32_e32 v200, 0x3377d1cf, v204
	v_fmac_f32_e32 v200, 0x3f317217, v204
	v_cmp_lt_f32_e64 vcc, |v204|, s73
	s_nop 1
	v_cndmask_b32_e32 v200, v204, v200, vcc
	v_sub_f32_e32 v203, 1.0, v202
	s_nop 0
	v_add_f32_dpp v200, v200, v200 row_shr:1 row_mask:0xf bank_mask:0xf bound_ctrl:1
	s_nop 0
	v_log_f32_e32 v203, v203
	v_add_f32_dpp v200, v200, v200 row_shr:2 row_mask:0xf bank_mask:0xf bound_ctrl:1
	v_mul_f32_e32 v205, 0x3f317217, v203
	v_fma_f32 v205, v203, s72, -v205
	v_fmac_f32_e32 v205, 0x3377d1cf, v203
	v_add_f32_dpp v200, v200, v200 row_shr:4 row_mask:0xf bank_mask:0xf bound_ctrl:1
	v_fmac_f32_e32 v205, 0x3f317217, v203
	v_cmp_lt_f32_e64 s[0:1], |v203|, s73
	v_add_f32_dpp v204, v200, v200 row_shr:8 row_mask:0xf bank_mask:0xf bound_ctrl:1
	ds_bpermute_b32 v200, v162, v204
	v_cndmask_b32_e64 v203, v203, v205, s[0:1]
	v_mul_f32_e32 v207, 0xbfb8aa3b, v204
	v_exp_f32_e32 v207, v207
	v_add_f32_dpp v203, v203, v203 row_shr:1 row_mask:0xf bank_mask:0xf bound_ctrl:1
	v_mul_f32_e32 v211, v201, v207
	s_nop 0
	v_add_f32_dpp v203, v203, v203 row_shr:2 row_mask:0xf bank_mask:0xf bound_ctrl:1
	v_mul_f32_e32 v207, 0x3fb8aa3b, v93
	v_exp_f32_e32 v207, v207
	v_add_f32_dpp v203, v203, v203 row_shr:4 row_mask:0xf bank_mask:0xf bound_ctrl:1
	s_nop 1
	v_add_f32_dpp v203, v203, v203 row_shr:8 row_mask:0xf bank_mask:0xf bound_ctrl:1
	s_waitcnt lgkmcnt(0)
	v_add_f32_e32 v203, v203, v200
	v_mul_f32_e32 v200, 0x3fb8aa3b, v204
	v_exp_f32_e32 v205, v200
	ds_bpermute_b32 v200, v162, v203
	v_mul_f32_e32 v206, 0x3fb8aa3b, v203
	v_exp_f32_e32 v206, v206
	v_mul_f32_e32 v208, 0xbfb8aa3b, v203
	v_exp_f32_e32 v208, v208
	s_waitcnt lgkmcnt(0)
	v_sub_f32_e32 v204, v200, v204
	v_mul_f32_e32 v204, 0x3fb8aa3b, v204
	v_exp_f32_e32 v204, v204
	v_sub_f32_e32 v203, v200, v203
	v_mul_f32_e32 v203, 0x3fb8aa3b, v203
	v_exp_f32_e32 v203, v203
	v_mul_f32_e32 v201, v201, v204
	v_cvt_pk_bf16_f32 v201, v201, v147
	global_store_short v[160:161], v201, off offset:384
	v_mul_f32_e32 v201, 0x3fb8aa3b, v109
	v_exp_f32_e32 v201, v201
	v_mul_f32_e32 v210, v112, v206
	v_mul_f32_e32 v212, v202, v208
	v_mul_f32_e32 v202, v202, v203
	v_add_f32_e32 v201, 1.0, v201
	v_div_scale_f32 v204, s[0:1], v201, v201, v133
	v_rcp_f32_e32 v206, v204
	v_cvt_pk_bf16_f32 v202, v202, v147
	global_store_short v[160:161], v202, off offset:416
	v_mul_f32_e32 v205, v124, v205
	v_fma_f32 v202, -v204, v206, 1.0
	v_fmac_f32_e32 v206, v202, v206
	v_div_scale_f32 v202, vcc, v133, v201, v133
	v_mul_f32_e32 v203, v202, v206
	v_fma_f32 v208, -v204, v203, v202
	v_fmac_f32_e32 v203, v208, v206
	v_fma_f32 v202, -v204, v203, v202
	v_add_f32_e32 v204, 1.0, v207
	v_div_scale_f32 v207, s[0:1], v204, v204, v133
	v_rcp_f32_e32 v208, v207
	v_div_fmas_f32 v202, v202, v206, v203
	v_div_fixup_f32 v202, v202, v201, v133
	v_fma_f32 v201, -v207, v208, 1.0
	v_fmac_f32_e32 v208, v201, v208
	v_div_scale_f32 v201, vcc, v133, v204, v133
	v_mul_f32_e32 v203, v201, v208
	v_fma_f32 v206, -v207, v203, v201
	v_fmac_f32_e32 v203, v206, v208
	v_sub_f32_e32 v206, 1.0, v202
	v_fma_f32 v201, -v207, v203, v201
	v_div_fmas_f32 v201, v201, v208, v203
	v_log_f32_e32 v206, v206
	v_div_fixup_f32 v203, v201, v204, v133
	v_mul_f32_e32 v201, 0x3f317217, v206
	v_fma_f32 v201, v206, s72, -v201
	v_fmac_f32_e32 v201, 0x3377d1cf, v206
	v_fmac_f32_e32 v201, 0x3f317217, v206
	v_cmp_lt_f32_e64 vcc, |v206|, s73
	s_nop 1
	v_cndmask_b32_e32 v201, v206, v201, vcc
	v_sub_f32_e32 v204, 1.0, v203
	s_nop 0
	v_add_f32_dpp v201, v201, v201 row_shr:1 row_mask:0xf bank_mask:0xf bound_ctrl:1
	s_nop 0
	v_log_f32_e32 v204, v204
	v_add_f32_dpp v201, v201, v201 row_shr:2 row_mask:0xf bank_mask:0xf bound_ctrl:1
	v_mul_f32_e32 v207, 0x3f317217, v204
	v_fma_f32 v207, v204, s72, -v207
	v_fmac_f32_e32 v207, 0x3377d1cf, v204
	v_add_f32_dpp v201, v201, v201 row_shr:4 row_mask:0xf bank_mask:0xf bound_ctrl:1
	v_fmac_f32_e32 v207, 0x3f317217, v204
	v_cmp_lt_f32_e64 s[0:1], |v204|, s73
	v_add_f32_dpp v206, v201, v201 row_shr:8 row_mask:0xf bank_mask:0xf bound_ctrl:1
	ds_bpermute_b32 v201, v162, v206
	v_cndmask_b32_e64 v204, v204, v207, s[0:1]
	v_mul_f32_e32 v207, 0x3fb8aa3b, v206
	v_mul_f32_e32 v209, 0xbfb8aa3b, v206
	v_add_f32_dpp v204, v204, v204 row_shr:1 row_mask:0xf bank_mask:0xf bound_ctrl:1
	v_exp_f32_e32 v209, v209
	v_exp_f32_e32 v207, v207
	v_add_f32_dpp v204, v204, v204 row_shr:2 row_mask:0xf bank_mask:0xf bound_ctrl:1
	v_mul_f32_e32 v216, v202, v209
	s_nop 0
	v_add_f32_dpp v204, v204, v204 row_shr:4 row_mask:0xf bank_mask:0xf bound_ctrl:1
	v_mul_f32_e32 v214, v125, v207
	s_nop 0
	v_add_f32_dpp v204, v204, v204 row_shr:8 row_mask:0xf bank_mask:0xf bound_ctrl:1
	s_waitcnt lgkmcnt(0)
; __device__ __forceinline__ unsigned cvt_pk_bf16(float lo, float hi) { unsigned r; asm volatile("v_cvt_pk_bf16_f32 %0, %1, %2" : "=v"(r) : "v"(lo), "v"(hi)); return r; }
; __device__ __forceinline__ float row_scan16(float v) { v += dpp_shr0<0x111>(v); v += dpp_shr0<0x112>(v); v += dpp_shr0<0x114>(v); v += dpp_shr0<0x118>(v); return v; }
;     __device__ __forceinline__ void operator()(const f32x4 (&acc)[2][2][4][2], const Unit& u, int wr, int wc, int fr, int fq) const {
;     ...
;                     for (int q = 0; q < 4; ++q) { const int j = 4 * n + q;
;                         const float k0 = om[n][q] / (1.0f + __expf(acc[ai][1][2 * mp][n][q])), k1 = om[n][q] / (1.0f + __expf(acc[ai][1][2 * mp + 1][n][q]));
;                         const float p0 = row_scan16(__logf(1.0f - k0)); const float t0 = row_last16(p0, lane);
;                         const float p1 = row_scan16(__logf(1.0f - k1)) + t0; const float bl = row_last16(p1, lane);
;                         const float e0 = __expf(p0), e1 = __expf(p1);
;                         qi[0][j] = acc[ai][0][2 * mp][n][q] * e0; qi[1][j] = acc[ai][0][2 * mp + 1][n][q] * e1;
;                         ki[0][j] = k0 * __expf(-p0); ki[1][j] = k1 * __expf(-p1);
;                         kot[(size_t)j * 32] = (bf16_t)cvt_pk_bf16(k0 * __expf(bl - p0), 0.f); kot[(size_t)j * 32 + 16] = (bf16_t)cvt_pk_bf16(k1 * __expf(bl - p1), 0.f);
;                         dec[j] = __expf(bl); }
; #pragma unroll
;                 for (int mm = 0; mm < 2; ++mm) { const size_t ro = (size_t)(rowa + 16 * mm) * 1024 + colh;
;                     u32x4 w; w.x = cvt_pk_bf16(qi[mm][0], qi[mm][1]); w.y = cvt_pk_bf16(qi[mm][2], qi[mm][3]); w.z = cvt_pk_bf16(qi[mm][4], qi[mm][5]); w.w = cvt_pk_bf16(qi[mm][6], qi[mm][7]);
;                     *(u32x4*)(CQ + ro) = w;
;                     w.x = cvt_pk_bf16(ki[mm][0], ki[mm][1]); w.y = cvt_pk_bf16(ki[mm][2], ki[mm][3]); w.z = cvt_pk_bf16(ki[mm][4], ki[mm][5]); w.w = cvt_pk_bf16(ki[mm][6], ki[mm][7]);
;                     *(u32x4*)(CK + ro) = w; }
;                 if (fr == 15) { float* dp = DEC + (size_t)g * 1024 + colh; *(f32x4*)dp = (f32x4){dec[0], dec[1], dec[2], dec[3]}; *(f32x4*)(dp + 4) = (f32x4){dec[4], dec[5], dec[6], dec[7]}; }
	v_add_f32_e32 v204, v204, v201
	ds_bpermute_b32 v201, v162, v204
	v_mul_f32_e32 v208, 0x3fb8aa3b, v204
	v_mul_f32_e32 v213, 0xbfb8aa3b, v204
	v_exp_f32_e32 v213, v213
	v_exp_f32_e32 v208, v208
	s_waitcnt lgkmcnt(0)
	v_sub_f32_e32 v206, v201, v206
	v_mul_f32_e32 v206, 0x3fb8aa3b, v206
	v_exp_f32_e32 v206, v206
	v_sub_f32_e32 v204, v201, v204
	v_mul_f32_e32 v204, 0x3fb8aa3b, v204
	v_exp_f32_e32 v204, v204
	v_mul_f32_e32 v202, v202, v206
	v_cvt_pk_bf16_f32 v202, v202, v147
	global_store_short v[160:161], v202, off offset:448
	v_mul_f32_e32 v202, v203, v204
	v_cvt_pk_bf16_f32 v202, v202, v147
	global_store_short v[160:161], v202, off offset:480
	v_or_b32_e32 v160, s2, v1
	v_ashrrev_i32_e32 v161, 31, v160
	v_mul_f32_e32 v213, v203, v213
	v_lshlrev_b64 v[202:203], 10, v[160:161]
	v_or_b32_e32 v160, 16, v160
	v_lshl_add_u64 v[206:207], v[202:203], 0, v[158:159]
	v_ashrrev_i32_e32 v161, 31, v160
	v_lshlrev_b64 v[206:207], 1, v[206:207]
	v_lshlrev_b64 v[160:161], 10, v[160:161]
	v_mul_f32_e32 v215, v113, v208
	v_cvt_pk_bf16_f32 v202, v173, v177
	v_cvt_pk_bf16_f32 v203, v182, v188
	v_cvt_pk_bf16_f32 v204, v193, v198
	v_cvt_pk_bf16_f32 v205, v205, v214
	v_lshl_add_u64 v[208:209], s[64:65], 0, v[206:207]
	v_lshl_add_u64 v[160:161], v[160:161], 0, v[158:159]
	global_store_dwordx4 v[208:209], v[202:205], off
	v_lshlrev_b64 v[160:161], 1, v[160:161]
	s_nop 0
	v_cvt_pk_bf16_f32 v202, v172, v178
	v_cvt_pk_bf16_f32 v203, v183, v189
	v_cvt_pk_bf16_f32 v204, v194, v199
	v_cvt_pk_bf16_f32 v205, v211, v216
	v_lshl_add_u64 v[172:173], s[14:15], 0, v[206:207]
	global_store_dwordx4 v[172:173], v[202:205], off
	s_nop 1
	v_lshl_add_u64 v[172:173], s[64:65], 0, v[160:161]
	v_lshl_add_u64 v[160:161], s[14:15], 0, v[160:161]
	v_cvt_pk_bf16_f32 v202, v171, v176
	v_cvt_pk_bf16_f32 v203, v181, v187
	v_cvt_pk_bf16_f32 v204, v192, v197
	v_cvt_pk_bf16_f32 v205, v210, v215
	global_store_dwordx4 v[172:173], v[202:205], off
	s_nop 1
	v_cvt_pk_bf16_f32 v202, v131, v175
	v_cvt_pk_bf16_f32 v203, v180, v185
	v_cvt_pk_bf16_f32 v204, v191, v196
	v_cvt_pk_bf16_f32 v205, v212, v213
	global_store_dwordx4 v[160:161], v[202:205], off
	s_and_saveexec_b64 s[0:1], s[4:5]
	s_cbranch_execz .LBB0_1147
	v_mul_f32_e32 v131, 0x3fb8aa3b, v201
	v_exp_f32_e32 v183, v131
	v_mul_f32_e32 v131, 0x3fb8aa3b, v200
	v_exp_f32_e32 v182, v131
	v_mul_f32_e32 v131, 0x3fb8aa3b, v195
	v_exp_f32_e32 v181, v131
	v_mul_f32_e32 v131, 0x3fb8aa3b, v190
	v_exp_f32_e32 v180, v131
	v_mul_f32_e32 v131, 0x3fb8aa3b, v184
	v_exp_f32_e32 v177, v131
	v_mul_f32_e32 v131, 0x3fb8aa3b, v179
	v_exp_f32_e32 v176, v131
	v_mul_f32_e32 v131, 0x3fb8aa3b, v174
	v_mul_f32_e32 v130, 0x3fb8aa3b, v130
	v_exp_f32_e32 v175, v131
	v_exp_f32_e32 v174, v130
	s_lshl_b64 s[8:9], s[38:39], 2
	s_add_u32 s8, s47, s8
	s_addc_u32 s9, s52, s9
	v_lshl_add_u64 v[130:131], v[158:159], 2, s[8:9]
	global_store_dwordx4 v[130:131], v[174:177], off
	global_store_dwordx4 v[130:131], v[180:183], off offset:16
.LBB0_1147:
	s_or_b64 exec, exec, s[0:1]
	v_mul_f32_e32 v130, 0x3fb8aa3b, v82
	v_exp_f32_e32 v130, v130
	s_or_b32 s3, s2, 32
	s_ashr_i32 s0, s3, 5
	s_ashr_i32 s1, s0, 31
	v_add_f32_e32 v160, 1.0, v130
	s_lshl_b64 s[8:9], s[0:1], 10
	v_div_scale_f32 v161, s[0:1], v160, v160, v170
	v_rcp_f32_e32 v171, v161
	v_mul_f32_e32 v174, 0x3fb8aa3b, v70
	v_exp_f32_e32 v174, v174
	v_lshl_add_u64 v[130:131], s[8:9], 0, v[158:159]
	v_fma_f32 v172, -v161, v171, 1.0
	v_fmac_f32_e32 v171, v172, v171
	v_div_scale_f32 v172, vcc, v170, v160, v170
	v_mul_f32_e32 v173, v172, v171
	v_fma_f32 v175, -v161, v173, v172
	v_fmac_f32_e32 v173, v175, v171
	v_fma_f32 v161, -v161, v173, v172
	v_add_f32_e32 v172, 1.0, v174
	v_div_scale_f32 v174, s[0:1], v172, v172, v170
	v_rcp_f32_e32 v175, v174
	v_div_fmas_f32 v161, v161, v171, v173
	v_div_fixup_f32 v176, v161, v160, v170
	v_lshlrev_b64 v[130:131], 6, v[130:131]
	v_fma_f32 v160, -v174, v175, 1.0
	v_fmac_f32_e32 v175, v160, v175
	v_div_scale_f32 v160, vcc, v170, v172, v170
	v_mul_f32_e32 v161, v160, v175
	v_fma_f32 v171, -v174, v161, v160
	v_fmac_f32_e32 v161, v171, v175
	v_sub_f32_e32 v171, 1.0, v176
	v_fma_f32 v160, -v174, v161, v160
	v_div_fmas_f32 v160, v160, v175, v161
	v_log_f32_e32 v171, v171
	v_div_fixup_f32 v174, v160, v172, v170
	v_lshl_add_u64 v[130:131], v[148:149], 0, v[130:131]
	v_mul_f32_e32 v160, 0x3f317217, v171
	v_fma_f32 v160, v171, s72, -v160
	v_fmac_f32_e32 v160, 0x3377d1cf, v171
	v_fmac_f32_e32 v160, 0x3f317217, v171
	v_cmp_lt_f32_e64 vcc, |v171|, s73
	v_mul_f32_e32 v179, 0x3fb8aa3b, v71
	v_exp_f32_e32 v179, v179
	v_cndmask_b32_e32 v160, v171, v160, vcc
	v_sub_f32_e32 v161, 1.0, v174
	s_nop 0
	v_add_f32_dpp v160, v160, v160 row_shr:1 row_mask:0xf bank_mask:0xf bound_ctrl:1
	v_mul_f32_e32 v184, 0x3fb8aa3b, v72
	v_log_f32_e32 v161, v161
	v_add_f32_dpp v160, v160, v160 row_shr:2 row_mask:0xf bank_mask:0xf bound_ctrl:1
	v_exp_f32_e32 v184, v184
	v_mul_f32_e32 v190, 0x3fb8aa3b, v73
	v_mul_f32_e32 v172, 0x3f317217, v161
	v_fma_f32 v172, v161, s72, -v172
	v_fmac_f32_e32 v172, 0x3377d1cf, v161
	v_add_f32_dpp v160, v160, v160 row_shr:4 row_mask:0xf bank_mask:0xf bound_ctrl:1
	v_fmac_f32_e32 v172, 0x3f317217, v161
	v_cmp_lt_f32_e64 s[0:1], |v161|, s73
	v_add_f32_dpp v171, v160, v160 row_shr:8 row_mask:0xf bank_mask:0xf bound_ctrl:1
	ds_bpermute_b32 v160, v162, v171
	v_cndmask_b32_e64 v161, v161, v172, s[0:1]
	v_exp_f32_e32 v190, v190
	v_mul_f32_e32 v195, 0x3fb8aa3b, v66
	v_add_f32_dpp v161, v161, v161 row_shr:1 row_mask:0xf bank_mask:0xf bound_ctrl:1
	v_exp_f32_e32 v195, v195
	s_nop 0
	v_add_f32_dpp v161, v161, v161 row_shr:2 row_mask:0xf bank_mask:0xf bound_ctrl:1
	s_nop 1
	v_add_f32_dpp v161, v161, v161 row_shr:4 row_mask:0xf bank_mask:0xf bound_ctrl:1
	s_nop 1
	v_add_f32_dpp v161, v161, v161 row_shr:8 row_mask:0xf bank_mask:0xf bound_ctrl:1
	s_waitcnt lgkmcnt(0)
; __device__ __forceinline__ unsigned cvt_pk_bf16(float lo, float hi) { unsigned r; asm volatile("v_cvt_pk_bf16_f32 %0, %1, %2" : "=v"(r) : "v"(lo), "v"(hi)); return r; }
; __device__ __forceinline__ float row_scan16(float v) { v += dpp_shr0<0x111>(v); v += dpp_shr0<0x112>(v); v += dpp_shr0<0x114>(v); v += dpp_shr0<0x118>(v); return v; }
; __device__ __forceinline__ float row_last16(float v, int lane) { return __builtin_bit_cast(float, __builtin_amdgcn_ds_bpermute((lane | 15) << 2, __builtin_bit_cast(int, v))); }
;     __device__ __forceinline__ void operator()(const f32x4 (&acc)[2][2][4][2], const Unit& u, int wr, int wc, int fr, int fq) const {
;     ...
;                     for (int q = 0; q < 4; ++q) { const int j = 4 * n + q;
;                         const float k0 = om[n][q] / (1.0f + __expf(acc[ai][1][2 * mp][n][q])), k1 = om[n][q] / (1.0f + __expf(acc[ai][1][2 * mp + 1][n][q]));
;                         const float p0 = row_scan16(__logf(1.0f - k0)); const float t0 = row_last16(p0, lane);
;                         const float p1 = row_scan16(__logf(1.0f - k1)) + t0; const float bl = row_last16(p1, lane);
;                         const float e0 = __expf(p0), e1 = __expf(p1);
;                         qi[0][j] = acc[ai][0][2 * mp][n][q] * e0; qi[1][j] = acc[ai][0][2 * mp + 1][n][q] * e1;
;                         ki[0][j] = k0 * __expf(-p0); ki[1][j] = k1 * __expf(-p1);
;                         kot[(size_t)j * 32] = (bf16_t)cvt_pk_bf16(k0 * __expf(bl - p0), 0.f); kot[(size_t)j * 32 + 16] = (bf16_t)cvt_pk_bf16(k1 * __expf(bl - p1), 0.f);
;                         dec[j] = __expf(bl); }
	v_add_f32_e32 v175, v161, v160
	v_mul_f32_e32 v160, 0x3fb8aa3b, v171
	v_exp_f32_e32 v161, v160
	ds_bpermute_b32 v160, v162, v175
	v_mul_f32_e32 v172, 0x3fb8aa3b, v175
	v_exp_f32_e32 v173, v172
	v_mul_f32_e32 v172, v102, v161
	v_mul_f32_e32 v161, 0xbfb8aa3b, v171
	s_waitcnt lgkmcnt(0)
	v_sub_f32_e32 v171, v160, v171
	v_mul_f32_e32 v171, 0x3fb8aa3b, v171
	v_exp_f32_e32 v161, v161
	v_exp_f32_e32 v178, v171
	v_mul_f32_e32 v171, v86, v173
	v_mul_f32_e32 v177, 0xbfb8aa3b, v175
	v_mul_f32_e32 v173, v176, v161
	v_mul_f32_e32 v176, v176, v178
	v_cvt_pk_bf16_f32 v176, v176, v147
	global_store_short v[130:131], v176, off
	v_mul_f32_e32 v176, 0x3fb8aa3b, v83
	v_exp_f32_e32 v176, v176
	v_exp_f32_e32 v177, v177
	v_sub_f32_e32 v175, v160, v175
	v_mul_f32_e32 v175, 0x3fb8aa3b, v175
	v_exp_f32_e32 v175, v175
	v_add_f32_e32 v176, 1.0, v176
	v_mul_f32_e32 v161, v174, v177
	v_div_scale_f32 v177, s[0:1], v176, v176, v146
	v_rcp_f32_e32 v178, v177
	v_mul_f32_e32 v174, v174, v175
	v_cvt_pk_bf16_f32 v174, v174, v147
	global_store_short v[130:131], v174, off offset:32
	v_fma_f32 v174, -v177, v178, 1.0
	v_fmac_f32_e32 v178, v174, v178
	v_div_scale_f32 v174, vcc, v146, v176, v146
	v_mul_f32_e32 v175, v174, v178
	v_fma_f32 v180, -v177, v175, v174
	v_fmac_f32_e32 v175, v180, v178
	v_fma_f32 v174, -v177, v175, v174
	v_add_f32_e32 v177, 1.0, v179
	v_div_scale_f32 v179, s[0:1], v177, v177, v146
	v_rcp_f32_e32 v180, v179
	v_div_fmas_f32 v174, v174, v178, v175
	v_div_fixup_f32 v181, v174, v176, v146
	v_fma_f32 v174, -v179, v180, 1.0
	v_fmac_f32_e32 v180, v174, v180
	v_div_scale_f32 v174, vcc, v146, v177, v146
	v_mul_f32_e32 v175, v174, v180
	v_fma_f32 v176, -v179, v175, v174
	v_fmac_f32_e32 v175, v176, v180
	v_sub_f32_e32 v176, 1.0, v181
	v_fma_f32 v174, -v179, v175, v174
	v_div_fmas_f32 v174, v174, v180, v175
	v_log_f32_e32 v176, v176
	v_div_fixup_f32 v179, v174, v177, v146
	v_mul_f32_e32 v174, 0x3f317217, v176
	v_fma_f32 v174, v176, s72, -v174
	v_fmac_f32_e32 v174, 0x3377d1cf, v176
	v_fmac_f32_e32 v174, 0x3f317217, v176
	v_cmp_lt_f32_e64 vcc, |v176|, s73
	s_nop 1
	v_cndmask_b32_e32 v174, v176, v174, vcc
	v_sub_f32_e32 v175, 1.0, v179
	s_nop 0
	v_add_f32_dpp v174, v174, v174 row_shr:1 row_mask:0xf bank_mask:0xf bound_ctrl:1
	s_nop 0
	v_log_f32_e32 v175, v175
	v_add_f32_dpp v174, v174, v174 row_shr:2 row_mask:0xf bank_mask:0xf bound_ctrl:1
	v_mul_f32_e32 v177, 0x3f317217, v175
	v_fma_f32 v177, v175, s72, -v177
	v_fmac_f32_e32 v177, 0x3377d1cf, v175
	v_add_f32_dpp v174, v174, v174 row_shr:4 row_mask:0xf bank_mask:0xf bound_ctrl:1
	v_fmac_f32_e32 v177, 0x3f317217, v175
	v_cmp_lt_f32_e64 s[0:1], |v175|, s73
	v_add_f32_dpp v176, v174, v174 row_shr:8 row_mask:0xf bank_mask:0xf bound_ctrl:1
	ds_bpermute_b32 v174, v162, v176
	v_cndmask_b32_e64 v175, v175, v177, s[0:1]
	s_nop 1
	v_add_f32_dpp v175, v175, v175 row_shr:1 row_mask:0xf bank_mask:0xf bound_ctrl:1
	s_nop 1
	v_add_f32_dpp v175, v175, v175 row_shr:2 row_mask:0xf bank_mask:0xf bound_ctrl:1
	s_nop 1
	v_add_f32_dpp v175, v175, v175 row_shr:4 row_mask:0xf bank_mask:0xf bound_ctrl:1
	s_nop 1
	v_add_f32_dpp v175, v175, v175 row_shr:8 row_mask:0xf bank_mask:0xf bound_ctrl:1
	s_waitcnt lgkmcnt(0)
	v_add_f32_e32 v180, v175, v174
	v_mul_f32_e32 v174, 0x3fb8aa3b, v176
	v_exp_f32_e32 v175, v174
	ds_bpermute_b32 v174, v162, v180
	v_mul_f32_e32 v177, 0x3fb8aa3b, v180
	v_exp_f32_e32 v178, v177
	v_mul_f32_e32 v177, v103, v175
	v_mul_f32_e32 v175, 0xbfb8aa3b, v176
	s_waitcnt lgkmcnt(0)
	v_sub_f32_e32 v176, v174, v176
	v_mul_f32_e32 v176, 0x3fb8aa3b, v176
	v_exp_f32_e32 v175, v175
	v_exp_f32_e32 v183, v176
	v_mul_f32_e32 v176, v87, v178
	v_mul_f32_e32 v182, 0xbfb8aa3b, v180
	v_mul_f32_e32 v178, v181, v175
	v_mul_f32_e32 v181, v181, v183
	v_cvt_pk_bf16_f32 v181, v181, v147
	global_store_short v[130:131], v181, off offset:64
	v_mul_f32_e32 v181, 0x3fb8aa3b, v84
	v_exp_f32_e32 v181, v181
	v_exp_f32_e32 v182, v182
	v_sub_f32_e32 v180, v174, v180
	v_mul_f32_e32 v180, 0x3fb8aa3b, v180
	v_exp_f32_e32 v180, v180
	v_add_f32_e32 v181, 1.0, v181
	v_mul_f32_e32 v175, v179, v182
	v_div_scale_f32 v182, s[0:1], v181, v181, v136
	v_rcp_f32_e32 v183, v182
	v_mul_f32_e32 v179, v179, v180
	v_cvt_pk_bf16_f32 v179, v179, v147
	global_store_short v[130:131], v179, off offset:96
	v_fma_f32 v179, -v182, v183, 1.0
	v_fmac_f32_e32 v183, v179, v183
	v_div_scale_f32 v179, vcc, v136, v181, v136
	v_mul_f32_e32 v180, v179, v183
	v_fma_f32 v185, -v182, v180, v179
	v_fmac_f32_e32 v180, v185, v183
	v_fma_f32 v179, -v182, v180, v179
	v_add_f32_e32 v182, 1.0, v184
	v_div_scale_f32 v184, s[0:1], v182, v182, v136
	v_rcp_f32_e32 v185, v184
	v_div_fmas_f32 v179, v179, v183, v180
	v_div_fixup_f32 v187, v179, v181, v136
	v_fma_f32 v179, -v184, v185, 1.0
	v_fmac_f32_e32 v185, v179, v185
	v_div_scale_f32 v179, vcc, v136, v182, v136
	v_mul_f32_e32 v180, v179, v185
	v_fma_f32 v181, -v184, v180, v179
	v_fmac_f32_e32 v180, v181, v185
	v_sub_f32_e32 v181, 1.0, v187
	v_fma_f32 v179, -v184, v180, v179
	v_div_fmas_f32 v179, v179, v185, v180
	v_log_f32_e32 v181, v181
	v_div_fixup_f32 v184, v179, v182, v136
	v_mul_f32_e32 v179, 0x3f317217, v181
	v_fma_f32 v179, v181, s72, -v179
	v_fmac_f32_e32 v179, 0x3377d1cf, v181
	v_fmac_f32_e32 v179, 0x3f317217, v181
	v_cmp_lt_f32_e64 vcc, |v181|, s73
	s_nop 1
	v_cndmask_b32_e32 v179, v181, v179, vcc
	v_sub_f32_e32 v180, 1.0, v184
	s_nop 0
	v_add_f32_dpp v179, v179, v179 row_shr:1 row_mask:0xf bank_mask:0xf bound_ctrl:1
	s_nop 0
	v_log_f32_e32 v180, v180
	v_add_f32_dpp v179, v179, v179 row_shr:2 row_mask:0xf bank_mask:0xf bound_ctrl:1
	v_mul_f32_e32 v182, 0x3f317217, v180
	v_fma_f32 v182, v180, s72, -v182
	v_fmac_f32_e32 v182, 0x3377d1cf, v180
	v_add_f32_dpp v179, v179, v179 row_shr:4 row_mask:0xf bank_mask:0xf bound_ctrl:1
	v_fmac_f32_e32 v182, 0x3f317217, v180
	v_cmp_lt_f32_e64 s[0:1], |v180|, s73
	v_add_f32_dpp v181, v179, v179 row_shr:8 row_mask:0xf bank_mask:0xf bound_ctrl:1
	ds_bpermute_b32 v179, v162, v181
	v_cndmask_b32_e64 v180, v180, v182, s[0:1]
	s_nop 1
	v_add_f32_dpp v180, v180, v180 row_shr:1 row_mask:0xf bank_mask:0xf bound_ctrl:1
	s_nop 1
	v_add_f32_dpp v180, v180, v180 row_shr:2 row_mask:0xf bank_mask:0xf bound_ctrl:1
	s_nop 1
	v_add_f32_dpp v180, v180, v180 row_shr:4 row_mask:0xf bank_mask:0xf bound_ctrl:1
	s_nop 1
	v_add_f32_dpp v180, v180, v180 row_shr:8 row_mask:0xf bank_mask:0xf bound_ctrl:1
	s_waitcnt lgkmcnt(0)
; __device__ __forceinline__ unsigned cvt_pk_bf16(float lo, float hi) { unsigned r; asm volatile("v_cvt_pk_bf16_f32 %0, %1, %2" : "=v"(r) : "v"(lo), "v"(hi)); return r; }
; __device__ __forceinline__ float row_scan16(float v) { v += dpp_shr0<0x111>(v); v += dpp_shr0<0x112>(v); v += dpp_shr0<0x114>(v); v += dpp_shr0<0x118>(v); return v; }
; __device__ __forceinline__ float row_last16(float v, int lane) { return __builtin_bit_cast(float, __builtin_amdgcn_ds_bpermute((lane | 15) << 2, __builtin_bit_cast(int, v))); }
;     __device__ __forceinline__ void operator()(const f32x4 (&acc)[2][2][4][2], const Unit& u, int wr, int wc, int fr, int fq) const {
;     ...
;                     for (int q = 0; q < 4; ++q) { const int j = 4 * n + q;
;                         const float k0 = om[n][q] / (1.0f + __expf(acc[ai][1][2 * mp][n][q])), k1 = om[n][q] / (1.0f + __expf(acc[ai][1][2 * mp + 1][n][q]));
;                         const float p0 = row_scan16(__logf(1.0f - k0)); const float t0 = row_last16(p0, lane);
;                         const float p1 = row_scan16(__logf(1.0f - k1)) + t0; const float bl = row_last16(p1, lane);
;                         const float e0 = __expf(p0), e1 = __expf(p1);
;                         qi[0][j] = acc[ai][0][2 * mp][n][q] * e0; qi[1][j] = acc[ai][0][2 * mp + 1][n][q] * e1;
;                         ki[0][j] = k0 * __expf(-p0); ki[1][j] = k1 * __expf(-p1);
;                         kot[(size_t)j * 32] = (bf16_t)cvt_pk_bf16(k0 * __expf(bl - p0), 0.f); kot[(size_t)j * 32 + 16] = (bf16_t)cvt_pk_bf16(k1 * __expf(bl - p1), 0.f);
;                         dec[j] = __expf(bl); }
	v_add_f32_e32 v185, v180, v179
	v_mul_f32_e32 v179, 0x3fb8aa3b, v181
	v_exp_f32_e32 v180, v179
	ds_bpermute_b32 v179, v162, v185
	v_mul_f32_e32 v182, 0x3fb8aa3b, v185
	v_exp_f32_e32 v183, v182
	v_mul_f32_e32 v182, v104, v180
	v_mul_f32_e32 v180, 0xbfb8aa3b, v181
	s_waitcnt lgkmcnt(0)
	v_sub_f32_e32 v181, v179, v181
	v_mul_f32_e32 v181, 0x3fb8aa3b, v181
	v_exp_f32_e32 v180, v180
	v_exp_f32_e32 v189, v181
	v_mul_f32_e32 v181, v88, v183
	v_mul_f32_e32 v188, 0xbfb8aa3b, v185
	v_mul_f32_e32 v183, v187, v180
	v_mul_f32_e32 v187, v187, v189
	v_cvt_pk_bf16_f32 v187, v187, v147
	global_store_short v[130:131], v187, off offset:128
	v_mul_f32_e32 v187, 0x3fb8aa3b, v85
	v_exp_f32_e32 v187, v187
	v_exp_f32_e32 v188, v188
	v_sub_f32_e32 v185, v179, v185
	v_mul_f32_e32 v185, 0x3fb8aa3b, v185
	v_exp_f32_e32 v185, v185
	v_add_f32_e32 v187, 1.0, v187
	v_mul_f32_e32 v180, v184, v188
	v_div_scale_f32 v188, s[0:1], v187, v187, v137
	v_rcp_f32_e32 v189, v188
	v_mul_f32_e32 v184, v184, v185
	v_cvt_pk_bf16_f32 v184, v184, v147
	global_store_short v[130:131], v184, off offset:160
	v_fma_f32 v184, -v188, v189, 1.0
	v_fmac_f32_e32 v189, v184, v189
	v_div_scale_f32 v184, vcc, v137, v187, v137
	v_mul_f32_e32 v185, v184, v189
	v_fma_f32 v191, -v188, v185, v184
	v_fmac_f32_e32 v185, v191, v189
	v_fma_f32 v184, -v188, v185, v184
	v_add_f32_e32 v188, 1.0, v190
	v_div_scale_f32 v190, s[0:1], v188, v188, v137
	v_rcp_f32_e32 v191, v190
	v_div_fmas_f32 v184, v184, v189, v185
	v_div_fixup_f32 v192, v184, v187, v137
	v_fma_f32 v184, -v190, v191, 1.0
	v_fmac_f32_e32 v191, v184, v191
	v_div_scale_f32 v184, vcc, v137, v188, v137
	v_mul_f32_e32 v185, v184, v191
	v_fma_f32 v187, -v190, v185, v184
	v_fmac_f32_e32 v185, v187, v191
	v_sub_f32_e32 v187, 1.0, v192
	v_fma_f32 v184, -v190, v185, v184
	v_div_fmas_f32 v184, v184, v191, v185
	v_log_f32_e32 v187, v187
	v_div_fixup_f32 v190, v184, v188, v137
	v_mul_f32_e32 v184, 0x3f317217, v187
	v_fma_f32 v184, v187, s72, -v184
	v_fmac_f32_e32 v184, 0x3377d1cf, v187
	v_fmac_f32_e32 v184, 0x3f317217, v187
	v_cmp_lt_f32_e64 vcc, |v187|, s73
	s_nop 1
	v_cndmask_b32_e32 v184, v187, v184, vcc
	v_sub_f32_e32 v185, 1.0, v190
	s_nop 0
	v_add_f32_dpp v184, v184, v184 row_shr:1 row_mask:0xf bank_mask:0xf bound_ctrl:1
	s_nop 0
	v_log_f32_e32 v185, v185
	v_add_f32_dpp v184, v184, v184 row_shr:2 row_mask:0xf bank_mask:0xf bound_ctrl:1
	v_mul_f32_e32 v188, 0x3f317217, v185
	v_fma_f32 v188, v185, s72, -v188
	v_fmac_f32_e32 v188, 0x3377d1cf, v185
	v_add_f32_dpp v184, v184, v184 row_shr:4 row_mask:0xf bank_mask:0xf bound_ctrl:1
	v_fmac_f32_e32 v188, 0x3f317217, v185
	v_cmp_lt_f32_e64 s[0:1], |v185|, s73
	v_add_f32_dpp v187, v184, v184 row_shr:8 row_mask:0xf bank_mask:0xf bound_ctrl:1
	ds_bpermute_b32 v184, v162, v187
	v_cndmask_b32_e64 v185, v185, v188, s[0:1]
	s_nop 1
	v_add_f32_dpp v185, v185, v185 row_shr:1 row_mask:0xf bank_mask:0xf bound_ctrl:1
	s_nop 1
	v_add_f32_dpp v185, v185, v185 row_shr:2 row_mask:0xf bank_mask:0xf bound_ctrl:1
	s_nop 1
	v_add_f32_dpp v185, v185, v185 row_shr:4 row_mask:0xf bank_mask:0xf bound_ctrl:1
	s_nop 1
	v_add_f32_dpp v185, v185, v185 row_shr:8 row_mask:0xf bank_mask:0xf bound_ctrl:1
	s_waitcnt lgkmcnt(0)
	v_add_f32_e32 v191, v185, v184
	v_mul_f32_e32 v184, 0x3fb8aa3b, v187
	v_exp_f32_e32 v185, v184
	ds_bpermute_b32 v184, v162, v191
	v_mul_f32_e32 v188, 0x3fb8aa3b, v191
	v_exp_f32_e32 v189, v188
	v_mul_f32_e32 v188, v105, v185
	v_mul_f32_e32 v185, 0xbfb8aa3b, v187
	s_waitcnt lgkmcnt(0)
	v_sub_f32_e32 v187, v184, v187
	v_mul_f32_e32 v187, 0x3fb8aa3b, v187
	v_exp_f32_e32 v185, v185
	v_exp_f32_e32 v194, v187
	v_mul_f32_e32 v187, v89, v189
	v_mul_f32_e32 v193, 0xbfb8aa3b, v191
	v_mul_f32_e32 v189, v192, v185
	v_mul_f32_e32 v192, v192, v194
	v_cvt_pk_bf16_f32 v192, v192, v147
	global_store_short v[130:131], v192, off offset:192
	v_mul_f32_e32 v192, 0x3fb8aa3b, v74
	v_exp_f32_e32 v192, v192
	v_exp_f32_e32 v193, v193
	v_sub_f32_e32 v191, v184, v191
	v_mul_f32_e32 v191, 0x3fb8aa3b, v191
	v_exp_f32_e32 v191, v191
	v_add_f32_e32 v192, 1.0, v192
	v_mul_f32_e32 v185, v190, v193
	v_div_scale_f32 v193, s[0:1], v192, v192, v135
	v_rcp_f32_e32 v194, v193
	v_mul_f32_e32 v190, v190, v191
	v_cvt_pk_bf16_f32 v190, v190, v147
	global_store_short v[130:131], v190, off offset:224
	v_fma_f32 v190, -v193, v194, 1.0
	v_fmac_f32_e32 v194, v190, v194
	v_div_scale_f32 v190, vcc, v135, v192, v135
	v_mul_f32_e32 v191, v190, v194
	v_fma_f32 v196, -v193, v191, v190
	v_fmac_f32_e32 v191, v196, v194
	v_fma_f32 v190, -v193, v191, v190
	v_add_f32_e32 v193, 1.0, v195
	v_div_scale_f32 v195, s[0:1], v193, v193, v135
	v_rcp_f32_e32 v196, v195
	v_div_fmas_f32 v190, v190, v194, v191
	v_div_fixup_f32 v191, v190, v192, v135
	v_fma_f32 v190, -v195, v196, 1.0
	v_fmac_f32_e32 v196, v190, v196
	v_div_scale_f32 v190, vcc, v135, v193, v135
	v_mul_f32_e32 v192, v190, v196
	v_fma_f32 v194, -v195, v192, v190
	v_fmac_f32_e32 v192, v194, v196
	v_sub_f32_e32 v194, 1.0, v191
	v_fma_f32 v190, -v195, v192, v190
	v_div_fmas_f32 v190, v190, v196, v192
	v_log_f32_e32 v194, v194
	v_div_fixup_f32 v192, v190, v193, v135
	v_mul_f32_e32 v190, 0x3f317217, v194
	v_fma_f32 v190, v194, s72, -v190
	v_fmac_f32_e32 v190, 0x3377d1cf, v194
	v_fmac_f32_e32 v190, 0x3f317217, v194
	v_cmp_lt_f32_e64 vcc, |v194|, s73
	s_nop 1
	v_cndmask_b32_e32 v190, v194, v190, vcc
	v_sub_f32_e32 v193, 1.0, v192
	s_nop 0
	v_add_f32_dpp v190, v190, v190 row_shr:1 row_mask:0xf bank_mask:0xf bound_ctrl:1
	s_nop 0
	v_log_f32_e32 v193, v193
	v_add_f32_dpp v190, v190, v190 row_shr:2 row_mask:0xf bank_mask:0xf bound_ctrl:1
	v_mul_f32_e32 v195, 0x3f317217, v193
	v_fma_f32 v195, v193, s72, -v195
	v_fmac_f32_e32 v195, 0x3377d1cf, v193
	v_add_f32_dpp v190, v190, v190 row_shr:4 row_mask:0xf bank_mask:0xf bound_ctrl:1
	v_fmac_f32_e32 v195, 0x3f317217, v193
	v_cmp_lt_f32_e64 s[0:1], |v193|, s73
	v_add_f32_dpp v194, v190, v190 row_shr:8 row_mask:0xf bank_mask:0xf bound_ctrl:1
	ds_bpermute_b32 v190, v162, v194
	v_cndmask_b32_e64 v193, v193, v195, s[0:1]
	s_nop 1
	v_add_f32_dpp v193, v193, v193 row_shr:1 row_mask:0xf bank_mask:0xf bound_ctrl:1
	s_nop 1
	v_add_f32_dpp v193, v193, v193 row_shr:2 row_mask:0xf bank_mask:0xf bound_ctrl:1
	s_nop 1
	v_add_f32_dpp v193, v193, v193 row_shr:4 row_mask:0xf bank_mask:0xf bound_ctrl:1
	s_nop 1
	v_add_f32_dpp v193, v193, v193 row_shr:8 row_mask:0xf bank_mask:0xf bound_ctrl:1
	s_waitcnt lgkmcnt(0)
; __device__ __forceinline__ unsigned cvt_pk_bf16(float lo, float hi) { unsigned r; asm volatile("v_cvt_pk_bf16_f32 %0, %1, %2" : "=v"(r) : "v"(lo), "v"(hi)); return r; }
; __device__ __forceinline__ float row_scan16(float v) { v += dpp_shr0<0x111>(v); v += dpp_shr0<0x112>(v); v += dpp_shr0<0x114>(v); v += dpp_shr0<0x118>(v); return v; }
; __device__ __forceinline__ float row_last16(float v, int lane) { return __builtin_bit_cast(float, __builtin_amdgcn_ds_bpermute((lane | 15) << 2, __builtin_bit_cast(int, v))); }
;     __device__ __forceinline__ void operator()(const f32x4 (&acc)[2][2][4][2], const Unit& u, int wr, int wc, int fr, int fq) const {
;     ...
;                     for (int q = 0; q < 4; ++q) { const int j = 4 * n + q;
;                         const float k0 = om[n][q] / (1.0f + __expf(acc[ai][1][2 * mp][n][q])), k1 = om[n][q] / (1.0f + __expf(acc[ai][1][2 * mp + 1][n][q]));
;                         const float p0 = row_scan16(__logf(1.0f - k0)); const float t0 = row_last16(p0, lane);
;                         const float p1 = row_scan16(__logf(1.0f - k1)) + t0; const float bl = row_last16(p1, lane);
;                         const float e0 = __expf(p0), e1 = __expf(p1);
;                         qi[0][j] = acc[ai][0][2 * mp][n][q] * e0; qi[1][j] = acc[ai][0][2 * mp + 1][n][q] * e1;
;                         ki[0][j] = k0 * __expf(-p0); ki[1][j] = k1 * __expf(-p1);
;                         kot[(size_t)j * 32] = (bf16_t)cvt_pk_bf16(k0 * __expf(bl - p0), 0.f); kot[(size_t)j * 32 + 16] = (bf16_t)cvt_pk_bf16(k1 * __expf(bl - p1), 0.f);
;                         dec[j] = __expf(bl); }
	v_add_f32_e32 v193, v193, v190
	v_mul_f32_e32 v190, 0x3fb8aa3b, v194
	v_exp_f32_e32 v195, v190
	ds_bpermute_b32 v190, v162, v193
	v_mul_f32_e32 v196, 0x3fb8aa3b, v193
	v_mul_f32_e32 v198, 0xbfb8aa3b, v193
	v_mul_f32_e32 v197, v94, v195
	v_mul_f32_e32 v195, 0xbfb8aa3b, v194
	s_waitcnt lgkmcnt(0)
	v_sub_f32_e32 v194, v190, v194
	v_mul_f32_e32 v194, 0x3fb8aa3b, v194
	v_exp_f32_e32 v195, v195
	v_exp_f32_e32 v194, v194
	v_sub_f32_e32 v193, v190, v193
	v_mul_f32_e32 v193, 0x3fb8aa3b, v193
	v_mul_f32_e32 v203, v191, v195
	v_mul_f32_e32 v191, v191, v194
	v_cvt_pk_bf16_f32 v191, v191, v147
	global_store_short v[130:131], v191, off offset:256
	v_mul_f32_e32 v191, 0x3fb8aa3b, v75
	v_exp_f32_e32 v191, v191
	v_exp_f32_e32 v198, v198
	v_exp_f32_e32 v193, v193
	v_exp_f32_e32 v196, v196
	v_add_f32_e32 v191, 1.0, v191
	v_div_scale_f32 v194, s[0:1], v191, v191, v134
	v_rcp_f32_e32 v195, v194
	v_mul_f32_e32 v204, v192, v198
	v_mul_f32_e32 v192, v192, v193
	v_cvt_pk_bf16_f32 v192, v192, v147
	v_mul_f32_e32 v202, v78, v196
	global_store_short v[130:131], v192, off offset:288
	v_fma_f32 v192, -v194, v195, 1.0
	v_mul_f32_e32 v196, 0x3fb8aa3b, v67
	v_fmac_f32_e32 v195, v192, v195
	v_div_scale_f32 v192, vcc, v134, v191, v134
	v_exp_f32_e32 v196, v196
	v_mul_f32_e32 v193, v192, v195
	v_fma_f32 v198, -v194, v193, v192
	v_fmac_f32_e32 v193, v198, v195
	v_fma_f32 v192, -v194, v193, v192
	v_add_f32_e32 v194, 1.0, v196
	v_div_scale_f32 v196, s[0:1], v194, v194, v134
	v_rcp_f32_e32 v198, v196
	v_div_fmas_f32 v192, v192, v195, v193
	v_div_fixup_f32 v192, v192, v191, v134
	v_fma_f32 v191, -v196, v198, 1.0
	v_fmac_f32_e32 v198, v191, v198
	v_div_scale_f32 v191, vcc, v134, v194, v134
	v_mul_f32_e32 v193, v191, v198
	v_fma_f32 v195, -v196, v193, v191
	v_fmac_f32_e32 v193, v195, v198
	v_sub_f32_e32 v195, 1.0, v192
	v_fma_f32 v191, -v196, v193, v191
	v_div_fmas_f32 v191, v191, v198, v193
	v_log_f32_e32 v195, v195
	v_div_fixup_f32 v193, v191, v194, v134
	v_mul_f32_e32 v191, 0x3f317217, v195
	v_fma_f32 v191, v195, s72, -v191
	v_fmac_f32_e32 v191, 0x3377d1cf, v195
	v_fmac_f32_e32 v191, 0x3f317217, v195
	v_cmp_lt_f32_e64 vcc, |v195|, s73
	s_nop 1
	v_cndmask_b32_e32 v191, v195, v191, vcc
	v_sub_f32_e32 v194, 1.0, v193
	s_nop 0
	v_add_f32_dpp v191, v191, v191 row_shr:1 row_mask:0xf bank_mask:0xf bound_ctrl:1
	s_nop 0
	v_log_f32_e32 v194, v194
	v_add_f32_dpp v191, v191, v191 row_shr:2 row_mask:0xf bank_mask:0xf bound_ctrl:1
	v_mul_f32_e32 v196, 0x3f317217, v194
	v_fma_f32 v196, v194, s72, -v196
	v_fmac_f32_e32 v196, 0x3377d1cf, v194
	v_add_f32_dpp v191, v191, v191 row_shr:4 row_mask:0xf bank_mask:0xf bound_ctrl:1
	v_fmac_f32_e32 v196, 0x3f317217, v194
	v_cmp_lt_f32_e64 s[0:1], |v194|, s73
	v_add_f32_dpp v195, v191, v191 row_shr:8 row_mask:0xf bank_mask:0xf bound_ctrl:1
	ds_bpermute_b32 v191, v162, v195
	v_cndmask_b32_e64 v194, v194, v196, s[0:1]
	v_mul_f32_e32 v199, 0xbfb8aa3b, v195
	v_exp_f32_e32 v199, v199
	v_add_f32_dpp v194, v194, v194 row_shr:1 row_mask:0xf bank_mask:0xf bound_ctrl:1
	v_mul_f32_e32 v206, v192, v199
	s_nop 0
	v_add_f32_dpp v194, v194, v194 row_shr:2 row_mask:0xf bank_mask:0xf bound_ctrl:1
	v_mul_f32_e32 v199, 0x3fb8aa3b, v68
	v_exp_f32_e32 v199, v199
	v_add_f32_dpp v194, v194, v194 row_shr:4 row_mask:0xf bank_mask:0xf bound_ctrl:1
	s_nop 1
	v_add_f32_dpp v194, v194, v194 row_shr:8 row_mask:0xf bank_mask:0xf bound_ctrl:1
	s_waitcnt lgkmcnt(0)
	v_add_f32_e32 v194, v194, v191
	v_mul_f32_e32 v191, 0x3fb8aa3b, v195
	v_exp_f32_e32 v196, v191
	ds_bpermute_b32 v191, v162, v194
	v_mul_f32_e32 v198, 0x3fb8aa3b, v194
	v_exp_f32_e32 v198, v198
	v_mul_f32_e32 v200, 0xbfb8aa3b, v194
	v_exp_f32_e32 v200, v200
	s_waitcnt lgkmcnt(0)
	v_sub_f32_e32 v195, v191, v195
	v_mul_f32_e32 v195, 0x3fb8aa3b, v195
	v_exp_f32_e32 v195, v195
	v_sub_f32_e32 v194, v191, v194
	v_mul_f32_e32 v194, 0x3fb8aa3b, v194
	v_exp_f32_e32 v194, v194
	v_mul_f32_e32 v192, v192, v195
	v_cvt_pk_bf16_f32 v192, v192, v147
	global_store_short v[130:131], v192, off offset:320
	v_mul_f32_e32 v192, 0x3fb8aa3b, v76
	v_exp_f32_e32 v192, v192
	v_mul_f32_e32 v205, v79, v198
	v_mul_f32_e32 v207, v193, v200
	v_mul_f32_e32 v193, v193, v194
	v_add_f32_e32 v192, 1.0, v192
	v_div_scale_f32 v195, s[0:1], v192, v192, v132
	v_rcp_f32_e32 v198, v195
	v_cvt_pk_bf16_f32 v193, v193, v147
	global_store_short v[130:131], v193, off offset:352
	v_mul_f32_e32 v196, v95, v196
	v_fma_f32 v193, -v195, v198, 1.0
	v_fmac_f32_e32 v198, v193, v198
	v_div_scale_f32 v193, vcc, v132, v192, v132
	v_mul_f32_e32 v194, v193, v198
	v_fma_f32 v200, -v195, v194, v193
	v_fmac_f32_e32 v194, v200, v198
	v_fma_f32 v193, -v195, v194, v193
	v_add_f32_e32 v195, 1.0, v199
	v_div_scale_f32 v199, s[0:1], v195, v195, v132
	v_rcp_f32_e32 v200, v199
	v_div_fmas_f32 v193, v193, v198, v194
	v_div_fixup_f32 v193, v193, v192, v132
	v_fma_f32 v192, -v199, v200, 1.0
	v_fmac_f32_e32 v200, v192, v200
	v_div_scale_f32 v192, vcc, v132, v195, v132
	v_mul_f32_e32 v194, v192, v200
	v_fma_f32 v198, -v199, v194, v192
	v_fmac_f32_e32 v194, v198, v200
	v_sub_f32_e32 v198, 1.0, v193
	v_fma_f32 v192, -v199, v194, v192
	v_div_fmas_f32 v192, v192, v200, v194
	v_log_f32_e32 v198, v198
	v_div_fixup_f32 v194, v192, v195, v132
	v_mul_f32_e32 v192, 0x3f317217, v198
	v_fma_f32 v192, v198, s72, -v192
	v_fmac_f32_e32 v192, 0x3377d1cf, v198
	v_fmac_f32_e32 v192, 0x3f317217, v198
	v_cmp_lt_f32_e64 vcc, |v198|, s73
	s_nop 1
	v_cndmask_b32_e32 v192, v198, v192, vcc
	v_sub_f32_e32 v195, 1.0, v194
	s_nop 0
	v_add_f32_dpp v192, v192, v192 row_shr:1 row_mask:0xf bank_mask:0xf bound_ctrl:1
	s_nop 0
	v_log_f32_e32 v195, v195
	v_add_f32_dpp v192, v192, v192 row_shr:2 row_mask:0xf bank_mask:0xf bound_ctrl:1
	v_mul_f32_e32 v199, 0x3f317217, v195
	v_fma_f32 v199, v195, s72, -v199
	v_fmac_f32_e32 v199, 0x3377d1cf, v195
	v_add_f32_dpp v192, v192, v192 row_shr:4 row_mask:0xf bank_mask:0xf bound_ctrl:1
	v_fmac_f32_e32 v199, 0x3f317217, v195
	v_cmp_lt_f32_e64 s[0:1], |v195|, s73
	v_add_f32_dpp v198, v192, v192 row_shr:8 row_mask:0xf bank_mask:0xf bound_ctrl:1
	ds_bpermute_b32 v192, v162, v198
	v_cndmask_b32_e64 v195, v195, v199, s[0:1]
	s_nop 1
	v_add_f32_dpp v195, v195, v195 row_shr:1 row_mask:0xf bank_mask:0xf bound_ctrl:1
	s_nop 1
	v_add_f32_dpp v195, v195, v195 row_shr:2 row_mask:0xf bank_mask:0xf bound_ctrl:1
	s_nop 1
	v_add_f32_dpp v195, v195, v195 row_shr:4 row_mask:0xf bank_mask:0xf bound_ctrl:1
	s_nop 1
	v_add_f32_dpp v195, v195, v195 row_shr:8 row_mask:0xf bank_mask:0xf bound_ctrl:1
	s_waitcnt lgkmcnt(0)
; __device__ __forceinline__ unsigned cvt_pk_bf16(float lo, float hi) { unsigned r; asm volatile("v_cvt_pk_bf16_f32 %0, %1, %2" : "=v"(r) : "v"(lo), "v"(hi)); return r; }
; __device__ __forceinline__ float row_scan16(float v) { v += dpp_shr0<0x111>(v); v += dpp_shr0<0x112>(v); v += dpp_shr0<0x114>(v); v += dpp_shr0<0x118>(v); return v; }
;     __device__ __forceinline__ void operator()(const f32x4 (&acc)[2][2][4][2], const Unit& u, int wr, int wc, int fr, int fq) const {
;     ...
;                     for (int q = 0; q < 4; ++q) { const int j = 4 * n + q;
;                         const float k0 = om[n][q] / (1.0f + __expf(acc[ai][1][2 * mp][n][q])), k1 = om[n][q] / (1.0f + __expf(acc[ai][1][2 * mp + 1][n][q]));
;                         const float p0 = row_scan16(__logf(1.0f - k0)); const float t0 = row_last16(p0, lane);
;                         const float p1 = row_scan16(__logf(1.0f - k1)) + t0; const float bl = row_last16(p1, lane);
;                         const float e0 = __expf(p0), e1 = __expf(p1);
;                         qi[0][j] = acc[ai][0][2 * mp][n][q] * e0; qi[1][j] = acc[ai][0][2 * mp + 1][n][q] * e1;
;                         ki[0][j] = k0 * __expf(-p0); ki[1][j] = k1 * __expf(-p1);
;                         kot[(size_t)j * 32] = (bf16_t)cvt_pk_bf16(k0 * __expf(bl - p0), 0.f); kot[(size_t)j * 32 + 16] = (bf16_t)cvt_pk_bf16(k1 * __expf(bl - p1), 0.f);
;                         dec[j] = __expf(bl); }
; #pragma unroll
;                 for (int mm = 0; mm < 2; ++mm) { const size_t ro = (size_t)(rowa + 16 * mm) * 1024 + colh;
;                     u32x4 w; w.x = cvt_pk_bf16(qi[mm][0], qi[mm][1]); w.y = cvt_pk_bf16(qi[mm][2], qi[mm][3]); w.z = cvt_pk_bf16(qi[mm][4], qi[mm][5]); w.w = cvt_pk_bf16(qi[mm][6], qi[mm][7]);
;                     *(u32x4*)(CQ + ro) = w;
;                     w.x = cvt_pk_bf16(ki[mm][0], ki[mm][1]); w.y = cvt_pk_bf16(ki[mm][2], ki[mm][3]); w.z = cvt_pk_bf16(ki[mm][4], ki[mm][5]); w.w = cvt_pk_bf16(ki[mm][6], ki[mm][7]);
;                     *(u32x4*)(CK + ro) = w; }
;                 if (fr == 15) { float* dp = DEC + (size_t)g * 1024 + colh; *(f32x4*)dp = (f32x4){dec[0], dec[1], dec[2], dec[3]}; *(f32x4*)(dp + 4) = (f32x4){dec[4], dec[5], dec[6], dec[7]}; }
	v_add_f32_e32 v195, v195, v192
	v_mul_f32_e32 v192, 0x3fb8aa3b, v198
	v_exp_f32_e32 v199, v192
	ds_bpermute_b32 v192, v162, v195
	v_mul_f32_e32 v200, 0x3fb8aa3b, v195
	v_mul_f32_e32 v208, 0xbfb8aa3b, v195
	v_mul_f32_e32 v201, v96, v199
	v_mul_f32_e32 v199, 0xbfb8aa3b, v198
	s_waitcnt lgkmcnt(0)
	v_sub_f32_e32 v198, v192, v198
	v_mul_f32_e32 v198, 0x3fb8aa3b, v198
	v_exp_f32_e32 v199, v199
	v_exp_f32_e32 v198, v198
	v_sub_f32_e32 v195, v192, v195
	v_mul_f32_e32 v195, 0x3fb8aa3b, v195
	v_mul_f32_e32 v210, v193, v199
	v_mul_f32_e32 v193, v193, v198
	v_cvt_pk_bf16_f32 v193, v193, v147
	global_store_short v[130:131], v193, off offset:384
	v_mul_f32_e32 v193, 0x3fb8aa3b, v77
	v_exp_f32_e32 v193, v193
	v_exp_f32_e32 v208, v208
	v_exp_f32_e32 v195, v195
	v_exp_f32_e32 v200, v200
	v_add_f32_e32 v193, 1.0, v193
	v_div_scale_f32 v198, s[0:1], v193, v193, v133
	v_rcp_f32_e32 v199, v198
	v_mul_f32_e32 v208, v194, v208
	v_mul_f32_e32 v194, v194, v195
	v_cvt_pk_bf16_f32 v194, v194, v147
	v_mul_f32_e32 v209, v80, v200
	global_store_short v[130:131], v194, off offset:416
	v_fma_f32 v194, -v198, v199, 1.0
	v_mul_f32_e32 v200, 0x3fb8aa3b, v69
	v_fmac_f32_e32 v199, v194, v199
	v_div_scale_f32 v194, vcc, v133, v193, v133
	v_exp_f32_e32 v200, v200
	v_mul_f32_e32 v195, v194, v199
	v_fma_f32 v211, -v198, v195, v194
	v_fmac_f32_e32 v195, v211, v199
	v_fma_f32 v194, -v198, v195, v194
	v_add_f32_e32 v198, 1.0, v200
	v_div_scale_f32 v200, s[0:1], v198, v198, v133
	v_rcp_f32_e32 v211, v200
	v_div_fmas_f32 v194, v194, v199, v195
	v_div_fixup_f32 v194, v194, v193, v133
	v_fma_f32 v193, -v200, v211, 1.0
	v_fmac_f32_e32 v211, v193, v211
	v_div_scale_f32 v193, vcc, v133, v198, v133
	v_mul_f32_e32 v195, v193, v211
	v_fma_f32 v199, -v200, v195, v193
	v_fmac_f32_e32 v195, v199, v211
	v_sub_f32_e32 v199, 1.0, v194
	v_fma_f32 v193, -v200, v195, v193
	v_div_fmas_f32 v193, v193, v211, v195
	v_log_f32_e32 v199, v199
	v_div_fixup_f32 v195, v193, v198, v133
	v_mul_f32_e32 v193, 0x3f317217, v199
	v_fma_f32 v193, v199, s72, -v193
	v_fmac_f32_e32 v193, 0x3377d1cf, v199
	v_fmac_f32_e32 v193, 0x3f317217, v199
	v_cmp_lt_f32_e64 vcc, |v199|, s73
	s_nop 1
	v_cndmask_b32_e32 v193, v199, v193, vcc
	v_sub_f32_e32 v198, 1.0, v195
	s_nop 0
	v_add_f32_dpp v193, v193, v193 row_shr:1 row_mask:0xf bank_mask:0xf bound_ctrl:1
	s_nop 0
	v_log_f32_e32 v198, v198
	v_add_f32_dpp v193, v193, v193 row_shr:2 row_mask:0xf bank_mask:0xf bound_ctrl:1
	v_mul_f32_e32 v200, 0x3f317217, v198
	v_fma_f32 v200, v198, s72, -v200
	v_fmac_f32_e32 v200, 0x3377d1cf, v198
	v_add_f32_dpp v193, v193, v193 row_shr:4 row_mask:0xf bank_mask:0xf bound_ctrl:1
	v_fmac_f32_e32 v200, 0x3f317217, v198
	v_cmp_lt_f32_e64 s[0:1], |v198|, s73
	v_add_f32_dpp v199, v193, v193 row_shr:8 row_mask:0xf bank_mask:0xf bound_ctrl:1
	ds_bpermute_b32 v193, v162, v199
	v_cndmask_b32_e64 v198, v198, v200, s[0:1]
	v_mul_f32_e32 v200, 0x3fb8aa3b, v199
	v_mul_f32_e32 v212, 0xbfb8aa3b, v199
	v_add_f32_dpp v198, v198, v198 row_shr:1 row_mask:0xf bank_mask:0xf bound_ctrl:1
	v_exp_f32_e32 v212, v212
	v_exp_f32_e32 v200, v200
	v_add_f32_dpp v198, v198, v198 row_shr:2 row_mask:0xf bank_mask:0xf bound_ctrl:1
	v_mul_f32_e32 v212, v194, v212
	s_nop 0
	v_add_f32_dpp v198, v198, v198 row_shr:4 row_mask:0xf bank_mask:0xf bound_ctrl:1
	v_mul_f32_e32 v200, v97, v200
	s_nop 0
	v_add_f32_dpp v198, v198, v198 row_shr:8 row_mask:0xf bank_mask:0xf bound_ctrl:1
	s_waitcnt lgkmcnt(0)
	v_add_f32_e32 v198, v198, v193
	ds_bpermute_b32 v193, v162, v198
	v_mul_f32_e32 v211, 0x3fb8aa3b, v198
	v_mul_f32_e32 v213, 0xbfb8aa3b, v198
	v_exp_f32_e32 v213, v213
	v_exp_f32_e32 v211, v211
	s_waitcnt lgkmcnt(0)
	v_sub_f32_e32 v199, v193, v199
	v_mul_f32_e32 v199, 0x3fb8aa3b, v199
	v_exp_f32_e32 v199, v199
	v_sub_f32_e32 v198, v193, v198
	v_mul_f32_e32 v198, 0x3fb8aa3b, v198
	v_exp_f32_e32 v198, v198
	v_mul_f32_e32 v194, v194, v199
	v_cvt_pk_bf16_f32 v194, v194, v147
	global_store_short v[130:131], v194, off offset:448
	v_mul_f32_e32 v194, v195, v198
	v_cvt_pk_bf16_f32 v194, v194, v147
	global_store_short v[130:131], v194, off offset:480
	v_or_b32_e32 v130, s3, v1
	v_ashrrev_i32_e32 v131, 31, v130
	v_mul_f32_e32 v213, v195, v213
	v_lshlrev_b64 v[194:195], 10, v[130:131]
	v_or_b32_e32 v130, 16, v130
	v_lshl_add_u64 v[198:199], v[194:195], 0, v[158:159]
	v_ashrrev_i32_e32 v131, 31, v130
	v_lshlrev_b64 v[198:199], 1, v[198:199]
	v_lshlrev_b64 v[130:131], 10, v[130:131]
	v_cvt_pk_bf16_f32 v194, v172, v177
	v_cvt_pk_bf16_f32 v195, v182, v188
	v_cvt_pk_bf16_f32 v196, v197, v196
	v_cvt_pk_bf16_f32 v197, v201, v200
	v_lshl_add_u64 v[200:201], s[64:65], 0, v[198:199]
	v_lshl_add_u64 v[130:131], v[130:131], 0, v[158:159]
	global_store_dwordx4 v[200:201], v[194:197], off
	v_lshlrev_b64 v[130:131], 1, v[130:131]
	v_mul_f32_e32 v211, v81, v211
	v_cvt_pk_bf16_f32 v194, v173, v178
	v_cvt_pk_bf16_f32 v195, v183, v189
	v_cvt_pk_bf16_f32 v196, v203, v206
	v_cvt_pk_bf16_f32 v197, v210, v212
	v_lshl_add_u64 v[172:173], s[14:15], 0, v[198:199]
	global_store_dwordx4 v[172:173], v[194:197], off
	s_nop 1
	v_lshl_add_u64 v[172:173], s[64:65], 0, v[130:131]
	v_lshl_add_u64 v[130:131], s[14:15], 0, v[130:131]
	v_cvt_pk_bf16_f32 v194, v171, v176
	v_cvt_pk_bf16_f32 v195, v181, v187
	v_cvt_pk_bf16_f32 v196, v202, v205
	v_cvt_pk_bf16_f32 v197, v209, v211
	global_store_dwordx4 v[172:173], v[194:197], off
	s_nop 1
	v_cvt_pk_bf16_f32 v194, v161, v175
	v_cvt_pk_bf16_f32 v195, v180, v185
	v_cvt_pk_bf16_f32 v196, v204, v207
	v_cvt_pk_bf16_f32 v197, v208, v213
	global_store_dwordx4 v[130:131], v[194:197], off
	s_and_saveexec_b64 s[0:1], s[4:5]
	s_cbranch_execz .LBB0_1149
	v_mul_f32_e32 v130, 0x3fb8aa3b, v193
	v_exp_f32_e32 v183, v130
	v_mul_f32_e32 v130, 0x3fb8aa3b, v192
	v_exp_f32_e32 v182, v130
	v_mul_f32_e32 v130, 0x3fb8aa3b, v191
	v_exp_f32_e32 v181, v130
	v_mul_f32_e32 v130, 0x3fb8aa3b, v190
	v_exp_f32_e32 v180, v130
	v_mul_f32_e32 v130, 0x3fb8aa3b, v184
	v_exp_f32_e32 v177, v130
	v_mul_f32_e32 v130, 0x3fb8aa3b, v179
	v_exp_f32_e32 v176, v130
	v_mul_f32_e32 v130, 0x3fb8aa3b, v174
	v_exp_f32_e32 v175, v130
	v_mul_f32_e32 v130, 0x3fb8aa3b, v160
	v_exp_f32_e32 v174, v130
	s_lshl_b64 s[8:9], s[8:9], 2
	s_add_u32 s8, s47, s8
	s_addc_u32 s9, s52, s9
	v_lshl_add_u64 v[130:131], v[158:159], 2, s[8:9]
	global_store_dwordx4 v[130:131], v[174:177], off
	global_store_dwordx4 v[130:131], v[180:183], off offset:16
; __device__ __forceinline__ unsigned cvt_pk_bf16(float lo, float hi) { unsigned r; asm volatile("v_cvt_pk_bf16_f32 %0, %1, %2" : "=v"(r) : "v"(lo), "v"(hi)); return r; }
; __device__ __forceinline__ float row_scan16(float v) { v += dpp_shr0<0x111>(v); v += dpp_shr0<0x112>(v); v += dpp_shr0<0x114>(v); v += dpp_shr0<0x118>(v); return v; }
; __device__ __forceinline__ float row_last16(float v, int lane) { return __builtin_bit_cast(float, __builtin_amdgcn_ds_bpermute((lane | 15) << 2, __builtin_bit_cast(int, v))); }
;     __device__ __forceinline__ void operator()(const f32x4 (&acc)[2][2][4][2], const Unit& u, int wr, int wc, int fr, int fq) const {
;     ...
;                     for (int q = 0; q < 4; ++q) { const int j = 4 * n + q;
;                         const float k0 = om[n][q] / (1.0f + __expf(acc[ai][1][2 * mp][n][q])), k1 = om[n][q] / (1.0f + __expf(acc[ai][1][2 * mp + 1][n][q]));
;                         const float p0 = row_scan16(__logf(1.0f - k0)); const float t0 = row_last16(p0, lane);
;                         const float p1 = row_scan16(__logf(1.0f - k1)) + t0; const float bl = row_last16(p1, lane);
;                         const float e0 = __expf(p0), e1 = __expf(p1);
;                         qi[0][j] = acc[ai][0][2 * mp][n][q] * e0; qi[1][j] = acc[ai][0][2 * mp + 1][n][q] * e1;
;                         ki[0][j] = k0 * __expf(-p0); ki[1][j] = k1 * __expf(-p1);
;                         kot[(size_t)j * 32] = (bf16_t)cvt_pk_bf16(k0 * __expf(bl - p0), 0.f); kot[(size_t)j * 32 + 16] = (bf16_t)cvt_pk_bf16(k1 * __expf(bl - p1), 0.f);
;                         dec[j] = __expf(bl); }
.LBB0_1149:
	s_or_b64 exec, exec, s[0:1]
	v_mul_f32_e32 v130, 0x3fb8aa3b, v50
	v_exp_f32_e32 v130, v130
	s_add_i32 s3, s2, 0x80
	s_ashr_i32 s0, s3, 5
	s_ashr_i32 s1, s0, 31
	v_add_f32_e32 v160, 1.0, v130
	s_lshl_b64 s[8:9], s[0:1], 10
	v_div_scale_f32 v161, s[0:1], v160, v160, v170
	v_rcp_f32_e32 v171, v161
	v_mul_f32_e32 v174, 0x3fb8aa3b, v34
	v_exp_f32_e32 v174, v174
	v_lshl_add_u64 v[130:131], s[8:9], 0, v[158:159]
	v_fma_f32 v172, -v161, v171, 1.0
	v_fmac_f32_e32 v171, v172, v171
	v_div_scale_f32 v172, vcc, v170, v160, v170
	v_mul_f32_e32 v173, v172, v171
	v_fma_f32 v175, -v161, v173, v172
	v_fmac_f32_e32 v173, v175, v171
	v_fma_f32 v161, -v161, v173, v172
	v_add_f32_e32 v172, 1.0, v174
	v_div_scale_f32 v174, s[0:1], v172, v172, v170
	v_rcp_f32_e32 v175, v174
	v_div_fmas_f32 v161, v161, v171, v173
	v_div_fixup_f32 v176, v161, v160, v170
	v_lshlrev_b64 v[130:131], 6, v[130:131]
	v_fma_f32 v160, -v174, v175, 1.0
	v_fmac_f32_e32 v175, v160, v175
	v_div_scale_f32 v160, vcc, v170, v172, v170
	v_mul_f32_e32 v161, v160, v175
	v_fma_f32 v171, -v174, v161, v160
	v_fmac_f32_e32 v161, v171, v175
	v_sub_f32_e32 v171, 1.0, v176
	v_fma_f32 v160, -v174, v161, v160
	v_div_fmas_f32 v160, v160, v175, v161
	v_log_f32_e32 v171, v171
	v_div_fixup_f32 v174, v160, v172, v170
	v_lshl_add_u64 v[130:131], v[148:149], 0, v[130:131]
	v_mul_f32_e32 v160, 0x3f317217, v171
	v_fma_f32 v160, v171, s72, -v160
	v_fmac_f32_e32 v160, 0x3377d1cf, v171
	v_fmac_f32_e32 v160, 0x3f317217, v171
	v_cmp_lt_f32_e64 vcc, |v171|, s73
	v_mul_f32_e32 v179, 0x3fb8aa3b, v35
	v_exp_f32_e32 v179, v179
	v_cndmask_b32_e32 v160, v171, v160, vcc
	v_sub_f32_e32 v161, 1.0, v174
	s_nop 0
	v_add_f32_dpp v160, v160, v160 row_shr:1 row_mask:0xf bank_mask:0xf bound_ctrl:1
	v_mul_f32_e32 v184, 0x3fb8aa3b, v36
	v_log_f32_e32 v161, v161
	v_add_f32_dpp v160, v160, v160 row_shr:2 row_mask:0xf bank_mask:0xf bound_ctrl:1
	v_exp_f32_e32 v184, v184
	v_mul_f32_e32 v190, 0x3fb8aa3b, v37
	v_mul_f32_e32 v172, 0x3f317217, v161
	v_fma_f32 v172, v161, s72, -v172
	v_fmac_f32_e32 v172, 0x3377d1cf, v161
	v_add_f32_dpp v160, v160, v160 row_shr:4 row_mask:0xf bank_mask:0xf bound_ctrl:1
	v_fmac_f32_e32 v172, 0x3f317217, v161
	v_cmp_lt_f32_e64 s[0:1], |v161|, s73
	v_add_f32_dpp v171, v160, v160 row_shr:8 row_mask:0xf bank_mask:0xf bound_ctrl:1
	ds_bpermute_b32 v160, v162, v171
	v_cndmask_b32_e64 v161, v161, v172, s[0:1]
	v_exp_f32_e32 v190, v190
	v_mul_f32_e32 v195, 0x3fb8aa3b, v26
	v_add_f32_dpp v161, v161, v161 row_shr:1 row_mask:0xf bank_mask:0xf bound_ctrl:1
	v_exp_f32_e32 v195, v195
	s_nop 0
	v_add_f32_dpp v161, v161, v161 row_shr:2 row_mask:0xf bank_mask:0xf bound_ctrl:1
	s_nop 1
	v_add_f32_dpp v161, v161, v161 row_shr:4 row_mask:0xf bank_mask:0xf bound_ctrl:1
	s_nop 1
	v_add_f32_dpp v161, v161, v161 row_shr:8 row_mask:0xf bank_mask:0xf bound_ctrl:1
	s_waitcnt lgkmcnt(0)
	v_add_f32_e32 v175, v161, v160
	v_mul_f32_e32 v160, 0x3fb8aa3b, v171
	v_exp_f32_e32 v161, v160
	ds_bpermute_b32 v160, v162, v175
	v_mul_f32_e32 v172, 0x3fb8aa3b, v175
	v_exp_f32_e32 v173, v172
	v_mul_f32_e32 v172, v62, v161
	v_mul_f32_e32 v161, 0xbfb8aa3b, v171
	s_waitcnt lgkmcnt(0)
	v_sub_f32_e32 v171, v160, v171
	v_mul_f32_e32 v171, 0x3fb8aa3b, v171
	v_exp_f32_e32 v161, v161
	v_exp_f32_e32 v178, v171
	v_mul_f32_e32 v171, v54, v173
	v_mul_f32_e32 v177, 0xbfb8aa3b, v175
	v_mul_f32_e32 v173, v176, v161
	v_mul_f32_e32 v176, v176, v178
	v_cvt_pk_bf16_f32 v176, v176, v147
	global_store_short v[130:131], v176, off
	v_mul_f32_e32 v176, 0x3fb8aa3b, v51
	v_exp_f32_e32 v176, v176
	v_exp_f32_e32 v177, v177
	v_sub_f32_e32 v175, v160, v175
	v_mul_f32_e32 v175, 0x3fb8aa3b, v175
	v_exp_f32_e32 v175, v175
	v_add_f32_e32 v176, 1.0, v176
	v_mul_f32_e32 v161, v174, v177
	v_div_scale_f32 v177, s[0:1], v176, v176, v146
	v_rcp_f32_e32 v178, v177
	v_mul_f32_e32 v174, v174, v175
	v_cvt_pk_bf16_f32 v174, v174, v147
	global_store_short v[130:131], v174, off offset:32
	v_fma_f32 v174, -v177, v178, 1.0
	v_fmac_f32_e32 v178, v174, v178
	v_div_scale_f32 v174, vcc, v146, v176, v146
	v_mul_f32_e32 v175, v174, v178
	v_fma_f32 v180, -v177, v175, v174
	v_fmac_f32_e32 v175, v180, v178
	v_fma_f32 v174, -v177, v175, v174
	v_add_f32_e32 v177, 1.0, v179
	v_div_scale_f32 v179, s[0:1], v177, v177, v146
	v_rcp_f32_e32 v180, v179
	v_div_fmas_f32 v174, v174, v178, v175
	v_div_fixup_f32 v181, v174, v176, v146
	v_fma_f32 v174, -v179, v180, 1.0
	v_fmac_f32_e32 v180, v174, v180
	v_div_scale_f32 v174, vcc, v146, v177, v146
	v_mul_f32_e32 v175, v174, v180
	v_fma_f32 v176, -v179, v175, v174
	v_fmac_f32_e32 v175, v176, v180
	v_sub_f32_e32 v176, 1.0, v181
	v_fma_f32 v174, -v179, v175, v174
	v_div_fmas_f32 v174, v174, v180, v175
	v_log_f32_e32 v176, v176
	v_div_fixup_f32 v179, v174, v177, v146
	v_mul_f32_e32 v174, 0x3f317217, v176
	v_fma_f32 v174, v176, s72, -v174
	v_fmac_f32_e32 v174, 0x3377d1cf, v176
	v_fmac_f32_e32 v174, 0x3f317217, v176
	v_cmp_lt_f32_e64 vcc, |v176|, s73
	s_nop 1
	v_cndmask_b32_e32 v174, v176, v174, vcc
	v_sub_f32_e32 v175, 1.0, v179
	s_nop 0
	v_add_f32_dpp v174, v174, v174 row_shr:1 row_mask:0xf bank_mask:0xf bound_ctrl:1
	s_nop 0
	v_log_f32_e32 v175, v175
	v_add_f32_dpp v174, v174, v174 row_shr:2 row_mask:0xf bank_mask:0xf bound_ctrl:1
	v_mul_f32_e32 v177, 0x3f317217, v175
	v_fma_f32 v177, v175, s72, -v177
	v_fmac_f32_e32 v177, 0x3377d1cf, v175
	v_add_f32_dpp v174, v174, v174 row_shr:4 row_mask:0xf bank_mask:0xf bound_ctrl:1
	v_fmac_f32_e32 v177, 0x3f317217, v175
	v_cmp_lt_f32_e64 s[0:1], |v175|, s73
	v_add_f32_dpp v176, v174, v174 row_shr:8 row_mask:0xf bank_mask:0xf bound_ctrl:1
	ds_bpermute_b32 v174, v162, v176
	v_cndmask_b32_e64 v175, v175, v177, s[0:1]
	s_nop 1
	v_add_f32_dpp v175, v175, v175 row_shr:1 row_mask:0xf bank_mask:0xf bound_ctrl:1
	s_nop 1
	v_add_f32_dpp v175, v175, v175 row_shr:2 row_mask:0xf bank_mask:0xf bound_ctrl:1
	s_nop 1
	v_add_f32_dpp v175, v175, v175 row_shr:4 row_mask:0xf bank_mask:0xf bound_ctrl:1
	s_nop 1
	v_add_f32_dpp v175, v175, v175 row_shr:8 row_mask:0xf bank_mask:0xf bound_ctrl:1
	s_waitcnt lgkmcnt(0)
; __device__ __forceinline__ unsigned cvt_pk_bf16(float lo, float hi) { unsigned r; asm volatile("v_cvt_pk_bf16_f32 %0, %1, %2" : "=v"(r) : "v"(lo), "v"(hi)); return r; }
; __device__ __forceinline__ float row_scan16(float v) { v += dpp_shr0<0x111>(v); v += dpp_shr0<0x112>(v); v += dpp_shr0<0x114>(v); v += dpp_shr0<0x118>(v); return v; }
; __device__ __forceinline__ float row_last16(float v, int lane) { return __builtin_bit_cast(float, __builtin_amdgcn_ds_bpermute((lane | 15) << 2, __builtin_bit_cast(int, v))); }
;     __device__ __forceinline__ void operator()(const f32x4 (&acc)[2][2][4][2], const Unit& u, int wr, int wc, int fr, int fq) const {
;     ...
;                     for (int q = 0; q < 4; ++q) { const int j = 4 * n + q;
;                         const float k0 = om[n][q] / (1.0f + __expf(acc[ai][1][2 * mp][n][q])), k1 = om[n][q] / (1.0f + __expf(acc[ai][1][2 * mp + 1][n][q]));
;                         const float p0 = row_scan16(__logf(1.0f - k0)); const float t0 = row_last16(p0, lane);
;                         const float p1 = row_scan16(__logf(1.0f - k1)) + t0; const float bl = row_last16(p1, lane);
;                         const float e0 = __expf(p0), e1 = __expf(p1);
;                         qi[0][j] = acc[ai][0][2 * mp][n][q] * e0; qi[1][j] = acc[ai][0][2 * mp + 1][n][q] * e1;
;                         ki[0][j] = k0 * __expf(-p0); ki[1][j] = k1 * __expf(-p1);
;                         kot[(size_t)j * 32] = (bf16_t)cvt_pk_bf16(k0 * __expf(bl - p0), 0.f); kot[(size_t)j * 32 + 16] = (bf16_t)cvt_pk_bf16(k1 * __expf(bl - p1), 0.f);
;                         dec[j] = __expf(bl); }
	v_add_f32_e32 v180, v175, v174
	v_mul_f32_e32 v174, 0x3fb8aa3b, v176
	v_exp_f32_e32 v175, v174
	ds_bpermute_b32 v174, v162, v180
	v_mul_f32_e32 v177, 0x3fb8aa3b, v180
	v_exp_f32_e32 v178, v177
	v_mul_f32_e32 v177, v63, v175
	v_mul_f32_e32 v175, 0xbfb8aa3b, v176
	s_waitcnt lgkmcnt(0)
	v_sub_f32_e32 v176, v174, v176
	v_mul_f32_e32 v176, 0x3fb8aa3b, v176
	v_exp_f32_e32 v175, v175
	v_exp_f32_e32 v183, v176
	v_mul_f32_e32 v176, v55, v178
	v_mul_f32_e32 v182, 0xbfb8aa3b, v180
	v_mul_f32_e32 v178, v181, v175
	v_mul_f32_e32 v181, v181, v183
	v_cvt_pk_bf16_f32 v181, v181, v147
	global_store_short v[130:131], v181, off offset:64
	v_mul_f32_e32 v181, 0x3fb8aa3b, v52
	v_exp_f32_e32 v181, v181
	v_exp_f32_e32 v182, v182
	v_sub_f32_e32 v180, v174, v180
	v_mul_f32_e32 v180, 0x3fb8aa3b, v180
	v_exp_f32_e32 v180, v180
	v_add_f32_e32 v181, 1.0, v181
	v_mul_f32_e32 v175, v179, v182
	v_div_scale_f32 v182, s[0:1], v181, v181, v136
	v_rcp_f32_e32 v183, v182
	v_mul_f32_e32 v179, v179, v180
	v_cvt_pk_bf16_f32 v179, v179, v147
	global_store_short v[130:131], v179, off offset:96
	v_fma_f32 v179, -v182, v183, 1.0
	v_fmac_f32_e32 v183, v179, v183
	v_div_scale_f32 v179, vcc, v136, v181, v136
	v_mul_f32_e32 v180, v179, v183
	v_fma_f32 v185, -v182, v180, v179
	v_fmac_f32_e32 v180, v185, v183
	v_fma_f32 v179, -v182, v180, v179
	v_add_f32_e32 v182, 1.0, v184
	v_div_scale_f32 v184, s[0:1], v182, v182, v136
	v_rcp_f32_e32 v185, v184
	v_div_fmas_f32 v179, v179, v183, v180
	v_div_fixup_f32 v187, v179, v181, v136
	v_fma_f32 v179, -v184, v185, 1.0
	v_fmac_f32_e32 v185, v179, v185
	v_div_scale_f32 v179, vcc, v136, v182, v136
	v_mul_f32_e32 v180, v179, v185
	v_fma_f32 v181, -v184, v180, v179
	v_fmac_f32_e32 v180, v181, v185
	v_sub_f32_e32 v181, 1.0, v187
	v_fma_f32 v179, -v184, v180, v179
	v_div_fmas_f32 v179, v179, v185, v180
	v_log_f32_e32 v181, v181
	v_div_fixup_f32 v184, v179, v182, v136
	v_mul_f32_e32 v179, 0x3f317217, v181
	v_fma_f32 v179, v181, s72, -v179
	v_fmac_f32_e32 v179, 0x3377d1cf, v181
	v_fmac_f32_e32 v179, 0x3f317217, v181
	v_cmp_lt_f32_e64 vcc, |v181|, s73
	s_nop 1
	v_cndmask_b32_e32 v179, v181, v179, vcc
	v_sub_f32_e32 v180, 1.0, v184
	s_nop 0
	v_add_f32_dpp v179, v179, v179 row_shr:1 row_mask:0xf bank_mask:0xf bound_ctrl:1
	s_nop 0
	v_log_f32_e32 v180, v180
	v_add_f32_dpp v179, v179, v179 row_shr:2 row_mask:0xf bank_mask:0xf bound_ctrl:1
	v_mul_f32_e32 v182, 0x3f317217, v180
	v_fma_f32 v182, v180, s72, -v182
	v_fmac_f32_e32 v182, 0x3377d1cf, v180
	v_add_f32_dpp v179, v179, v179 row_shr:4 row_mask:0xf bank_mask:0xf bound_ctrl:1
	v_fmac_f32_e32 v182, 0x3f317217, v180
	v_cmp_lt_f32_e64 s[0:1], |v180|, s73
	v_add_f32_dpp v181, v179, v179 row_shr:8 row_mask:0xf bank_mask:0xf bound_ctrl:1
	ds_bpermute_b32 v179, v162, v181
	v_cndmask_b32_e64 v180, v180, v182, s[0:1]
	s_nop 1
	v_add_f32_dpp v180, v180, v180 row_shr:1 row_mask:0xf bank_mask:0xf bound_ctrl:1
	s_nop 1
	v_add_f32_dpp v180, v180, v180 row_shr:2 row_mask:0xf bank_mask:0xf bound_ctrl:1
	s_nop 1
	v_add_f32_dpp v180, v180, v180 row_shr:4 row_mask:0xf bank_mask:0xf bound_ctrl:1
	s_nop 1
	v_add_f32_dpp v180, v180, v180 row_shr:8 row_mask:0xf bank_mask:0xf bound_ctrl:1
	s_waitcnt lgkmcnt(0)
	v_add_f32_e32 v185, v180, v179
	v_mul_f32_e32 v179, 0x3fb8aa3b, v181
	v_exp_f32_e32 v180, v179
	ds_bpermute_b32 v179, v162, v185
	v_mul_f32_e32 v182, 0x3fb8aa3b, v185
	v_exp_f32_e32 v183, v182
	v_mul_f32_e32 v182, v64, v180
	v_mul_f32_e32 v180, 0xbfb8aa3b, v181
	s_waitcnt lgkmcnt(0)
	v_sub_f32_e32 v181, v179, v181
	v_mul_f32_e32 v181, 0x3fb8aa3b, v181
	v_exp_f32_e32 v180, v180
	v_exp_f32_e32 v189, v181
	v_mul_f32_e32 v181, v56, v183
	v_mul_f32_e32 v188, 0xbfb8aa3b, v185
	v_mul_f32_e32 v183, v187, v180
	v_mul_f32_e32 v187, v187, v189
	v_cvt_pk_bf16_f32 v187, v187, v147
	global_store_short v[130:131], v187, off offset:128
	v_mul_f32_e32 v187, 0x3fb8aa3b, v53
	v_exp_f32_e32 v187, v187
	v_exp_f32_e32 v188, v188
	v_sub_f32_e32 v185, v179, v185
	v_mul_f32_e32 v185, 0x3fb8aa3b, v185
	v_exp_f32_e32 v185, v185
	v_add_f32_e32 v187, 1.0, v187
	v_mul_f32_e32 v180, v184, v188
	v_div_scale_f32 v188, s[0:1], v187, v187, v137
	v_rcp_f32_e32 v189, v188
	v_mul_f32_e32 v184, v184, v185
	v_cvt_pk_bf16_f32 v184, v184, v147
	global_store_short v[130:131], v184, off offset:160
	v_fma_f32 v184, -v188, v189, 1.0
	v_fmac_f32_e32 v189, v184, v189
	v_div_scale_f32 v184, vcc, v137, v187, v137
	v_mul_f32_e32 v185, v184, v189
	v_fma_f32 v191, -v188, v185, v184
	v_fmac_f32_e32 v185, v191, v189
	v_fma_f32 v184, -v188, v185, v184
	v_add_f32_e32 v188, 1.0, v190
	v_div_scale_f32 v190, s[0:1], v188, v188, v137
	v_rcp_f32_e32 v191, v190
	v_div_fmas_f32 v184, v184, v189, v185
	v_div_fixup_f32 v192, v184, v187, v137
	v_fma_f32 v184, -v190, v191, 1.0
	v_fmac_f32_e32 v191, v184, v191
	v_div_scale_f32 v184, vcc, v137, v188, v137
	v_mul_f32_e32 v185, v184, v191
	v_fma_f32 v187, -v190, v185, v184
	v_fmac_f32_e32 v185, v187, v191
	v_sub_f32_e32 v187, 1.0, v192
	v_fma_f32 v184, -v190, v185, v184
	v_div_fmas_f32 v184, v184, v191, v185
	v_log_f32_e32 v187, v187
	v_div_fixup_f32 v190, v184, v188, v137
	v_mul_f32_e32 v184, 0x3f317217, v187
	v_fma_f32 v184, v187, s72, -v184
	v_fmac_f32_e32 v184, 0x3377d1cf, v187
	v_fmac_f32_e32 v184, 0x3f317217, v187
	v_cmp_lt_f32_e64 vcc, |v187|, s73
	s_nop 1
	v_cndmask_b32_e32 v184, v187, v184, vcc
	v_sub_f32_e32 v185, 1.0, v190
	s_nop 0
	v_add_f32_dpp v184, v184, v184 row_shr:1 row_mask:0xf bank_mask:0xf bound_ctrl:1
	s_nop 0
	v_log_f32_e32 v185, v185
	v_add_f32_dpp v184, v184, v184 row_shr:2 row_mask:0xf bank_mask:0xf bound_ctrl:1
	v_mul_f32_e32 v188, 0x3f317217, v185
	v_fma_f32 v188, v185, s72, -v188
	v_fmac_f32_e32 v188, 0x3377d1cf, v185
	v_add_f32_dpp v184, v184, v184 row_shr:4 row_mask:0xf bank_mask:0xf bound_ctrl:1
	v_fmac_f32_e32 v188, 0x3f317217, v185
	v_cmp_lt_f32_e64 s[0:1], |v185|, s73
	v_add_f32_dpp v187, v184, v184 row_shr:8 row_mask:0xf bank_mask:0xf bound_ctrl:1
	ds_bpermute_b32 v184, v162, v187
	v_cndmask_b32_e64 v185, v185, v188, s[0:1]
	s_nop 1
	v_add_f32_dpp v185, v185, v185 row_shr:1 row_mask:0xf bank_mask:0xf bound_ctrl:1
	s_nop 1
	v_add_f32_dpp v185, v185, v185 row_shr:2 row_mask:0xf bank_mask:0xf bound_ctrl:1
	s_nop 1
	v_add_f32_dpp v185, v185, v185 row_shr:4 row_mask:0xf bank_mask:0xf bound_ctrl:1
	s_nop 1
	v_add_f32_dpp v185, v185, v185 row_shr:8 row_mask:0xf bank_mask:0xf bound_ctrl:1
	s_waitcnt lgkmcnt(0)
; __device__ __forceinline__ unsigned cvt_pk_bf16(float lo, float hi) { unsigned r; asm volatile("v_cvt_pk_bf16_f32 %0, %1, %2" : "=v"(r) : "v"(lo), "v"(hi)); return r; }
; __device__ __forceinline__ float row_scan16(float v) { v += dpp_shr0<0x111>(v); v += dpp_shr0<0x112>(v); v += dpp_shr0<0x114>(v); v += dpp_shr0<0x118>(v); return v; }
; __device__ __forceinline__ float row_last16(float v, int lane) { return __builtin_bit_cast(float, __builtin_amdgcn_ds_bpermute((lane | 15) << 2, __builtin_bit_cast(int, v))); }
;     __device__ __forceinline__ void operator()(const f32x4 (&acc)[2][2][4][2], const Unit& u, int wr, int wc, int fr, int fq) const {
;     ...
;                     for (int q = 0; q < 4; ++q) { const int j = 4 * n + q;
;                         const float k0 = om[n][q] / (1.0f + __expf(acc[ai][1][2 * mp][n][q])), k1 = om[n][q] / (1.0f + __expf(acc[ai][1][2 * mp + 1][n][q]));
;                         const float p0 = row_scan16(__logf(1.0f - k0)); const float t0 = row_last16(p0, lane);
;                         const float p1 = row_scan16(__logf(1.0f - k1)) + t0; const float bl = row_last16(p1, lane);
;                         const float e0 = __expf(p0), e1 = __expf(p1);
;                         qi[0][j] = acc[ai][0][2 * mp][n][q] * e0; qi[1][j] = acc[ai][0][2 * mp + 1][n][q] * e1;
;                         ki[0][j] = k0 * __expf(-p0); ki[1][j] = k1 * __expf(-p1);
;                         kot[(size_t)j * 32] = (bf16_t)cvt_pk_bf16(k0 * __expf(bl - p0), 0.f); kot[(size_t)j * 32 + 16] = (bf16_t)cvt_pk_bf16(k1 * __expf(bl - p1), 0.f);
;                         dec[j] = __expf(bl); }
	v_add_f32_e32 v191, v185, v184
	v_mul_f32_e32 v184, 0x3fb8aa3b, v187
	v_exp_f32_e32 v185, v184
	ds_bpermute_b32 v184, v162, v191
	v_mul_f32_e32 v188, 0x3fb8aa3b, v191
	v_exp_f32_e32 v189, v188
	v_mul_f32_e32 v188, v65, v185
	v_mul_f32_e32 v185, 0xbfb8aa3b, v187
	s_waitcnt lgkmcnt(0)
	v_sub_f32_e32 v187, v184, v187
	v_mul_f32_e32 v187, 0x3fb8aa3b, v187
	v_exp_f32_e32 v185, v185
	v_exp_f32_e32 v194, v187
	v_mul_f32_e32 v187, v57, v189
	v_mul_f32_e32 v193, 0xbfb8aa3b, v191
	v_mul_f32_e32 v189, v192, v185
	v_mul_f32_e32 v192, v192, v194
	v_cvt_pk_bf16_f32 v192, v192, v147
	global_store_short v[130:131], v192, off offset:192
	v_mul_f32_e32 v192, 0x3fb8aa3b, v42
	v_exp_f32_e32 v192, v192
	v_exp_f32_e32 v193, v193
	v_sub_f32_e32 v191, v184, v191
	v_mul_f32_e32 v191, 0x3fb8aa3b, v191
	v_exp_f32_e32 v191, v191
	v_add_f32_e32 v192, 1.0, v192
	v_mul_f32_e32 v185, v190, v193
	v_div_scale_f32 v193, s[0:1], v192, v192, v135
	v_rcp_f32_e32 v194, v193
	v_mul_f32_e32 v190, v190, v191
	v_cvt_pk_bf16_f32 v190, v190, v147
	global_store_short v[130:131], v190, off offset:224
	v_fma_f32 v190, -v193, v194, 1.0
	v_fmac_f32_e32 v194, v190, v194
	v_div_scale_f32 v190, vcc, v135, v192, v135
	v_mul_f32_e32 v191, v190, v194
	v_fma_f32 v196, -v193, v191, v190
	v_fmac_f32_e32 v191, v196, v194
	v_fma_f32 v190, -v193, v191, v190
	v_add_f32_e32 v193, 1.0, v195
	v_div_scale_f32 v195, s[0:1], v193, v193, v135
	v_rcp_f32_e32 v196, v195
	v_div_fmas_f32 v190, v190, v194, v191
	v_div_fixup_f32 v191, v190, v192, v135
	v_fma_f32 v190, -v195, v196, 1.0
	v_fmac_f32_e32 v196, v190, v196
	v_div_scale_f32 v190, vcc, v135, v193, v135
	v_mul_f32_e32 v192, v190, v196
	v_fma_f32 v194, -v195, v192, v190
	v_fmac_f32_e32 v192, v194, v196
	v_sub_f32_e32 v194, 1.0, v191
	v_fma_f32 v190, -v195, v192, v190
	v_div_fmas_f32 v190, v190, v196, v192
	v_log_f32_e32 v194, v194
	v_div_fixup_f32 v192, v190, v193, v135
	v_mul_f32_e32 v190, 0x3f317217, v194
	v_fma_f32 v190, v194, s72, -v190
	v_fmac_f32_e32 v190, 0x3377d1cf, v194
	v_fmac_f32_e32 v190, 0x3f317217, v194
	v_cmp_lt_f32_e64 vcc, |v194|, s73
	s_nop 1
	v_cndmask_b32_e32 v190, v194, v190, vcc
	v_sub_f32_e32 v193, 1.0, v192
	s_nop 0
	v_add_f32_dpp v190, v190, v190 row_shr:1 row_mask:0xf bank_mask:0xf bound_ctrl:1
	s_nop 0
	v_log_f32_e32 v193, v193
	v_add_f32_dpp v190, v190, v190 row_shr:2 row_mask:0xf bank_mask:0xf bound_ctrl:1
	v_mul_f32_e32 v195, 0x3f317217, v193
	v_fma_f32 v195, v193, s72, -v195
	v_fmac_f32_e32 v195, 0x3377d1cf, v193
	v_add_f32_dpp v190, v190, v190 row_shr:4 row_mask:0xf bank_mask:0xf bound_ctrl:1
	v_fmac_f32_e32 v195, 0x3f317217, v193
	v_cmp_lt_f32_e64 s[0:1], |v193|, s73
	v_add_f32_dpp v194, v190, v190 row_shr:8 row_mask:0xf bank_mask:0xf bound_ctrl:1
	ds_bpermute_b32 v190, v162, v194
	v_cndmask_b32_e64 v193, v193, v195, s[0:1]
	s_nop 1
	v_add_f32_dpp v193, v193, v193 row_shr:1 row_mask:0xf bank_mask:0xf bound_ctrl:1
	s_nop 1
	v_add_f32_dpp v193, v193, v193 row_shr:2 row_mask:0xf bank_mask:0xf bound_ctrl:1
	s_nop 1
	v_add_f32_dpp v193, v193, v193 row_shr:4 row_mask:0xf bank_mask:0xf bound_ctrl:1
	s_nop 1
	v_add_f32_dpp v193, v193, v193 row_shr:8 row_mask:0xf bank_mask:0xf bound_ctrl:1
	s_waitcnt lgkmcnt(0)
	v_add_f32_e32 v193, v193, v190
	v_mul_f32_e32 v190, 0x3fb8aa3b, v194
	v_exp_f32_e32 v195, v190
	ds_bpermute_b32 v190, v162, v193
	v_mul_f32_e32 v196, 0x3fb8aa3b, v193
	v_mul_f32_e32 v198, 0xbfb8aa3b, v193
	v_mul_f32_e32 v197, v58, v195
	v_mul_f32_e32 v195, 0xbfb8aa3b, v194
	s_waitcnt lgkmcnt(0)
	v_sub_f32_e32 v194, v190, v194
	v_mul_f32_e32 v194, 0x3fb8aa3b, v194
	v_exp_f32_e32 v195, v195
	v_exp_f32_e32 v194, v194
	v_sub_f32_e32 v193, v190, v193
	v_mul_f32_e32 v193, 0x3fb8aa3b, v193
	v_mul_f32_e32 v203, v191, v195
	v_mul_f32_e32 v191, v191, v194
	v_cvt_pk_bf16_f32 v191, v191, v147
	global_store_short v[130:131], v191, off offset:256
	v_mul_f32_e32 v191, 0x3fb8aa3b, v43
	v_exp_f32_e32 v191, v191
	v_exp_f32_e32 v198, v198
	v_exp_f32_e32 v193, v193
	v_exp_f32_e32 v196, v196
	v_add_f32_e32 v191, 1.0, v191
	v_div_scale_f32 v194, s[0:1], v191, v191, v134
	v_rcp_f32_e32 v195, v194
	v_mul_f32_e32 v204, v192, v198
	v_mul_f32_e32 v192, v192, v193
	v_cvt_pk_bf16_f32 v192, v192, v147
	v_mul_f32_e32 v202, v46, v196
	global_store_short v[130:131], v192, off offset:288
	v_fma_f32 v192, -v194, v195, 1.0
	v_mul_f32_e32 v196, 0x3fb8aa3b, v27
	v_fmac_f32_e32 v195, v192, v195
	v_div_scale_f32 v192, vcc, v134, v191, v134
	v_exp_f32_e32 v196, v196
	v_mul_f32_e32 v193, v192, v195
	v_fma_f32 v198, -v194, v193, v192
	v_fmac_f32_e32 v193, v198, v195
	v_fma_f32 v192, -v194, v193, v192
	v_add_f32_e32 v194, 1.0, v196
	v_div_scale_f32 v196, s[0:1], v194, v194, v134
	v_rcp_f32_e32 v198, v196
	v_div_fmas_f32 v192, v192, v195, v193
	v_div_fixup_f32 v192, v192, v191, v134
	v_fma_f32 v191, -v196, v198, 1.0
	v_fmac_f32_e32 v198, v191, v198
	v_div_scale_f32 v191, vcc, v134, v194, v134
	v_mul_f32_e32 v193, v191, v198
	v_fma_f32 v195, -v196, v193, v191
	v_fmac_f32_e32 v193, v195, v198
	v_sub_f32_e32 v195, 1.0, v192
	v_fma_f32 v191, -v196, v193, v191
	v_div_fmas_f32 v191, v191, v198, v193
	v_log_f32_e32 v195, v195
	v_div_fixup_f32 v193, v191, v194, v134
	v_mul_f32_e32 v191, 0x3f317217, v195
	v_fma_f32 v191, v195, s72, -v191
	v_fmac_f32_e32 v191, 0x3377d1cf, v195
	v_fmac_f32_e32 v191, 0x3f317217, v195
	v_cmp_lt_f32_e64 vcc, |v195|, s73
	s_nop 1
	v_cndmask_b32_e32 v191, v195, v191, vcc
	v_sub_f32_e32 v194, 1.0, v193
	s_nop 0
	v_add_f32_dpp v191, v191, v191 row_shr:1 row_mask:0xf bank_mask:0xf bound_ctrl:1
	s_nop 0
	v_log_f32_e32 v194, v194
	v_add_f32_dpp v191, v191, v191 row_shr:2 row_mask:0xf bank_mask:0xf bound_ctrl:1
	v_mul_f32_e32 v196, 0x3f317217, v194
	v_fma_f32 v196, v194, s72, -v196
	v_fmac_f32_e32 v196, 0x3377d1cf, v194
	v_add_f32_dpp v191, v191, v191 row_shr:4 row_mask:0xf bank_mask:0xf bound_ctrl:1
	v_fmac_f32_e32 v196, 0x3f317217, v194
	v_cmp_lt_f32_e64 s[0:1], |v194|, s73
	v_add_f32_dpp v195, v191, v191 row_shr:8 row_mask:0xf bank_mask:0xf bound_ctrl:1
	ds_bpermute_b32 v191, v162, v195
	v_cndmask_b32_e64 v194, v194, v196, s[0:1]
	v_mul_f32_e32 v199, 0xbfb8aa3b, v195
	v_exp_f32_e32 v199, v199
	v_add_f32_dpp v194, v194, v194 row_shr:1 row_mask:0xf bank_mask:0xf bound_ctrl:1
	v_mul_f32_e32 v206, v192, v199
	s_nop 0
	v_add_f32_dpp v194, v194, v194 row_shr:2 row_mask:0xf bank_mask:0xf bound_ctrl:1
	v_mul_f32_e32 v199, 0x3fb8aa3b, v28
	v_exp_f32_e32 v199, v199
	v_add_f32_dpp v194, v194, v194 row_shr:4 row_mask:0xf bank_mask:0xf bound_ctrl:1
	s_nop 1
	v_add_f32_dpp v194, v194, v194 row_shr:8 row_mask:0xf bank_mask:0xf bound_ctrl:1
	s_waitcnt lgkmcnt(0)
; __device__ __forceinline__ unsigned cvt_pk_bf16(float lo, float hi) { unsigned r; asm volatile("v_cvt_pk_bf16_f32 %0, %1, %2" : "=v"(r) : "v"(lo), "v"(hi)); return r; }
; __device__ __forceinline__ float row_scan16(float v) { v += dpp_shr0<0x111>(v); v += dpp_shr0<0x112>(v); v += dpp_shr0<0x114>(v); v += dpp_shr0<0x118>(v); return v; }
; __device__ __forceinline__ float row_last16(float v, int lane) { return __builtin_bit_cast(float, __builtin_amdgcn_ds_bpermute((lane | 15) << 2, __builtin_bit_cast(int, v))); }
;     __device__ __forceinline__ void operator()(const f32x4 (&acc)[2][2][4][2], const Unit& u, int wr, int wc, int fr, int fq) const {
;     ...
;                     for (int q = 0; q < 4; ++q) { const int j = 4 * n + q;
;                         const float k0 = om[n][q] / (1.0f + __expf(acc[ai][1][2 * mp][n][q])), k1 = om[n][q] / (1.0f + __expf(acc[ai][1][2 * mp + 1][n][q]));
;                         const float p0 = row_scan16(__logf(1.0f - k0)); const float t0 = row_last16(p0, lane);
;                         const float p1 = row_scan16(__logf(1.0f - k1)) + t0; const float bl = row_last16(p1, lane);
;                         const float e0 = __expf(p0), e1 = __expf(p1);
;                         qi[0][j] = acc[ai][0][2 * mp][n][q] * e0; qi[1][j] = acc[ai][0][2 * mp + 1][n][q] * e1;
;                         ki[0][j] = k0 * __expf(-p0); ki[1][j] = k1 * __expf(-p1);
;                         kot[(size_t)j * 32] = (bf16_t)cvt_pk_bf16(k0 * __expf(bl - p0), 0.f); kot[(size_t)j * 32 + 16] = (bf16_t)cvt_pk_bf16(k1 * __expf(bl - p1), 0.f);
;                         dec[j] = __expf(bl); }
	v_add_f32_e32 v194, v194, v191
	v_mul_f32_e32 v191, 0x3fb8aa3b, v195
	v_exp_f32_e32 v196, v191
	ds_bpermute_b32 v191, v162, v194
	v_mul_f32_e32 v198, 0x3fb8aa3b, v194
	v_exp_f32_e32 v198, v198
	v_mul_f32_e32 v200, 0xbfb8aa3b, v194
	v_exp_f32_e32 v200, v200
	s_waitcnt lgkmcnt(0)
	v_sub_f32_e32 v195, v191, v195
	v_mul_f32_e32 v195, 0x3fb8aa3b, v195
	v_exp_f32_e32 v195, v195
	v_sub_f32_e32 v194, v191, v194
	v_mul_f32_e32 v194, 0x3fb8aa3b, v194
	v_exp_f32_e32 v194, v194
	v_mul_f32_e32 v192, v192, v195
	v_cvt_pk_bf16_f32 v192, v192, v147
	global_store_short v[130:131], v192, off offset:320
	v_mul_f32_e32 v192, 0x3fb8aa3b, v44
	v_exp_f32_e32 v192, v192
	v_mul_f32_e32 v205, v47, v198
	v_mul_f32_e32 v207, v193, v200
	v_mul_f32_e32 v193, v193, v194
	v_add_f32_e32 v192, 1.0, v192
	v_div_scale_f32 v195, s[0:1], v192, v192, v132
	v_rcp_f32_e32 v198, v195
	v_cvt_pk_bf16_f32 v193, v193, v147
	global_store_short v[130:131], v193, off offset:352
	v_mul_f32_e32 v196, v59, v196
	v_fma_f32 v193, -v195, v198, 1.0
	v_fmac_f32_e32 v198, v193, v198
	v_div_scale_f32 v193, vcc, v132, v192, v132
	v_mul_f32_e32 v194, v193, v198
	v_fma_f32 v200, -v195, v194, v193
	v_fmac_f32_e32 v194, v200, v198
	v_fma_f32 v193, -v195, v194, v193
	v_add_f32_e32 v195, 1.0, v199
	v_div_scale_f32 v199, s[0:1], v195, v195, v132
	v_rcp_f32_e32 v200, v199
	v_div_fmas_f32 v193, v193, v198, v194
	v_div_fixup_f32 v193, v193, v192, v132
	v_fma_f32 v192, -v199, v200, 1.0
	v_fmac_f32_e32 v200, v192, v200
	v_div_scale_f32 v192, vcc, v132, v195, v132
	v_mul_f32_e32 v194, v192, v200
	v_fma_f32 v198, -v199, v194, v192
	v_fmac_f32_e32 v194, v198, v200
	v_sub_f32_e32 v198, 1.0, v193
	v_fma_f32 v192, -v199, v194, v192
	v_div_fmas_f32 v192, v192, v200, v194
	v_log_f32_e32 v198, v198
	v_div_fixup_f32 v194, v192, v195, v132
	v_mul_f32_e32 v192, 0x3f317217, v198
	v_fma_f32 v192, v198, s72, -v192
	v_fmac_f32_e32 v192, 0x3377d1cf, v198
	v_fmac_f32_e32 v192, 0x3f317217, v198
	v_cmp_lt_f32_e64 vcc, |v198|, s73
	s_nop 1
	v_cndmask_b32_e32 v192, v198, v192, vcc
	v_sub_f32_e32 v195, 1.0, v194
	s_nop 0
	v_add_f32_dpp v192, v192, v192 row_shr:1 row_mask:0xf bank_mask:0xf bound_ctrl:1
	s_nop 0
	v_log_f32_e32 v195, v195
	v_add_f32_dpp v192, v192, v192 row_shr:2 row_mask:0xf bank_mask:0xf bound_ctrl:1
	v_mul_f32_e32 v199, 0x3f317217, v195
	v_fma_f32 v199, v195, s72, -v199
	v_fmac_f32_e32 v199, 0x3377d1cf, v195
	v_add_f32_dpp v192, v192, v192 row_shr:4 row_mask:0xf bank_mask:0xf bound_ctrl:1
	v_fmac_f32_e32 v199, 0x3f317217, v195
	v_cmp_lt_f32_e64 s[0:1], |v195|, s73
	v_add_f32_dpp v198, v192, v192 row_shr:8 row_mask:0xf bank_mask:0xf bound_ctrl:1
	ds_bpermute_b32 v192, v162, v198
	v_cndmask_b32_e64 v195, v195, v199, s[0:1]
	s_nop 1
	v_add_f32_dpp v195, v195, v195 row_shr:1 row_mask:0xf bank_mask:0xf bound_ctrl:1
	s_nop 1
	v_add_f32_dpp v195, v195, v195 row_shr:2 row_mask:0xf bank_mask:0xf bound_ctrl:1
	s_nop 1
	v_add_f32_dpp v195, v195, v195 row_shr:4 row_mask:0xf bank_mask:0xf bound_ctrl:1
	s_nop 1
	v_add_f32_dpp v195, v195, v195 row_shr:8 row_mask:0xf bank_mask:0xf bound_ctrl:1
	s_waitcnt lgkmcnt(0)
	v_add_f32_e32 v195, v195, v192
	v_mul_f32_e32 v192, 0x3fb8aa3b, v198
	v_exp_f32_e32 v199, v192
	ds_bpermute_b32 v192, v162, v195
	v_mul_f32_e32 v200, 0x3fb8aa3b, v195
	v_mul_f32_e32 v208, 0xbfb8aa3b, v195
	v_mul_f32_e32 v201, v60, v199
	v_mul_f32_e32 v199, 0xbfb8aa3b, v198
	s_waitcnt lgkmcnt(0)
	v_sub_f32_e32 v198, v192, v198
	v_mul_f32_e32 v198, 0x3fb8aa3b, v198
	v_exp_f32_e32 v199, v199
	v_exp_f32_e32 v198, v198
	v_sub_f32_e32 v195, v192, v195
	v_mul_f32_e32 v195, 0x3fb8aa3b, v195
	v_mul_f32_e32 v210, v193, v199
	v_mul_f32_e32 v193, v193, v198
	v_cvt_pk_bf16_f32 v193, v193, v147
	global_store_short v[130:131], v193, off offset:384
	v_mul_f32_e32 v193, 0x3fb8aa3b, v45
	v_exp_f32_e32 v193, v193
	v_exp_f32_e32 v208, v208
	v_exp_f32_e32 v195, v195
	v_exp_f32_e32 v200, v200
	v_add_f32_e32 v193, 1.0, v193
	v_div_scale_f32 v198, s[0:1], v193, v193, v133
	v_rcp_f32_e32 v199, v198
	v_mul_f32_e32 v208, v194, v208
	v_mul_f32_e32 v194, v194, v195
	v_cvt_pk_bf16_f32 v194, v194, v147
	v_mul_f32_e32 v209, v48, v200
	global_store_short v[130:131], v194, off offset:416
	v_fma_f32 v194, -v198, v199, 1.0
	v_mul_f32_e32 v200, 0x3fb8aa3b, v29
	v_fmac_f32_e32 v199, v194, v199
	v_div_scale_f32 v194, vcc, v133, v193, v133
	v_exp_f32_e32 v200, v200
	v_mul_f32_e32 v195, v194, v199
	v_fma_f32 v211, -v198, v195, v194
	v_fmac_f32_e32 v195, v211, v199
	v_fma_f32 v194, -v198, v195, v194
	v_add_f32_e32 v198, 1.0, v200
	v_div_scale_f32 v200, s[0:1], v198, v198, v133
	v_rcp_f32_e32 v211, v200
	v_div_fmas_f32 v194, v194, v199, v195
	v_div_fixup_f32 v194, v194, v193, v133
	v_fma_f32 v193, -v200, v211, 1.0
	v_fmac_f32_e32 v211, v193, v211
	v_div_scale_f32 v193, vcc, v133, v198, v133
	v_mul_f32_e32 v195, v193, v211
	v_fma_f32 v199, -v200, v195, v193
	v_fmac_f32_e32 v195, v199, v211
	v_sub_f32_e32 v199, 1.0, v194
	v_fma_f32 v193, -v200, v195, v193
	v_div_fmas_f32 v193, v193, v211, v195
	v_log_f32_e32 v199, v199
	v_div_fixup_f32 v195, v193, v198, v133
	v_mul_f32_e32 v193, 0x3f317217, v199
	v_fma_f32 v193, v199, s72, -v193
	v_fmac_f32_e32 v193, 0x3377d1cf, v199
	v_fmac_f32_e32 v193, 0x3f317217, v199
	v_cmp_lt_f32_e64 vcc, |v199|, s73
	s_nop 1
	v_cndmask_b32_e32 v193, v199, v193, vcc
	v_sub_f32_e32 v198, 1.0, v195
	s_nop 0
	v_add_f32_dpp v193, v193, v193 row_shr:1 row_mask:0xf bank_mask:0xf bound_ctrl:1
	s_nop 0
	v_log_f32_e32 v198, v198
	v_add_f32_dpp v193, v193, v193 row_shr:2 row_mask:0xf bank_mask:0xf bound_ctrl:1
	v_mul_f32_e32 v200, 0x3f317217, v198
	v_fma_f32 v200, v198, s72, -v200
	v_fmac_f32_e32 v200, 0x3377d1cf, v198
	v_add_f32_dpp v193, v193, v193 row_shr:4 row_mask:0xf bank_mask:0xf bound_ctrl:1
	v_fmac_f32_e32 v200, 0x3f317217, v198
	v_cmp_lt_f32_e64 s[0:1], |v198|, s73
	v_add_f32_dpp v199, v193, v193 row_shr:8 row_mask:0xf bank_mask:0xf bound_ctrl:1
	ds_bpermute_b32 v193, v162, v199
	v_cndmask_b32_e64 v198, v198, v200, s[0:1]
	v_mul_f32_e32 v200, 0x3fb8aa3b, v199
	v_mul_f32_e32 v212, 0xbfb8aa3b, v199
	v_add_f32_dpp v198, v198, v198 row_shr:1 row_mask:0xf bank_mask:0xf bound_ctrl:1
	v_exp_f32_e32 v212, v212
	v_exp_f32_e32 v200, v200
	v_add_f32_dpp v198, v198, v198 row_shr:2 row_mask:0xf bank_mask:0xf bound_ctrl:1
	v_mul_f32_e32 v212, v194, v212
	s_nop 0
	v_add_f32_dpp v198, v198, v198 row_shr:4 row_mask:0xf bank_mask:0xf bound_ctrl:1
	v_mul_f32_e32 v200, v61, v200
	s_nop 0
	v_add_f32_dpp v198, v198, v198 row_shr:8 row_mask:0xf bank_mask:0xf bound_ctrl:1
	s_waitcnt lgkmcnt(0)
; __device__ __forceinline__ unsigned cvt_pk_bf16(float lo, float hi) { unsigned r; asm volatile("v_cvt_pk_bf16_f32 %0, %1, %2" : "=v"(r) : "v"(lo), "v"(hi)); return r; }
; __device__ __forceinline__ float row_scan16(float v) { v += dpp_shr0<0x111>(v); v += dpp_shr0<0x112>(v); v += dpp_shr0<0x114>(v); v += dpp_shr0<0x118>(v); return v; }
;     __device__ __forceinline__ void operator()(const f32x4 (&acc)[2][2][4][2], const Unit& u, int wr, int wc, int fr, int fq) const {
;     ...
;                     for (int q = 0; q < 4; ++q) { const int j = 4 * n + q;
;                         const float k0 = om[n][q] / (1.0f + __expf(acc[ai][1][2 * mp][n][q])), k1 = om[n][q] / (1.0f + __expf(acc[ai][1][2 * mp + 1][n][q]));
;                         const float p0 = row_scan16(__logf(1.0f - k0)); const float t0 = row_last16(p0, lane);
;                         const float p1 = row_scan16(__logf(1.0f - k1)) + t0; const float bl = row_last16(p1, lane);
;                         const float e0 = __expf(p0), e1 = __expf(p1);
;                         qi[0][j] = acc[ai][0][2 * mp][n][q] * e0; qi[1][j] = acc[ai][0][2 * mp + 1][n][q] * e1;
;                         ki[0][j] = k0 * __expf(-p0); ki[1][j] = k1 * __expf(-p1);
;                         kot[(size_t)j * 32] = (bf16_t)cvt_pk_bf16(k0 * __expf(bl - p0), 0.f); kot[(size_t)j * 32 + 16] = (bf16_t)cvt_pk_bf16(k1 * __expf(bl - p1), 0.f);
;                         dec[j] = __expf(bl); }
; #pragma unroll
;                 for (int mm = 0; mm < 2; ++mm) { const size_t ro = (size_t)(rowa + 16 * mm) * 1024 + colh;
;                     u32x4 w; w.x = cvt_pk_bf16(qi[mm][0], qi[mm][1]); w.y = cvt_pk_bf16(qi[mm][2], qi[mm][3]); w.z = cvt_pk_bf16(qi[mm][4], qi[mm][5]); w.w = cvt_pk_bf16(qi[mm][6], qi[mm][7]);
;                     *(u32x4*)(CQ + ro) = w;
;                     w.x = cvt_pk_bf16(ki[mm][0], ki[mm][1]); w.y = cvt_pk_bf16(ki[mm][2], ki[mm][3]); w.z = cvt_pk_bf16(ki[mm][4], ki[mm][5]); w.w = cvt_pk_bf16(ki[mm][6], ki[mm][7]);
;                     *(u32x4*)(CK + ro) = w; }
;                 if (fr == 15) { float* dp = DEC + (size_t)g * 1024 + colh; *(f32x4*)dp = (f32x4){dec[0], dec[1], dec[2], dec[3]}; *(f32x4*)(dp + 4) = (f32x4){dec[4], dec[5], dec[6], dec[7]}; }
	v_add_f32_e32 v198, v198, v193
	ds_bpermute_b32 v193, v162, v198
	v_mul_f32_e32 v211, 0x3fb8aa3b, v198
	v_mul_f32_e32 v213, 0xbfb8aa3b, v198
	v_exp_f32_e32 v213, v213
	v_exp_f32_e32 v211, v211
	s_waitcnt lgkmcnt(0)
	v_sub_f32_e32 v199, v193, v199
	v_mul_f32_e32 v199, 0x3fb8aa3b, v199
	v_exp_f32_e32 v199, v199
	v_sub_f32_e32 v198, v193, v198
	v_mul_f32_e32 v198, 0x3fb8aa3b, v198
	v_exp_f32_e32 v198, v198
	v_mul_f32_e32 v194, v194, v199
	v_cvt_pk_bf16_f32 v194, v194, v147
	global_store_short v[130:131], v194, off offset:448
	v_mul_f32_e32 v194, v195, v198
	v_cvt_pk_bf16_f32 v194, v194, v147
	global_store_short v[130:131], v194, off offset:480
	v_or_b32_e32 v130, s3, v1
	v_ashrrev_i32_e32 v131, 31, v130
	v_mul_f32_e32 v213, v195, v213
	v_lshlrev_b64 v[194:195], 10, v[130:131]
	v_or_b32_e32 v130, 16, v130
	v_lshl_add_u64 v[198:199], v[194:195], 0, v[158:159]
	v_ashrrev_i32_e32 v131, 31, v130
	v_lshlrev_b64 v[198:199], 1, v[198:199]
	v_lshlrev_b64 v[130:131], 10, v[130:131]
	v_cvt_pk_bf16_f32 v194, v172, v177
	v_cvt_pk_bf16_f32 v195, v182, v188
	v_cvt_pk_bf16_f32 v196, v197, v196
	v_cvt_pk_bf16_f32 v197, v201, v200
	v_lshl_add_u64 v[200:201], s[64:65], 0, v[198:199]
	v_lshl_add_u64 v[130:131], v[130:131], 0, v[158:159]
	global_store_dwordx4 v[200:201], v[194:197], off
	v_lshlrev_b64 v[130:131], 1, v[130:131]
	v_mul_f32_e32 v211, v49, v211
	v_cvt_pk_bf16_f32 v194, v173, v178
	v_cvt_pk_bf16_f32 v195, v183, v189
	v_cvt_pk_bf16_f32 v196, v203, v206
	v_cvt_pk_bf16_f32 v197, v210, v212
	v_lshl_add_u64 v[172:173], s[14:15], 0, v[198:199]
	global_store_dwordx4 v[172:173], v[194:197], off
	s_nop 1
	v_lshl_add_u64 v[172:173], s[64:65], 0, v[130:131]
	v_lshl_add_u64 v[130:131], s[14:15], 0, v[130:131]
	v_cvt_pk_bf16_f32 v194, v171, v176
	v_cvt_pk_bf16_f32 v195, v181, v187
	v_cvt_pk_bf16_f32 v196, v202, v205
	v_cvt_pk_bf16_f32 v197, v209, v211
	global_store_dwordx4 v[172:173], v[194:197], off
	s_nop 1
	v_cvt_pk_bf16_f32 v194, v161, v175
	v_cvt_pk_bf16_f32 v195, v180, v185
	v_cvt_pk_bf16_f32 v196, v204, v207
	v_cvt_pk_bf16_f32 v197, v208, v213
	global_store_dwordx4 v[130:131], v[194:197], off
	s_and_saveexec_b64 s[0:1], s[4:5]
	s_cbranch_execz .LBB0_1151
	v_mul_f32_e32 v130, 0x3fb8aa3b, v193
	v_exp_f32_e32 v183, v130
	v_mul_f32_e32 v130, 0x3fb8aa3b, v192
	v_exp_f32_e32 v182, v130
	v_mul_f32_e32 v130, 0x3fb8aa3b, v191
	v_exp_f32_e32 v181, v130
	v_mul_f32_e32 v130, 0x3fb8aa3b, v190
	v_exp_f32_e32 v180, v130
	v_mul_f32_e32 v130, 0x3fb8aa3b, v184
	v_exp_f32_e32 v177, v130
	v_mul_f32_e32 v130, 0x3fb8aa3b, v179
	v_exp_f32_e32 v176, v130
	v_mul_f32_e32 v130, 0x3fb8aa3b, v174
	v_exp_f32_e32 v175, v130
	v_mul_f32_e32 v130, 0x3fb8aa3b, v160
	v_exp_f32_e32 v174, v130
	s_lshl_b64 s[8:9], s[8:9], 2
	s_add_u32 s8, s47, s8
	s_addc_u32 s9, s52, s9
	v_lshl_add_u64 v[130:131], v[158:159], 2, s[8:9]
	global_store_dwordx4 v[130:131], v[174:177], off
	global_store_dwordx4 v[130:131], v[180:183], off offset:16
.LBB0_1151:
	s_or_b64 exec, exec, s[0:1]
	v_mul_f32_e32 v130, 0x3fb8aa3b, v18
	v_exp_f32_e32 v130, v130
	s_addk_i32 s2, 0xa0
	s_ashr_i32 s0, s2, 5
	s_ashr_i32 s1, s0, 31
	v_add_f32_e32 v160, 1.0, v130
	s_lshl_b64 s[8:9], s[0:1], 10
	v_div_scale_f32 v161, s[0:1], v160, v160, v170
	v_rcp_f32_e32 v171, v161
	v_mul_f32_e32 v174, 0x3fb8aa3b, v6
	v_exp_f32_e32 v174, v174
	v_lshl_add_u64 v[130:131], s[8:9], 0, v[158:159]
	v_fma_f32 v172, -v161, v171, 1.0
	v_fmac_f32_e32 v171, v172, v171
	v_div_scale_f32 v172, vcc, v170, v160, v170
	v_mul_f32_e32 v173, v172, v171
	v_fma_f32 v175, -v161, v173, v172
	v_fmac_f32_e32 v173, v175, v171
	v_fma_f32 v161, -v161, v173, v172
	v_add_f32_e32 v172, 1.0, v174
	v_div_scale_f32 v174, s[0:1], v172, v172, v170
	v_rcp_f32_e32 v175, v174
	v_div_fmas_f32 v161, v161, v171, v173
	v_div_fixup_f32 v173, v161, v160, v170
	v_lshlrev_b64 v[130:131], 6, v[130:131]
	v_fma_f32 v160, -v174, v175, 1.0
	v_fmac_f32_e32 v175, v160, v175
	v_div_scale_f32 v160, vcc, v170, v172, v170
	v_mul_f32_e32 v161, v160, v175
	v_fma_f32 v171, -v174, v161, v160
	v_fmac_f32_e32 v161, v171, v175
	v_sub_f32_e32 v171, 1.0, v173
	v_fma_f32 v160, -v174, v161, v160
	v_div_fmas_f32 v160, v160, v175, v161
	v_log_f32_e32 v171, v171
	v_div_fixup_f32 v174, v160, v172, v170
	v_lshl_add_u64 v[130:131], v[148:149], 0, v[130:131]
	v_mul_f32_e32 v160, 0x3f317217, v171
	v_fma_f32 v160, v171, s72, -v160
	v_fmac_f32_e32 v160, 0x3377d1cf, v171
	v_fmac_f32_e32 v160, 0x3f317217, v171
	v_cmp_lt_f32_e64 vcc, |v171|, s73
	v_mul_f32_e32 v178, 0x3fb8aa3b, v7
	v_exp_f32_e32 v178, v178
	v_cndmask_b32_e32 v160, v171, v160, vcc
	v_sub_f32_e32 v161, 1.0, v174
	s_nop 0
	v_add_f32_dpp v160, v160, v160 row_shr:1 row_mask:0xf bank_mask:0xf bound_ctrl:1
	v_mul_f32_e32 v182, 0x3fb8aa3b, v8
	v_log_f32_e32 v161, v161
	v_add_f32_dpp v160, v160, v160 row_shr:2 row_mask:0xf bank_mask:0xf bound_ctrl:1
	v_exp_f32_e32 v182, v182
	v_mul_f32_e32 v187, 0x3fb8aa3b, v9
	v_mul_f32_e32 v171, 0x3f317217, v161
	v_fma_f32 v171, v161, s72, -v171
	v_fmac_f32_e32 v171, 0x3377d1cf, v161
	v_add_f32_dpp v160, v160, v160 row_shr:4 row_mask:0xf bank_mask:0xf bound_ctrl:1
	v_fmac_f32_e32 v171, 0x3f317217, v161
	v_cmp_lt_f32_e64 s[0:1], |v161|, s73
	v_add_f32_dpp v170, v160, v160 row_shr:8 row_mask:0xf bank_mask:0xf bound_ctrl:1
	ds_bpermute_b32 v160, v162, v170
	v_cndmask_b32_e64 v161, v161, v171, s[0:1]
	v_exp_f32_e32 v187, v187
	v_mul_f32_e32 v191, 0x3fb8aa3b, v2
	v_add_f32_dpp v161, v161, v161 row_shr:1 row_mask:0xf bank_mask:0xf bound_ctrl:1
	v_exp_f32_e32 v191, v191
	s_nop 0
	v_add_f32_dpp v161, v161, v161 row_shr:2 row_mask:0xf bank_mask:0xf bound_ctrl:1
	s_nop 1
	v_add_f32_dpp v161, v161, v161 row_shr:4 row_mask:0xf bank_mask:0xf bound_ctrl:1
	s_nop 1
	v_add_f32_dpp v161, v161, v161 row_shr:8 row_mask:0xf bank_mask:0xf bound_ctrl:1
	s_waitcnt lgkmcnt(0)
; __device__ __forceinline__ unsigned cvt_pk_bf16(float lo, float hi) { unsigned r; asm volatile("v_cvt_pk_bf16_f32 %0, %1, %2" : "=v"(r) : "v"(lo), "v"(hi)); return r; }
; __device__ __forceinline__ float row_scan16(float v) { v += dpp_shr0<0x111>(v); v += dpp_shr0<0x112>(v); v += dpp_shr0<0x114>(v); v += dpp_shr0<0x118>(v); return v; }
; __device__ __forceinline__ float row_last16(float v, int lane) { return __builtin_bit_cast(float, __builtin_amdgcn_ds_bpermute((lane | 15) << 2, __builtin_bit_cast(int, v))); }
;     __device__ __forceinline__ void operator()(const f32x4 (&acc)[2][2][4][2], const Unit& u, int wr, int wc, int fr, int fq) const {
;     ...
;                     for (int q = 0; q < 4; ++q) { const int j = 4 * n + q;
;                         const float k0 = om[n][q] / (1.0f + __expf(acc[ai][1][2 * mp][n][q])), k1 = om[n][q] / (1.0f + __expf(acc[ai][1][2 * mp + 1][n][q]));
;                         const float p0 = row_scan16(__logf(1.0f - k0)); const float t0 = row_last16(p0, lane);
;                         const float p1 = row_scan16(__logf(1.0f - k1)) + t0; const float bl = row_last16(p1, lane);
;                         const float e0 = __expf(p0), e1 = __expf(p1);
;                         qi[0][j] = acc[ai][0][2 * mp][n][q] * e0; qi[1][j] = acc[ai][0][2 * mp + 1][n][q] * e1;
;                         ki[0][j] = k0 * __expf(-p0); ki[1][j] = k1 * __expf(-p1);
;                         kot[(size_t)j * 32] = (bf16_t)cvt_pk_bf16(k0 * __expf(bl - p0), 0.f); kot[(size_t)j * 32 + 16] = (bf16_t)cvt_pk_bf16(k1 * __expf(bl - p1), 0.f);
;                         dec[j] = __expf(bl); }
	v_add_f32_e32 v175, v161, v160
	v_mul_f32_e32 v160, 0x3fb8aa3b, v170
	v_exp_f32_e32 v161, v160
	ds_bpermute_b32 v160, v162, v175
	v_mul_f32_e32 v171, 0x3fb8aa3b, v175
	v_exp_f32_e32 v172, v171
	v_mul_f32_e32 v171, v38, v161
	v_mul_f32_e32 v161, 0xbfb8aa3b, v170
	s_waitcnt lgkmcnt(0)
	v_sub_f32_e32 v170, v160, v170
	v_mul_f32_e32 v170, 0x3fb8aa3b, v170
	v_exp_f32_e32 v161, v161
	v_exp_f32_e32 v177, v170
	v_mul_f32_e32 v170, v22, v172
	v_mul_f32_e32 v176, 0xbfb8aa3b, v175
	v_mul_f32_e32 v172, v173, v161
	v_mul_f32_e32 v173, v173, v177
	v_cvt_pk_bf16_f32 v173, v173, v147
	global_store_short v[130:131], v173, off
	v_mul_f32_e32 v173, 0x3fb8aa3b, v19
	v_exp_f32_e32 v173, v173
	v_exp_f32_e32 v176, v176
	v_sub_f32_e32 v175, v160, v175
	v_mul_f32_e32 v175, 0x3fb8aa3b, v175
	v_exp_f32_e32 v175, v175
	v_add_f32_e32 v173, 1.0, v173
	v_mul_f32_e32 v161, v174, v176
	v_div_scale_f32 v176, s[0:1], v173, v173, v146
	v_rcp_f32_e32 v177, v176
	v_mul_f32_e32 v174, v174, v175
	v_cvt_pk_bf16_f32 v174, v174, v147
	global_store_short v[130:131], v174, off offset:32
	v_fma_f32 v174, -v176, v177, 1.0
	v_fmac_f32_e32 v177, v174, v177
	v_div_scale_f32 v174, vcc, v146, v173, v146
	v_mul_f32_e32 v175, v174, v177
	v_fma_f32 v179, -v176, v175, v174
	v_fmac_f32_e32 v175, v179, v177
	v_fma_f32 v174, -v176, v175, v174
	v_add_f32_e32 v176, 1.0, v178
	v_div_scale_f32 v178, s[0:1], v176, v176, v146
	v_rcp_f32_e32 v179, v178
	v_div_fmas_f32 v174, v174, v177, v175
	v_div_fixup_f32 v177, v174, v173, v146
	v_fma_f32 v173, -v178, v179, 1.0
	v_fmac_f32_e32 v179, v173, v179
	v_div_scale_f32 v173, vcc, v146, v176, v146
	v_mul_f32_e32 v174, v173, v179
	v_fma_f32 v175, -v178, v174, v173
	v_fmac_f32_e32 v174, v175, v179
	v_sub_f32_e32 v175, 1.0, v177
	v_fma_f32 v173, -v178, v174, v173
	v_div_fmas_f32 v173, v173, v179, v174
	v_log_f32_e32 v175, v175
	v_div_fixup_f32 v178, v173, v176, v146
	v_mul_f32_e32 v146, 0x3f317217, v175
	v_fma_f32 v146, v175, s72, -v146
	v_fmac_f32_e32 v146, 0x3377d1cf, v175
	v_fmac_f32_e32 v146, 0x3f317217, v175
	v_cmp_lt_f32_e64 vcc, |v175|, s73
	s_nop 1
	v_cndmask_b32_e32 v146, v175, v146, vcc
	v_sub_f32_e32 v173, 1.0, v178
	s_nop 0
	v_add_f32_dpp v146, v146, v146 row_shr:1 row_mask:0xf bank_mask:0xf bound_ctrl:1
	s_nop 0
	v_log_f32_e32 v173, v173
	v_add_f32_dpp v146, v146, v146 row_shr:2 row_mask:0xf bank_mask:0xf bound_ctrl:1
	v_mul_f32_e32 v175, 0x3f317217, v173
	v_fma_f32 v175, v173, s72, -v175
	v_fmac_f32_e32 v175, 0x3377d1cf, v173
	v_add_f32_dpp v146, v146, v146 row_shr:4 row_mask:0xf bank_mask:0xf bound_ctrl:1
	v_fmac_f32_e32 v175, 0x3f317217, v173
	v_cmp_lt_f32_e64 s[0:1], |v173|, s73
	v_add_f32_dpp v174, v146, v146 row_shr:8 row_mask:0xf bank_mask:0xf bound_ctrl:1
	ds_bpermute_b32 v146, v162, v174
	v_cndmask_b32_e64 v173, v173, v175, s[0:1]
	s_nop 1
	v_add_f32_dpp v173, v173, v173 row_shr:1 row_mask:0xf bank_mask:0xf bound_ctrl:1
	s_nop 1
	v_add_f32_dpp v173, v173, v173 row_shr:2 row_mask:0xf bank_mask:0xf bound_ctrl:1
	s_nop 1
	v_add_f32_dpp v173, v173, v173 row_shr:4 row_mask:0xf bank_mask:0xf bound_ctrl:1
	s_nop 1
	v_add_f32_dpp v173, v173, v173 row_shr:8 row_mask:0xf bank_mask:0xf bound_ctrl:1
	s_waitcnt lgkmcnt(0)
	v_add_f32_e32 v179, v173, v146
	v_mul_f32_e32 v146, 0x3fb8aa3b, v174
	v_exp_f32_e32 v173, v146
	ds_bpermute_b32 v146, v162, v179
	v_mul_f32_e32 v175, 0x3fb8aa3b, v179
	v_exp_f32_e32 v176, v175
	v_mul_f32_e32 v175, v39, v173
	v_mul_f32_e32 v173, 0xbfb8aa3b, v174
	s_waitcnt lgkmcnt(0)
	v_sub_f32_e32 v174, v146, v174
	v_mul_f32_e32 v174, 0x3fb8aa3b, v174
	v_exp_f32_e32 v173, v173
	v_exp_f32_e32 v181, v174
	v_mul_f32_e32 v174, v23, v176
	v_mul_f32_e32 v180, 0xbfb8aa3b, v179
	v_mul_f32_e32 v176, v177, v173
	v_mul_f32_e32 v177, v177, v181
	v_cvt_pk_bf16_f32 v177, v177, v147
	global_store_short v[130:131], v177, off offset:64
	v_mul_f32_e32 v177, 0x3fb8aa3b, v20
	v_exp_f32_e32 v177, v177
	v_exp_f32_e32 v180, v180
	v_sub_f32_e32 v179, v146, v179
	v_mul_f32_e32 v179, 0x3fb8aa3b, v179
	v_exp_f32_e32 v179, v179
	v_add_f32_e32 v177, 1.0, v177
	v_mul_f32_e32 v173, v178, v180
	v_div_scale_f32 v180, s[0:1], v177, v177, v136
	v_rcp_f32_e32 v181, v180
	v_mul_f32_e32 v178, v178, v179
	v_cvt_pk_bf16_f32 v178, v178, v147
	global_store_short v[130:131], v178, off offset:96
	v_fma_f32 v178, -v180, v181, 1.0
	v_fmac_f32_e32 v181, v178, v181
	v_div_scale_f32 v178, vcc, v136, v177, v136
	v_mul_f32_e32 v179, v178, v181
	v_fma_f32 v183, -v180, v179, v178
	v_fmac_f32_e32 v179, v183, v181
	v_fma_f32 v178, -v180, v179, v178
	v_add_f32_e32 v180, 1.0, v182
	v_div_scale_f32 v182, s[0:1], v180, v180, v136
	v_rcp_f32_e32 v183, v182
	v_div_fmas_f32 v178, v178, v181, v179
	v_div_fixup_f32 v181, v178, v177, v136
	v_fma_f32 v177, -v182, v183, 1.0
	v_fmac_f32_e32 v183, v177, v183
	v_div_scale_f32 v177, vcc, v136, v180, v136
	v_mul_f32_e32 v178, v177, v183
	v_fma_f32 v179, -v182, v178, v177
	v_fmac_f32_e32 v178, v179, v183
	v_sub_f32_e32 v179, 1.0, v181
	v_fma_f32 v177, -v182, v178, v177
	v_div_fmas_f32 v177, v177, v183, v178
	v_log_f32_e32 v179, v179
	v_div_fixup_f32 v182, v177, v180, v136
	v_mul_f32_e32 v136, 0x3f317217, v179
	v_fma_f32 v136, v179, s72, -v136
	v_fmac_f32_e32 v136, 0x3377d1cf, v179
	v_fmac_f32_e32 v136, 0x3f317217, v179
	v_cmp_lt_f32_e64 vcc, |v179|, s73
	s_nop 1
	v_cndmask_b32_e32 v136, v179, v136, vcc
	v_sub_f32_e32 v177, 1.0, v182
	s_nop 0
	v_add_f32_dpp v136, v136, v136 row_shr:1 row_mask:0xf bank_mask:0xf bound_ctrl:1
	s_nop 0
	v_log_f32_e32 v177, v177
	v_add_f32_dpp v136, v136, v136 row_shr:2 row_mask:0xf bank_mask:0xf bound_ctrl:1
	v_mul_f32_e32 v179, 0x3f317217, v177
	v_fma_f32 v179, v177, s72, -v179
	v_fmac_f32_e32 v179, 0x3377d1cf, v177
	v_add_f32_dpp v136, v136, v136 row_shr:4 row_mask:0xf bank_mask:0xf bound_ctrl:1
	v_fmac_f32_e32 v179, 0x3f317217, v177
	v_cmp_lt_f32_e64 s[0:1], |v177|, s73
	v_add_f32_dpp v178, v136, v136 row_shr:8 row_mask:0xf bank_mask:0xf bound_ctrl:1
	ds_bpermute_b32 v136, v162, v178
	v_cndmask_b32_e64 v177, v177, v179, s[0:1]
	s_nop 1
	v_add_f32_dpp v177, v177, v177 row_shr:1 row_mask:0xf bank_mask:0xf bound_ctrl:1
	s_nop 1
	v_add_f32_dpp v177, v177, v177 row_shr:2 row_mask:0xf bank_mask:0xf bound_ctrl:1
	s_nop 1
	v_add_f32_dpp v177, v177, v177 row_shr:4 row_mask:0xf bank_mask:0xf bound_ctrl:1
	s_nop 1
	v_add_f32_dpp v177, v177, v177 row_shr:8 row_mask:0xf bank_mask:0xf bound_ctrl:1
	s_waitcnt lgkmcnt(0)
; __device__ __forceinline__ unsigned cvt_pk_bf16(float lo, float hi) { unsigned r; asm volatile("v_cvt_pk_bf16_f32 %0, %1, %2" : "=v"(r) : "v"(lo), "v"(hi)); return r; }
; __device__ __forceinline__ float row_scan16(float v) { v += dpp_shr0<0x111>(v); v += dpp_shr0<0x112>(v); v += dpp_shr0<0x114>(v); v += dpp_shr0<0x118>(v); return v; }
; __device__ __forceinline__ float row_last16(float v, int lane) { return __builtin_bit_cast(float, __builtin_amdgcn_ds_bpermute((lane | 15) << 2, __builtin_bit_cast(int, v))); }
;     __device__ __forceinline__ void operator()(const f32x4 (&acc)[2][2][4][2], const Unit& u, int wr, int wc, int fr, int fq) const {
;     ...
;                     for (int q = 0; q < 4; ++q) { const int j = 4 * n + q;
;                         const float k0 = om[n][q] / (1.0f + __expf(acc[ai][1][2 * mp][n][q])), k1 = om[n][q] / (1.0f + __expf(acc[ai][1][2 * mp + 1][n][q]));
;                         const float p0 = row_scan16(__logf(1.0f - k0)); const float t0 = row_last16(p0, lane);
;                         const float p1 = row_scan16(__logf(1.0f - k1)) + t0; const float bl = row_last16(p1, lane);
;                         const float e0 = __expf(p0), e1 = __expf(p1);
;                         qi[0][j] = acc[ai][0][2 * mp][n][q] * e0; qi[1][j] = acc[ai][0][2 * mp + 1][n][q] * e1;
;                         ki[0][j] = k0 * __expf(-p0); ki[1][j] = k1 * __expf(-p1);
;                         kot[(size_t)j * 32] = (bf16_t)cvt_pk_bf16(k0 * __expf(bl - p0), 0.f); kot[(size_t)j * 32 + 16] = (bf16_t)cvt_pk_bf16(k1 * __expf(bl - p1), 0.f);
;                         dec[j] = __expf(bl); }
	v_add_f32_e32 v183, v177, v136
	v_mul_f32_e32 v136, 0x3fb8aa3b, v178
	v_exp_f32_e32 v177, v136
	ds_bpermute_b32 v136, v162, v183
	v_mul_f32_e32 v179, 0x3fb8aa3b, v183
	v_exp_f32_e32 v180, v179
	v_mul_f32_e32 v179, v40, v177
	v_mul_f32_e32 v177, 0xbfb8aa3b, v178
	s_waitcnt lgkmcnt(0)
	v_sub_f32_e32 v178, v136, v178
	v_mul_f32_e32 v178, 0x3fb8aa3b, v178
	v_exp_f32_e32 v177, v177
	v_exp_f32_e32 v185, v178
	v_mul_f32_e32 v178, v24, v180
	v_mul_f32_e32 v184, 0xbfb8aa3b, v183
	v_mul_f32_e32 v180, v181, v177
	v_mul_f32_e32 v181, v181, v185
	v_cvt_pk_bf16_f32 v181, v181, v147
	global_store_short v[130:131], v181, off offset:128
	v_mul_f32_e32 v181, 0x3fb8aa3b, v21
	v_exp_f32_e32 v181, v181
	v_exp_f32_e32 v184, v184
	v_sub_f32_e32 v183, v136, v183
	v_mul_f32_e32 v183, 0x3fb8aa3b, v183
	v_exp_f32_e32 v183, v183
	v_add_f32_e32 v181, 1.0, v181
	v_mul_f32_e32 v177, v182, v184
	v_div_scale_f32 v184, s[0:1], v181, v181, v137
	v_rcp_f32_e32 v185, v184
	v_mul_f32_e32 v182, v182, v183
	v_cvt_pk_bf16_f32 v182, v182, v147
	global_store_short v[130:131], v182, off offset:160
	v_fma_f32 v182, -v184, v185, 1.0
	v_fmac_f32_e32 v185, v182, v185
	v_div_scale_f32 v182, vcc, v137, v181, v137
	v_mul_f32_e32 v183, v182, v185
	v_fma_f32 v188, -v184, v183, v182
	v_fmac_f32_e32 v183, v188, v185
	v_fma_f32 v182, -v184, v183, v182
	v_add_f32_e32 v184, 1.0, v187
	v_div_scale_f32 v187, s[0:1], v184, v184, v137
	v_rcp_f32_e32 v188, v187
	v_div_fmas_f32 v182, v182, v185, v183
	v_div_fixup_f32 v185, v182, v181, v137
	v_fma_f32 v181, -v187, v188, 1.0
	v_fmac_f32_e32 v188, v181, v188
	v_div_scale_f32 v181, vcc, v137, v184, v137
	v_mul_f32_e32 v182, v181, v188
	v_fma_f32 v183, -v187, v182, v181
	v_fmac_f32_e32 v182, v183, v188
	v_sub_f32_e32 v183, 1.0, v185
	v_fma_f32 v181, -v187, v182, v181
	v_div_fmas_f32 v181, v181, v188, v182
	v_log_f32_e32 v183, v183
	v_div_fixup_f32 v187, v181, v184, v137
	v_mul_f32_e32 v137, 0x3f317217, v183
	v_fma_f32 v137, v183, s72, -v137
	v_fmac_f32_e32 v137, 0x3377d1cf, v183
	v_fmac_f32_e32 v137, 0x3f317217, v183
	v_cmp_lt_f32_e64 vcc, |v183|, s73
	s_nop 1
	v_cndmask_b32_e32 v137, v183, v137, vcc
	v_sub_f32_e32 v181, 1.0, v187
	s_nop 0
	v_add_f32_dpp v137, v137, v137 row_shr:1 row_mask:0xf bank_mask:0xf bound_ctrl:1
	s_nop 0
	v_log_f32_e32 v181, v181
	v_add_f32_dpp v137, v137, v137 row_shr:2 row_mask:0xf bank_mask:0xf bound_ctrl:1
	v_mul_f32_e32 v183, 0x3f317217, v181
	v_fma_f32 v183, v181, s72, -v183
	v_fmac_f32_e32 v183, 0x3377d1cf, v181
	v_add_f32_dpp v137, v137, v137 row_shr:4 row_mask:0xf bank_mask:0xf bound_ctrl:1
	v_fmac_f32_e32 v183, 0x3f317217, v181
	v_cmp_lt_f32_e64 s[0:1], |v181|, s73
	v_add_f32_dpp v182, v137, v137 row_shr:8 row_mask:0xf bank_mask:0xf bound_ctrl:1
	ds_bpermute_b32 v137, v162, v182
	v_cndmask_b32_e64 v181, v181, v183, s[0:1]
	s_nop 1
	v_add_f32_dpp v181, v181, v181 row_shr:1 row_mask:0xf bank_mask:0xf bound_ctrl:1
	s_nop 1
	v_add_f32_dpp v181, v181, v181 row_shr:2 row_mask:0xf bank_mask:0xf bound_ctrl:1
	s_nop 1
	v_add_f32_dpp v181, v181, v181 row_shr:4 row_mask:0xf bank_mask:0xf bound_ctrl:1
	s_nop 1
	v_add_f32_dpp v181, v181, v181 row_shr:8 row_mask:0xf bank_mask:0xf bound_ctrl:1
	s_waitcnt lgkmcnt(0)
	v_add_f32_e32 v188, v181, v137
	v_mul_f32_e32 v137, 0x3fb8aa3b, v182
	v_exp_f32_e32 v181, v137
	ds_bpermute_b32 v137, v162, v188
	v_mul_f32_e32 v183, 0x3fb8aa3b, v188
	v_exp_f32_e32 v184, v183
	v_mul_f32_e32 v183, v41, v181
	v_mul_f32_e32 v181, 0xbfb8aa3b, v182
	s_waitcnt lgkmcnt(0)
	v_sub_f32_e32 v182, v137, v182
	v_mul_f32_e32 v182, 0x3fb8aa3b, v182
	v_exp_f32_e32 v181, v181
	v_exp_f32_e32 v190, v182
	v_mul_f32_e32 v182, v25, v184
	v_mul_f32_e32 v189, 0xbfb8aa3b, v188
	v_mul_f32_e32 v184, v185, v181
	v_mul_f32_e32 v185, v185, v190
	v_cvt_pk_bf16_f32 v185, v185, v147
	global_store_short v[130:131], v185, off offset:192
	v_mul_f32_e32 v185, 0x3fb8aa3b, v10
	v_exp_f32_e32 v185, v185
	v_exp_f32_e32 v189, v189
	v_sub_f32_e32 v188, v137, v188
	v_mul_f32_e32 v188, 0x3fb8aa3b, v188
	v_exp_f32_e32 v188, v188
	v_add_f32_e32 v185, 1.0, v185
	v_mul_f32_e32 v181, v187, v189
	v_div_scale_f32 v189, s[0:1], v185, v185, v135
	v_rcp_f32_e32 v190, v189
	v_mul_f32_e32 v187, v187, v188
	v_cvt_pk_bf16_f32 v187, v187, v147
	global_store_short v[130:131], v187, off offset:224
	v_fma_f32 v187, -v189, v190, 1.0
	v_fmac_f32_e32 v190, v187, v190
	v_div_scale_f32 v187, vcc, v135, v185, v135
	v_mul_f32_e32 v188, v187, v190
	v_fma_f32 v192, -v189, v188, v187
	v_fmac_f32_e32 v188, v192, v190
	v_fma_f32 v187, -v189, v188, v187
	v_add_f32_e32 v189, 1.0, v191
	v_div_scale_f32 v191, s[0:1], v189, v189, v135
	v_rcp_f32_e32 v192, v191
	v_div_fmas_f32 v187, v187, v190, v188
	v_div_fixup_f32 v185, v187, v185, v135
	v_fma_f32 v187, -v191, v192, 1.0
	v_fmac_f32_e32 v192, v187, v192
	v_div_scale_f32 v187, vcc, v135, v189, v135
	v_mul_f32_e32 v188, v187, v192
	v_fma_f32 v190, -v191, v188, v187
	v_fmac_f32_e32 v188, v190, v192
	v_sub_f32_e32 v190, 1.0, v185
	v_fma_f32 v187, -v191, v188, v187
	v_div_fmas_f32 v187, v187, v192, v188
	v_log_f32_e32 v190, v190
	v_div_fixup_f32 v187, v187, v189, v135
	v_mul_f32_e32 v135, 0x3f317217, v190
	v_fma_f32 v135, v190, s72, -v135
	v_fmac_f32_e32 v135, 0x3377d1cf, v190
	v_fmac_f32_e32 v135, 0x3f317217, v190
	v_cmp_lt_f32_e64 vcc, |v190|, s73
	s_nop 1
	v_cndmask_b32_e32 v135, v190, v135, vcc
	v_sub_f32_e32 v188, 1.0, v187
	s_nop 0
	v_add_f32_dpp v135, v135, v135 row_shr:1 row_mask:0xf bank_mask:0xf bound_ctrl:1
	s_nop 0
	v_log_f32_e32 v188, v188
	v_add_f32_dpp v135, v135, v135 row_shr:2 row_mask:0xf bank_mask:0xf bound_ctrl:1
	v_mul_f32_e32 v190, 0x3f317217, v188
	v_fma_f32 v190, v188, s72, -v190
	v_fmac_f32_e32 v190, 0x3377d1cf, v188
	v_add_f32_dpp v135, v135, v135 row_shr:4 row_mask:0xf bank_mask:0xf bound_ctrl:1
	v_fmac_f32_e32 v190, 0x3f317217, v188
	v_cmp_lt_f32_e64 s[0:1], |v188|, s73
	v_add_f32_dpp v189, v135, v135 row_shr:8 row_mask:0xf bank_mask:0xf bound_ctrl:1
	ds_bpermute_b32 v135, v162, v189
	v_cndmask_b32_e64 v188, v188, v190, s[0:1]
	v_mul_f32_e32 v192, 0xbfb8aa3b, v189
	v_exp_f32_e32 v192, v192
	v_add_f32_dpp v188, v188, v188 row_shr:1 row_mask:0xf bank_mask:0xf bound_ctrl:1
	v_mul_f32_e32 v197, v185, v192
	s_nop 0
	v_add_f32_dpp v188, v188, v188 row_shr:2 row_mask:0xf bank_mask:0xf bound_ctrl:1
	v_mul_f32_e32 v192, 0x3fb8aa3b, v3
	v_exp_f32_e32 v192, v192
	v_add_f32_dpp v188, v188, v188 row_shr:4 row_mask:0xf bank_mask:0xf bound_ctrl:1
	s_nop 1
	v_add_f32_dpp v188, v188, v188 row_shr:8 row_mask:0xf bank_mask:0xf bound_ctrl:1
	s_waitcnt lgkmcnt(0)
; __device__ __forceinline__ unsigned cvt_pk_bf16(float lo, float hi) { unsigned r; asm volatile("v_cvt_pk_bf16_f32 %0, %1, %2" : "=v"(r) : "v"(lo), "v"(hi)); return r; }
; __device__ __forceinline__ float row_scan16(float v) { v += dpp_shr0<0x111>(v); v += dpp_shr0<0x112>(v); v += dpp_shr0<0x114>(v); v += dpp_shr0<0x118>(v); return v; }
; __device__ __forceinline__ float row_last16(float v, int lane) { return __builtin_bit_cast(float, __builtin_amdgcn_ds_bpermute((lane | 15) << 2, __builtin_bit_cast(int, v))); }
;     __device__ __forceinline__ void operator()(const f32x4 (&acc)[2][2][4][2], const Unit& u, int wr, int wc, int fr, int fq) const {
;     ...
;                     for (int q = 0; q < 4; ++q) { const int j = 4 * n + q;
;                         const float k0 = om[n][q] / (1.0f + __expf(acc[ai][1][2 * mp][n][q])), k1 = om[n][q] / (1.0f + __expf(acc[ai][1][2 * mp + 1][n][q]));
;                         const float p0 = row_scan16(__logf(1.0f - k0)); const float t0 = row_last16(p0, lane);
;                         const float p1 = row_scan16(__logf(1.0f - k1)) + t0; const float bl = row_last16(p1, lane);
;                         const float e0 = __expf(p0), e1 = __expf(p1);
;                         qi[0][j] = acc[ai][0][2 * mp][n][q] * e0; qi[1][j] = acc[ai][0][2 * mp + 1][n][q] * e1;
;                         ki[0][j] = k0 * __expf(-p0); ki[1][j] = k1 * __expf(-p1);
;                         kot[(size_t)j * 32] = (bf16_t)cvt_pk_bf16(k0 * __expf(bl - p0), 0.f); kot[(size_t)j * 32 + 16] = (bf16_t)cvt_pk_bf16(k1 * __expf(bl - p1), 0.f);
;                         dec[j] = __expf(bl); }
	v_add_f32_e32 v188, v188, v135
	v_mul_f32_e32 v135, 0x3fb8aa3b, v189
	v_exp_f32_e32 v190, v135
	ds_bpermute_b32 v135, v162, v188
	v_mul_f32_e32 v191, 0x3fb8aa3b, v188
	v_exp_f32_e32 v191, v191
	v_mul_f32_e32 v193, 0xbfb8aa3b, v188
	v_exp_f32_e32 v193, v193
	s_waitcnt lgkmcnt(0)
	v_sub_f32_e32 v189, v135, v189
	v_mul_f32_e32 v189, 0x3fb8aa3b, v189
	v_exp_f32_e32 v189, v189
	v_sub_f32_e32 v188, v135, v188
	v_mul_f32_e32 v188, 0x3fb8aa3b, v188
	v_exp_f32_e32 v188, v188
	v_mul_f32_e32 v185, v185, v189
	v_cvt_pk_bf16_f32 v185, v185, v147
	global_store_short v[130:131], v185, off offset:256
	v_mul_f32_e32 v185, 0x3fb8aa3b, v11
	v_exp_f32_e32 v185, v185
	v_mul_f32_e32 v196, v14, v191
	v_mul_f32_e32 v198, v187, v193
	v_mul_f32_e32 v187, v187, v188
	v_add_f32_e32 v185, 1.0, v185
	v_div_scale_f32 v189, s[0:1], v185, v185, v134
	v_rcp_f32_e32 v191, v189
	v_cvt_pk_bf16_f32 v187, v187, v147
	global_store_short v[130:131], v187, off offset:288
	v_mul_f32_e32 v190, v30, v190
	v_fma_f32 v187, -v189, v191, 1.0
	v_fmac_f32_e32 v191, v187, v191
	v_div_scale_f32 v187, vcc, v134, v185, v134
	v_mul_f32_e32 v188, v187, v191
	v_fma_f32 v193, -v189, v188, v187
	v_fmac_f32_e32 v188, v193, v191
	v_fma_f32 v187, -v189, v188, v187
	v_add_f32_e32 v189, 1.0, v192
	v_div_scale_f32 v192, s[0:1], v189, v189, v134
	v_rcp_f32_e32 v193, v192
	v_div_fmas_f32 v187, v187, v191, v188
	v_div_fixup_f32 v185, v187, v185, v134
	v_fma_f32 v187, -v192, v193, 1.0
	v_fmac_f32_e32 v193, v187, v193
	v_div_scale_f32 v187, vcc, v134, v189, v134
	v_mul_f32_e32 v188, v187, v193
	v_fma_f32 v191, -v192, v188, v187
	v_fmac_f32_e32 v188, v191, v193
	v_sub_f32_e32 v191, 1.0, v185
	v_fma_f32 v187, -v192, v188, v187
	v_div_fmas_f32 v187, v187, v193, v188
	v_log_f32_e32 v191, v191
	v_div_fixup_f32 v187, v187, v189, v134
	v_mul_f32_e32 v134, 0x3f317217, v191
	v_fma_f32 v134, v191, s72, -v134
	v_fmac_f32_e32 v134, 0x3377d1cf, v191
	v_fmac_f32_e32 v134, 0x3f317217, v191
	v_cmp_lt_f32_e64 vcc, |v191|, s73
	s_nop 1
	v_cndmask_b32_e32 v134, v191, v134, vcc
	v_sub_f32_e32 v188, 1.0, v187
	s_nop 0
	v_add_f32_dpp v134, v134, v134 row_shr:1 row_mask:0xf bank_mask:0xf bound_ctrl:1
	s_nop 0
	v_log_f32_e32 v188, v188
	v_add_f32_dpp v134, v134, v134 row_shr:2 row_mask:0xf bank_mask:0xf bound_ctrl:1
	v_mul_f32_e32 v191, 0x3f317217, v188
	v_fma_f32 v191, v188, s72, -v191
	v_fmac_f32_e32 v191, 0x3377d1cf, v188
	v_add_f32_dpp v134, v134, v134 row_shr:4 row_mask:0xf bank_mask:0xf bound_ctrl:1
	v_fmac_f32_e32 v191, 0x3f317217, v188
	v_cmp_lt_f32_e64 s[0:1], |v188|, s73
	v_add_f32_dpp v189, v134, v134 row_shr:8 row_mask:0xf bank_mask:0xf bound_ctrl:1
	ds_bpermute_b32 v134, v162, v189
	v_cndmask_b32_e64 v188, v188, v191, s[0:1]
	v_mul_f32_e32 v193, 0xbfb8aa3b, v189
	v_exp_f32_e32 v193, v193
	v_add_f32_dpp v188, v188, v188 row_shr:1 row_mask:0xf bank_mask:0xf bound_ctrl:1
	v_mul_f32_e32 v200, v185, v193
	s_nop 0
	v_add_f32_dpp v188, v188, v188 row_shr:2 row_mask:0xf bank_mask:0xf bound_ctrl:1
	v_mul_f32_e32 v193, 0x3fb8aa3b, v4
	v_exp_f32_e32 v193, v193
	v_add_f32_dpp v188, v188, v188 row_shr:4 row_mask:0xf bank_mask:0xf bound_ctrl:1
	s_nop 1
	v_add_f32_dpp v188, v188, v188 row_shr:8 row_mask:0xf bank_mask:0xf bound_ctrl:1
	s_waitcnt lgkmcnt(0)
	v_add_f32_e32 v188, v188, v134
	v_mul_f32_e32 v134, 0x3fb8aa3b, v189
	v_exp_f32_e32 v191, v134
	ds_bpermute_b32 v134, v162, v188
	v_mul_f32_e32 v192, 0x3fb8aa3b, v188
	v_exp_f32_e32 v192, v192
	v_mul_f32_e32 v194, 0xbfb8aa3b, v188
	v_exp_f32_e32 v194, v194
	s_waitcnt lgkmcnt(0)
	v_sub_f32_e32 v189, v134, v189
	v_mul_f32_e32 v189, 0x3fb8aa3b, v189
	v_exp_f32_e32 v189, v189
	v_sub_f32_e32 v188, v134, v188
	v_mul_f32_e32 v188, 0x3fb8aa3b, v188
	v_exp_f32_e32 v188, v188
	v_mul_f32_e32 v185, v185, v189
	v_cvt_pk_bf16_f32 v185, v185, v147
	global_store_short v[130:131], v185, off offset:320
	v_mul_f32_e32 v185, 0x3fb8aa3b, v12
	v_exp_f32_e32 v185, v185
	v_mul_f32_e32 v199, v15, v192
	v_mul_f32_e32 v201, v187, v194
	v_mul_f32_e32 v187, v187, v188
	v_add_f32_e32 v185, 1.0, v185
	v_div_scale_f32 v189, s[0:1], v185, v185, v132
	v_rcp_f32_e32 v192, v189
	v_cvt_pk_bf16_f32 v187, v187, v147
	global_store_short v[130:131], v187, off offset:352
	v_mul_f32_e32 v191, v31, v191
	v_fma_f32 v187, -v189, v192, 1.0
	v_fmac_f32_e32 v192, v187, v192
	v_div_scale_f32 v187, vcc, v132, v185, v132
	v_mul_f32_e32 v188, v187, v192
	v_fma_f32 v194, -v189, v188, v187
	v_fmac_f32_e32 v188, v194, v192
	v_fma_f32 v187, -v189, v188, v187
	v_add_f32_e32 v189, 1.0, v193
	v_div_scale_f32 v193, s[0:1], v189, v189, v132
	v_rcp_f32_e32 v194, v193
	v_div_fmas_f32 v187, v187, v192, v188
	v_div_fixup_f32 v185, v187, v185, v132
	v_fma_f32 v187, -v193, v194, 1.0
	v_fmac_f32_e32 v194, v187, v194
	v_div_scale_f32 v187, vcc, v132, v189, v132
	v_mul_f32_e32 v188, v187, v194
	v_fma_f32 v192, -v193, v188, v187
	v_fmac_f32_e32 v188, v192, v194
	v_sub_f32_e32 v192, 1.0, v185
	v_fma_f32 v187, -v193, v188, v187
	v_div_fmas_f32 v187, v187, v194, v188
	v_log_f32_e32 v192, v192
	v_div_fixup_f32 v187, v187, v189, v132
	v_mul_f32_e32 v132, 0x3f317217, v192
	v_fma_f32 v132, v192, s72, -v132
	v_fmac_f32_e32 v132, 0x3377d1cf, v192
	v_fmac_f32_e32 v132, 0x3f317217, v192
	v_cmp_lt_f32_e64 vcc, |v192|, s73
	s_nop 1
	v_cndmask_b32_e32 v132, v192, v132, vcc
	v_sub_f32_e32 v188, 1.0, v187
	s_nop 0
	v_add_f32_dpp v132, v132, v132 row_shr:1 row_mask:0xf bank_mask:0xf bound_ctrl:1
	s_nop 0
	v_log_f32_e32 v188, v188
	v_add_f32_dpp v132, v132, v132 row_shr:2 row_mask:0xf bank_mask:0xf bound_ctrl:1
	v_mul_f32_e32 v192, 0x3f317217, v188
	v_fma_f32 v192, v188, s72, -v192
	v_fmac_f32_e32 v192, 0x3377d1cf, v188
	v_add_f32_dpp v132, v132, v132 row_shr:4 row_mask:0xf bank_mask:0xf bound_ctrl:1
	v_fmac_f32_e32 v192, 0x3f317217, v188
	v_cmp_lt_f32_e64 s[0:1], |v188|, s73
	v_add_f32_dpp v189, v132, v132 row_shr:8 row_mask:0xf bank_mask:0xf bound_ctrl:1
	ds_bpermute_b32 v132, v162, v189
	v_cndmask_b32_e64 v188, v188, v192, s[0:1]
	s_nop 1
	v_add_f32_dpp v188, v188, v188 row_shr:1 row_mask:0xf bank_mask:0xf bound_ctrl:1
	s_nop 1
	v_add_f32_dpp v188, v188, v188 row_shr:2 row_mask:0xf bank_mask:0xf bound_ctrl:1
	s_nop 1
	v_add_f32_dpp v188, v188, v188 row_shr:4 row_mask:0xf bank_mask:0xf bound_ctrl:1
	s_nop 1
	v_add_f32_dpp v188, v188, v188 row_shr:8 row_mask:0xf bank_mask:0xf bound_ctrl:1
	s_waitcnt lgkmcnt(0)
; __device__ __forceinline__ unsigned cvt_pk_bf16(float lo, float hi) { unsigned r; asm volatile("v_cvt_pk_bf16_f32 %0, %1, %2" : "=v"(r) : "v"(lo), "v"(hi)); return r; }
; __device__ __forceinline__ float row_scan16(float v) { v += dpp_shr0<0x111>(v); v += dpp_shr0<0x112>(v); v += dpp_shr0<0x114>(v); v += dpp_shr0<0x118>(v); return v; }
;     __device__ __forceinline__ void operator()(const f32x4 (&acc)[2][2][4][2], const Unit& u, int wr, int wc, int fr, int fq) const {
;     ...
;                     for (int q = 0; q < 4; ++q) { const int j = 4 * n + q;
;                         const float k0 = om[n][q] / (1.0f + __expf(acc[ai][1][2 * mp][n][q])), k1 = om[n][q] / (1.0f + __expf(acc[ai][1][2 * mp + 1][n][q]));
;                         const float p0 = row_scan16(__logf(1.0f - k0)); const float t0 = row_last16(p0, lane);
;                         const float p1 = row_scan16(__logf(1.0f - k1)) + t0; const float bl = row_last16(p1, lane);
;                         const float e0 = __expf(p0), e1 = __expf(p1);
;                         qi[0][j] = acc[ai][0][2 * mp][n][q] * e0; qi[1][j] = acc[ai][0][2 * mp + 1][n][q] * e1;
;                         ki[0][j] = k0 * __expf(-p0); ki[1][j] = k1 * __expf(-p1);
;                         kot[(size_t)j * 32] = (bf16_t)cvt_pk_bf16(k0 * __expf(bl - p0), 0.f); kot[(size_t)j * 32 + 16] = (bf16_t)cvt_pk_bf16(k1 * __expf(bl - p1), 0.f);
;                         dec[j] = __expf(bl); }
; #pragma unroll
;                 for (int mm = 0; mm < 2; ++mm) { const size_t ro = (size_t)(rowa + 16 * mm) * 1024 + colh;
;                     u32x4 w; w.x = cvt_pk_bf16(qi[mm][0], qi[mm][1]); w.y = cvt_pk_bf16(qi[mm][2], qi[mm][3]); w.z = cvt_pk_bf16(qi[mm][4], qi[mm][5]); w.w = cvt_pk_bf16(qi[mm][6], qi[mm][7]);
;                     *(u32x4*)(CQ + ro) = w;
;                     w.x = cvt_pk_bf16(ki[mm][0], ki[mm][1]); w.y = cvt_pk_bf16(ki[mm][2], ki[mm][3]); w.z = cvt_pk_bf16(ki[mm][4], ki[mm][5]); w.w = cvt_pk_bf16(ki[mm][6], ki[mm][7]);
;                     *(u32x4*)(CK + ro) = w; }
;                 if (fr == 15) { float* dp = DEC + (size_t)g * 1024 + colh; *(f32x4*)dp = (f32x4){dec[0], dec[1], dec[2], dec[3]}; *(f32x4*)(dp + 4) = (f32x4){dec[4], dec[5], dec[6], dec[7]}; }
	v_add_f32_e32 v188, v188, v132
	v_mul_f32_e32 v132, 0x3fb8aa3b, v189
	v_exp_f32_e32 v192, v132
	ds_bpermute_b32 v132, v162, v188
	v_mul_f32_e32 v193, 0x3fb8aa3b, v188
	v_mul_f32_e32 v195, 0xbfb8aa3b, v188
	v_mul_f32_e32 v194, v32, v192
	v_mul_f32_e32 v192, 0xbfb8aa3b, v189
	s_waitcnt lgkmcnt(0)
	v_sub_f32_e32 v189, v132, v189
	v_mul_f32_e32 v189, 0x3fb8aa3b, v189
	v_exp_f32_e32 v192, v192
	v_exp_f32_e32 v189, v189
	v_sub_f32_e32 v188, v132, v188
	v_mul_f32_e32 v188, 0x3fb8aa3b, v188
	v_mul_f32_e32 v203, v185, v192
	v_mul_f32_e32 v185, v185, v189
	v_cvt_pk_bf16_f32 v185, v185, v147
	global_store_short v[130:131], v185, off offset:384
	v_mul_f32_e32 v185, 0x3fb8aa3b, v13
	v_exp_f32_e32 v185, v185
	v_exp_f32_e32 v195, v195
	v_exp_f32_e32 v188, v188
	v_exp_f32_e32 v193, v193
	v_add_f32_e32 v185, 1.0, v185
	v_div_scale_f32 v189, s[0:1], v185, v185, v133
	v_rcp_f32_e32 v192, v189
	v_mul_f32_e32 v204, v187, v195
	v_mul_f32_e32 v187, v187, v188
	v_cvt_pk_bf16_f32 v187, v187, v147
	v_mul_f32_e32 v202, v16, v193
	global_store_short v[130:131], v187, off offset:416
	v_fma_f32 v187, -v189, v192, 1.0
	v_mul_f32_e32 v193, 0x3fb8aa3b, v5
	v_fmac_f32_e32 v192, v187, v192
	v_div_scale_f32 v187, vcc, v133, v185, v133
	v_exp_f32_e32 v193, v193
	v_mul_f32_e32 v188, v187, v192
	v_fma_f32 v195, -v189, v188, v187
	v_fmac_f32_e32 v188, v195, v192
	v_fma_f32 v187, -v189, v188, v187
	v_add_f32_e32 v189, 1.0, v193
	v_div_scale_f32 v193, s[0:1], v189, v189, v133
	v_rcp_f32_e32 v195, v193
	v_div_fmas_f32 v187, v187, v192, v188
	v_div_fixup_f32 v185, v187, v185, v133
	v_fma_f32 v187, -v193, v195, 1.0
	v_fmac_f32_e32 v195, v187, v195
	v_div_scale_f32 v187, vcc, v133, v189, v133
	v_mul_f32_e32 v188, v187, v195
	v_fma_f32 v192, -v193, v188, v187
	v_fmac_f32_e32 v188, v192, v195
	v_sub_f32_e32 v192, 1.0, v185
	v_fma_f32 v187, -v193, v188, v187
	v_div_fmas_f32 v187, v187, v195, v188
	v_log_f32_e32 v192, v192
	v_div_fixup_f32 v187, v187, v189, v133
	v_mul_f32_e32 v133, 0x3f317217, v192
	v_fma_f32 v133, v192, s72, -v133
	v_fmac_f32_e32 v133, 0x3377d1cf, v192
	v_fmac_f32_e32 v133, 0x3f317217, v192
	v_cmp_lt_f32_e64 vcc, |v192|, s73
	s_nop 1
	v_cndmask_b32_e32 v133, v192, v133, vcc
	v_sub_f32_e32 v188, 1.0, v187
	s_nop 0
	v_add_f32_dpp v133, v133, v133 row_shr:1 row_mask:0xf bank_mask:0xf bound_ctrl:1
	s_nop 0
	v_log_f32_e32 v188, v188
	v_add_f32_dpp v133, v133, v133 row_shr:2 row_mask:0xf bank_mask:0xf bound_ctrl:1
	v_mul_f32_e32 v192, 0x3f317217, v188
	v_fma_f32 v192, v188, s72, -v192
	v_fmac_f32_e32 v192, 0x3377d1cf, v188
	v_add_f32_dpp v133, v133, v133 row_shr:4 row_mask:0xf bank_mask:0xf bound_ctrl:1
	v_fmac_f32_e32 v192, 0x3f317217, v188
	v_cmp_lt_f32_e64 s[0:1], |v188|, s73
	v_add_f32_dpp v189, v133, v133 row_shr:8 row_mask:0xf bank_mask:0xf bound_ctrl:1
	ds_bpermute_b32 v133, v162, v189
	v_cndmask_b32_e64 v188, v188, v192, s[0:1]
	v_mul_f32_e32 v192, 0x3fb8aa3b, v189
	v_mul_f32_e32 v195, 0xbfb8aa3b, v189
	v_add_f32_dpp v188, v188, v188 row_shr:1 row_mask:0xf bank_mask:0xf bound_ctrl:1
	v_exp_f32_e32 v195, v195
	v_exp_f32_e32 v192, v192
	v_add_f32_dpp v188, v188, v188 row_shr:2 row_mask:0xf bank_mask:0xf bound_ctrl:1
	v_mul_f32_e32 v208, v185, v195
	s_nop 0
	v_add_f32_dpp v188, v188, v188 row_shr:4 row_mask:0xf bank_mask:0xf bound_ctrl:1
	v_mul_f32_e32 v206, v33, v192
	s_nop 0
	v_add_f32_dpp v188, v188, v188 row_shr:8 row_mask:0xf bank_mask:0xf bound_ctrl:1
	s_waitcnt lgkmcnt(0)
	v_add_f32_e32 v188, v188, v133
	ds_bpermute_b32 v133, v162, v188
	v_mul_f32_e32 v193, 0x3fb8aa3b, v188
	v_mul_f32_e32 v205, 0xbfb8aa3b, v188
	v_exp_f32_e32 v193, v193
	v_exp_f32_e32 v205, v205
	s_waitcnt lgkmcnt(0)
	v_sub_f32_e32 v189, v133, v189
	v_mul_f32_e32 v189, 0x3fb8aa3b, v189
	v_exp_f32_e32 v189, v189
	v_sub_f32_e32 v188, v133, v188
	v_mul_f32_e32 v188, 0x3fb8aa3b, v188
	v_exp_f32_e32 v188, v188
	v_mul_f32_e32 v185, v185, v189
	v_cvt_pk_bf16_f32 v185, v185, v147
	global_store_short v[130:131], v185, off offset:448
	v_mul_f32_e32 v185, v187, v188
	v_cvt_pk_bf16_f32 v185, v185, v147
	global_store_short v[130:131], v185, off offset:480
	v_or_b32_e32 v130, s2, v1
	v_ashrrev_i32_e32 v131, 31, v130
	v_lshlrev_b64 v[188:189], 10, v[130:131]
	v_or_b32_e32 v130, 16, v130
	v_mul_f32_e32 v207, v17, v193
	v_lshl_add_u64 v[192:193], v[188:189], 0, v[158:159]
	v_ashrrev_i32_e32 v131, 31, v130
	v_lshlrev_b64 v[192:193], 1, v[192:193]
	v_lshlrev_b64 v[130:131], 10, v[130:131]
	v_cvt_pk_bf16_f32 v188, v171, v175
	v_cvt_pk_bf16_f32 v189, v179, v183
	v_cvt_pk_bf16_f32 v190, v190, v191
	v_cvt_pk_bf16_f32 v191, v194, v206
	v_lshl_add_u64 v[194:195], s[64:65], 0, v[192:193]
	v_lshl_add_u64 v[130:131], v[130:131], 0, v[158:159]
	global_store_dwordx4 v[194:195], v[188:191], off
	v_lshlrev_b64 v[130:131], 1, v[130:131]
	v_mul_f32_e32 v205, v187, v205
	v_cvt_pk_bf16_f32 v188, v172, v176
	v_cvt_pk_bf16_f32 v189, v180, v184
	v_lshl_add_u64 v[184:185], s[14:15], 0, v[192:193]
	v_cvt_pk_bf16_f32 v190, v197, v200
	v_cvt_pk_bf16_f32 v191, v203, v208
	global_store_dwordx4 v[184:185], v[188:191], off
	s_nop 1
	v_cvt_pk_bf16_f32 v188, v170, v174
	v_lshl_add_u64 v[170:171], s[64:65], 0, v[130:131]
	v_lshl_add_u64 v[130:131], s[14:15], 0, v[130:131]
	v_cvt_pk_bf16_f32 v189, v178, v182
	v_cvt_pk_bf16_f32 v190, v196, v199
	v_cvt_pk_bf16_f32 v191, v202, v207
	global_store_dwordx4 v[170:171], v[188:191], off
	s_nop 1
	v_cvt_pk_bf16_f32 v170, v161, v173
	v_cvt_pk_bf16_f32 v171, v177, v181
	v_cvt_pk_bf16_f32 v172, v198, v201
	v_cvt_pk_bf16_f32 v173, v204, v205
	global_store_dwordx4 v[130:131], v[170:173], off
	s_and_saveexec_b64 s[0:1], s[4:5]
	s_cbranch_execz .LBB0_1153
	v_mul_f32_e32 v130, 0x3fb8aa3b, v133
	v_exp_f32_e32 v133, v130
	v_mul_f32_e32 v130, 0x3fb8aa3b, v132
	v_exp_f32_e32 v132, v130
	v_mul_f32_e32 v130, 0x3fb8aa3b, v134
	v_mul_f32_e32 v134, 0x3fb8aa3b, v137
	v_exp_f32_e32 v137, v134
	v_mul_f32_e32 v134, 0x3fb8aa3b, v136
	v_exp_f32_e32 v136, v134
	v_mul_f32_e32 v134, 0x3fb8aa3b, v146
	v_exp_f32_e32 v131, v130
	v_mul_f32_e32 v130, 0x3fb8aa3b, v135
	v_exp_f32_e32 v135, v134
	v_mul_f32_e32 v134, 0x3fb8aa3b, v160
	v_exp_f32_e32 v134, v134
	s_lshl_b64 s[2:3], s[8:9], 2
	v_exp_f32_e32 v130, v130
	s_add_u32 s2, s47, s2
	s_addc_u32 s3, s52, s3
	v_lshl_add_u64 v[158:159], v[158:159], 2, s[2:3]
	global_store_dwordx4 v[158:159], v[134:137], off
	global_store_dwordx4 v[158:159], v[130:133], off offset:16
